# xor-16/32 butterflies via v_permlane swaps, xor-1..8 via DPP adds in row-norm reductions (on top of rsq)
# speedup vs baseline: 1.0068x; 1.0022x over previous
; __device__ __forceinline__ void load_row_scales(const float* ssp, int row0, int fq, float (&rs)[2][4]) {
;     f32x4 part[2][4];
;     const float* sp = ssp + (size_t)row0 * 16 + 4 * fq;
; #pragma unroll
;     for (int ai = 0; ai < 2; ++ai)
; #pragma unroll
;         for (int m = 0; m < 4; ++m) part[ai][m] = *(const f32x4*)(sp + (size_t)(ai * HALF + m * 16) * 16);
; #pragma unroll
;     for (int ai = 0; ai < 2; ++ai)
; #pragma unroll
;         for (int m = 0; m < 4; ++m) { float t = (part[ai][m][0] + part[ai][m][1]) + (part[ai][m][2] + part[ai][m][3]);
;             t += __shfl_xor(t, 16); t += __shfl_xor(t, 32);
;             rs[ai][m] = 1.0f / sqrtf(t * (1.0f / 1024.0f) + 1e-6f); }
; }
;     __device__ __forceinline__ void operator()(f32x4 (&acc)[2][2][4][2], const Unit& u, int wr, int wc, int fr, int fq) const {
;     ...
;             if (ssp) load_row_scales(ssp, row0, fq, rsa);
.LBB0_271:
	s_and_b64 vcc, exec, s[6:7]
	s_cbranch_vccnz .LBB0_273
	v_lshlrev_b64 v[130:131], 6, v[172:173]
	v_lshl_add_u64 v[130:131], v[166:167], 0, v[130:131]
	global_load_dwordx4 v[182:185], v[130:131], off
	global_load_dwordx4 v[154:157], v[130:131], off offset:1024
	global_load_dwordx4 v[150:153], v[130:131], off offset:2048
	global_load_dwordx4 v[146:149], v[130:131], off offset:3072
	v_add_co_u32_e32 v130, vcc, 0x2000, v130
	v_and_b32_e32 v175, 64, v229
	s_nop 0
	v_addc_co_u32_e32 v131, vcc, 0, v131, vcc
	v_xor_b32_e32 v0, 16, v229
	v_add_u32_e32 v180, 64, v175
	v_cmp_lt_i32_e32 vcc, v0, v180
	global_load_dwordx4 v[142:145], v[130:131], off
	global_load_dwordx4 v[138:141], v[130:131], off offset:1024
	global_load_dwordx4 v[134:137], v[130:131], off offset:2048
	s_nop 0
	global_load_dwordx4 v[130:133], v[130:131], off offset:3072
	v_cndmask_b32_e32 v0, v229, v0, vcc
	v_lshlrev_b32_e32 v175, 2, v0
	v_xor_b32_e32 v0, 32, v229
	v_cmp_lt_i32_e32 vcc, v0, v180
	s_waitcnt vmcnt(0)
	v_mov_b32_e32 v188, v183
	v_mov_b32_e32 v189, v184
	v_mov_b32_e32 v183, v185
	v_cndmask_b32_e32 v0, v229, v0, vcc
	v_pk_add_f32 v[182:183], v[188:189], v[182:183]
	v_lshlrev_b32_e32 v180, 2, v0
	v_add_f32_e32 v0, v182, v183
	v_mov_b32_e32 v181, v0
	s_nop 1
	v_permlane16_swap_b32_e32 v181, v0
	s_waitcnt lgkmcnt(0)
	v_add_f32_e32 v0, v0, v181
	v_mov_b32_e32 v181, v0
	s_nop 1
	v_permlane32_swap_b32_e32 v181, v0
	s_waitcnt lgkmcnt(0)
	v_add_f32_e32 v0, v0, v181
	v_fmamk_f32 v0, v0, 0x3a800000, v230
	v_mov_b32_e32 v182, v155
	v_mov_b32_e32 v183, v156
	v_mov_b32_e32 v155, v157
	v_pk_add_f32 v[154:155], v[182:183], v[154:155]
	v_rsq_f32_e32 v0, v0
	s_nop 0
	v_add_f32_e32 v154, v154, v155
	v_mov_b32_e32 v155, v154
	s_nop 1
	v_permlane16_swap_b32_e32 v155, v154
	s_waitcnt lgkmcnt(0)
	v_add_f32_e32 v154, v154, v155
	v_mov_b32_e32 v155, v154
	s_nop 1
	v_permlane32_swap_b32_e32 v155, v154
	s_waitcnt lgkmcnt(0)
	v_add_f32_e32 v154, v154, v155
	v_fmamk_f32 v154, v154, 0x3a800000, v230
	v_mov_b32_e32 v156, v151
	v_mov_b32_e32 v157, v152
	v_mov_b32_e32 v151, v153
	v_pk_add_f32 v[150:151], v[156:157], v[150:151]
	v_rsq_f32_e32 v154, v154
	s_nop 0
	v_add_f32_e32 v150, v150, v151
	v_mov_b32_e32 v151, v150
	s_nop 1
	v_permlane16_swap_b32_e32 v151, v150
	s_waitcnt lgkmcnt(0)
	v_add_f32_e32 v150, v150, v151
	v_mov_b32_e32 v151, v150
	s_nop 1
	v_permlane32_swap_b32_e32 v151, v150
	s_waitcnt lgkmcnt(0)
	v_add_f32_e32 v150, v150, v151
	v_fmamk_f32 v150, v150, 0x3a800000, v230
	v_mov_b32_e32 v152, v147
	v_mov_b32_e32 v153, v148
	v_mov_b32_e32 v147, v149
	v_pk_add_f32 v[146:147], v[152:153], v[146:147]
	v_rsq_f32_e32 v150, v150
	s_nop 0
	v_add_f32_e32 v146, v146, v147
	v_mov_b32_e32 v147, v146
	s_nop 1
	v_permlane16_swap_b32_e32 v147, v146
	s_waitcnt lgkmcnt(0)
	v_add_f32_e32 v146, v146, v147
	v_mov_b32_e32 v147, v146
	s_nop 1
	v_permlane32_swap_b32_e32 v147, v146
	s_waitcnt lgkmcnt(0)
	v_add_f32_e32 v146, v146, v147
	v_fmamk_f32 v146, v146, 0x3a800000, v230
	v_mov_b32_e32 v148, v143
	v_mov_b32_e32 v149, v144
	v_mov_b32_e32 v143, v145
	v_pk_add_f32 v[142:143], v[148:149], v[142:143]
	v_rsq_f32_e32 v146, v146
	s_nop 0
	v_add_f32_e32 v142, v142, v143
	v_mov_b32_e32 v143, v142
	s_nop 1
	v_permlane16_swap_b32_e32 v143, v142
	s_waitcnt lgkmcnt(0)
	v_add_f32_e32 v142, v142, v143
	v_mov_b32_e32 v143, v142
	s_nop 1
	v_permlane32_swap_b32_e32 v143, v142
	s_waitcnt lgkmcnt(0)
	v_add_f32_e32 v142, v142, v143
	v_fmamk_f32 v142, v142, 0x3a800000, v230
	v_mov_b32_e32 v144, v139
	v_mov_b32_e32 v145, v140
	v_mov_b32_e32 v139, v141
	v_pk_add_f32 v[138:139], v[144:145], v[138:139]
	v_rsq_f32_e32 v142, v142
	s_nop 0
	v_add_f32_e32 v138, v138, v139
	v_mov_b32_e32 v139, v138
	s_nop 1
	v_permlane16_swap_b32_e32 v139, v138
	s_waitcnt lgkmcnt(0)
	v_add_f32_e32 v138, v138, v139
	v_mov_b32_e32 v139, v138
	s_nop 1
	v_permlane32_swap_b32_e32 v139, v138
	s_waitcnt lgkmcnt(0)
	v_add_f32_e32 v138, v138, v139
	v_fmamk_f32 v138, v138, 0x3a800000, v230
	v_mov_b32_e32 v140, v135
	v_mov_b32_e32 v141, v136
	v_mov_b32_e32 v135, v137
	v_pk_add_f32 v[134:135], v[140:141], v[134:135]
	v_rsq_f32_e32 v138, v138
	s_nop 0
	v_add_f32_e32 v134, v134, v135
	v_mov_b32_e32 v135, v134
	s_nop 1
	v_permlane16_swap_b32_e32 v135, v134
	s_waitcnt lgkmcnt(0)
	v_add_f32_e32 v134, v134, v135
	v_mov_b32_e32 v135, v134
	s_nop 1
	v_permlane32_swap_b32_e32 v135, v134
	s_waitcnt lgkmcnt(0)
	v_add_f32_e32 v134, v134, v135
	v_fmamk_f32 v134, v134, 0x3a800000, v230
	v_mov_b32_e32 v136, v131
	v_mov_b32_e32 v137, v132
	v_mov_b32_e32 v131, v133
	v_pk_add_f32 v[130:131], v[136:137], v[130:131]
	v_rsq_f32_e32 v134, v134
	s_nop 0
	v_add_f32_e32 v130, v130, v131
	v_mov_b32_e32 v131, v130
	s_nop 1
	v_permlane16_swap_b32_e32 v131, v130
	s_waitcnt lgkmcnt(0)
	v_add_f32_e32 v130, v130, v131
	v_mov_b32_e32 v131, v130
	s_nop 1
	v_permlane32_swap_b32_e32 v131, v130
	s_waitcnt lgkmcnt(0)
	v_add_f32_e32 v130, v130, v131
	v_fmamk_f32 v130, v130, 0x3a800000, v230
	v_rsq_f32_e32 v130, v130
	s_nop 0
	s_branch .LBB0_274

; __device__ __forceinline__ void load_row_scales(const float* ssp, int row0, int fq, float (&rs)[2][4]) {
;     f32x4 part[2][4];
;     const float* sp = ssp + (size_t)row0 * 16 + 4 * fq;
; #pragma unroll
;     for (int ai = 0; ai < 2; ++ai)
; #pragma unroll
;         for (int m = 0; m < 4; ++m) part[ai][m] = *(const f32x4*)(sp + (size_t)(ai * HALF + m * 16) * 16);
; #pragma unroll
;     for (int ai = 0; ai < 2; ++ai)
; #pragma unroll
;         for (int m = 0; m < 4; ++m) { float t = (part[ai][m][0] + part[ai][m][1]) + (part[ai][m][2] + part[ai][m][3]);
;             t += __shfl_xor(t, 16); t += __shfl_xor(t, 32);
;             rs[ai][m] = 1.0f / sqrtf(t * (1.0f / 1024.0f) + 1e-6f); }
; }
;     __device__ __forceinline__ void operator()(f32x4 (&acc)[2][2][4][2], const Unit& u, int wr, int wc, int fr, int fq) const {
;     ...
;         if (u.pn >= t_lo && u.pn < t_hi) {
;             if (ssp) { float rs[2][4]; load_row_scales(ssp, row0, fq, rs);
; #pragma unroll
;                 for (int ai = 0; ai < 2; ++ai)
; #pragma unroll
;                     for (int m = 0; m < 4; ++m)
; #pragma unroll
;                         for (int bj = 0; bj < 2; ++bj)
; #pragma unroll
;                             for (int n = 0; n < 2; ++n) acc[ai][bj][m][n] = acc[ai][bj][m][n] * rs[ai][m];
.LBB0_275:
	s_and_b64 vcc, exec, s[6:7]
	s_cbranch_vccnz .LBB0_277
	v_lshlrev_b64 v[130:131], 6, v[172:173]
	v_lshl_add_u64 v[130:131], v[166:167], 0, v[130:131]
	global_load_dwordx4 v[182:185], v[130:131], off
	global_load_dwordx4 v[154:157], v[130:131], off offset:1024
	global_load_dwordx4 v[150:153], v[130:131], off offset:2048
	global_load_dwordx4 v[146:149], v[130:131], off offset:3072
	v_add_co_u32_e32 v130, vcc, 0x2000, v130
	v_and_b32_e32 v175, 64, v229
	s_nop 0
	v_addc_co_u32_e32 v131, vcc, 0, v131, vcc
	v_xor_b32_e32 v0, 16, v229
	v_add_u32_e32 v180, 64, v175
	v_cmp_lt_i32_e32 vcc, v0, v180
	global_load_dwordx4 v[142:145], v[130:131], off
	global_load_dwordx4 v[138:141], v[130:131], off offset:1024
	global_load_dwordx4 v[134:137], v[130:131], off offset:2048
	s_nop 0
	global_load_dwordx4 v[130:133], v[130:131], off offset:3072
	v_cndmask_b32_e32 v0, v229, v0, vcc
	v_lshlrev_b32_e32 v175, 2, v0
	v_xor_b32_e32 v0, 32, v229
	v_cmp_lt_i32_e32 vcc, v0, v180
	s_waitcnt vmcnt(0)
	v_mov_b32_e32 v188, v183
	v_mov_b32_e32 v189, v184
	v_mov_b32_e32 v183, v185
	v_cndmask_b32_e32 v0, v229, v0, vcc
	v_pk_add_f32 v[182:183], v[188:189], v[182:183]
	v_lshlrev_b32_e32 v180, 2, v0
	v_add_f32_e32 v0, v182, v183
	v_mov_b32_e32 v181, v0
	s_nop 1
	v_permlane16_swap_b32_e32 v181, v0
	s_waitcnt lgkmcnt(0)
	v_add_f32_e32 v0, v0, v181
	v_mov_b32_e32 v181, v0
	s_nop 1
	v_permlane32_swap_b32_e32 v181, v0
	s_waitcnt lgkmcnt(0)
	v_add_f32_e32 v0, v0, v181
	v_fmamk_f32 v0, v0, 0x3a800000, v230
	v_mov_b32_e32 v182, v155
	v_mov_b32_e32 v183, v156
	v_mov_b32_e32 v155, v157
	v_pk_add_f32 v[154:155], v[182:183], v[154:155]
	v_rsq_f32_e32 v0, v0
	s_nop 0
	v_add_f32_e32 v154, v154, v155
	v_mov_b32_e32 v155, v154
	s_nop 1
	v_permlane16_swap_b32_e32 v155, v154
	v_pk_mul_f32 v[128:129], v[128:129], v[0:1] op_sel_hi:[1,0]
	v_pk_mul_f32 v[126:127], v[126:127], v[0:1] op_sel_hi:[1,0]
	v_pk_mul_f32 v[96:97], v[96:97], v[0:1] op_sel_hi:[1,0]
	v_pk_mul_f32 v[94:95], v[94:95], v[0:1] op_sel_hi:[1,0]
	s_waitcnt lgkmcnt(0)
	v_add_f32_e32 v154, v154, v155
	v_mov_b32_e32 v155, v154
	s_nop 1
	v_permlane32_swap_b32_e32 v155, v154
	v_pk_mul_f32 v[64:65], v[64:65], v[0:1] op_sel_hi:[1,0]
	v_pk_mul_f32 v[62:63], v[62:63], v[0:1] op_sel_hi:[1,0]
	v_pk_mul_f32 v[32:33], v[32:33], v[0:1] op_sel_hi:[1,0]
	v_pk_mul_f32 v[30:31], v[30:31], v[0:1] op_sel_hi:[1,0]
	s_waitcnt lgkmcnt(0)
	v_add_f32_e32 v154, v154, v155
	v_fmamk_f32 v154, v154, 0x3a800000, v230
	v_mov_b32_e32 v156, v151
	v_mov_b32_e32 v157, v152
	v_mov_b32_e32 v151, v153
	v_pk_add_f32 v[150:151], v[156:157], v[150:151]
	v_rsq_f32_e32 v154, v154
	s_nop 0
	v_add_f32_e32 v150, v150, v151
	v_mov_b32_e32 v151, v150
	s_nop 1
	v_permlane16_swap_b32_e32 v151, v150
	s_waitcnt lgkmcnt(0)
	v_add_f32_e32 v150, v150, v151
	v_mov_b32_e32 v151, v150
	s_nop 1
	v_permlane32_swap_b32_e32 v151, v150
	s_waitcnt lgkmcnt(0)
	v_add_f32_e32 v150, v150, v151
	v_fmamk_f32 v150, v150, 0x3a800000, v230
	v_mov_b32_e32 v152, v147
	v_mov_b32_e32 v153, v148
	v_mov_b32_e32 v147, v149
	v_pk_add_f32 v[146:147], v[152:153], v[146:147]
	v_rsq_f32_e32 v150, v150
	s_nop 0
	v_add_f32_e32 v146, v146, v147
	v_mov_b32_e32 v147, v146
	s_nop 1
	v_permlane16_swap_b32_e32 v147, v146
	v_pk_mul_f32 v[124:125], v[124:125], v[154:155] op_sel_hi:[1,0]
	v_pk_mul_f32 v[122:123], v[122:123], v[154:155] op_sel_hi:[1,0]
	v_pk_mul_f32 v[92:93], v[92:93], v[154:155] op_sel_hi:[1,0]
	v_pk_mul_f32 v[90:91], v[90:91], v[154:155] op_sel_hi:[1,0]
	s_waitcnt lgkmcnt(0)
	v_add_f32_e32 v146, v146, v147
	v_mov_b32_e32 v147, v146
	s_nop 1
	v_permlane32_swap_b32_e32 v147, v146
	v_pk_mul_f32 v[60:61], v[60:61], v[154:155] op_sel_hi:[1,0]
	v_pk_mul_f32 v[58:59], v[58:59], v[154:155] op_sel_hi:[1,0]
	v_pk_mul_f32 v[28:29], v[28:29], v[154:155] op_sel_hi:[1,0]
	v_pk_mul_f32 v[26:27], v[26:27], v[154:155] op_sel_hi:[1,0]
	s_waitcnt lgkmcnt(0)
	v_add_f32_e32 v146, v146, v147
	v_fmamk_f32 v146, v146, 0x3a800000, v230
	v_mov_b32_e32 v148, v143
	v_mov_b32_e32 v149, v144
	v_mov_b32_e32 v143, v145
	v_pk_add_f32 v[142:143], v[148:149], v[142:143]
	v_rsq_f32_e32 v146, v146
	s_nop 0
	v_add_f32_e32 v142, v142, v143
	v_mov_b32_e32 v143, v142
	s_nop 1
	v_permlane16_swap_b32_e32 v143, v142
	v_pk_mul_f32 v[120:121], v[120:121], v[150:151] op_sel_hi:[1,0]
	v_pk_mul_f32 v[118:119], v[118:119], v[150:151] op_sel_hi:[1,0]
	v_pk_mul_f32 v[88:89], v[88:89], v[150:151] op_sel_hi:[1,0]
	v_pk_mul_f32 v[86:87], v[86:87], v[150:151] op_sel_hi:[1,0]
	s_waitcnt lgkmcnt(0)
; __device__ __forceinline__ void load_row_scales(const float* ssp, int row0, int fq, float (&rs)[2][4]) {
;     f32x4 part[2][4];
;     const float* sp = ssp + (size_t)row0 * 16 + 4 * fq;
; #pragma unroll
;     for (int ai = 0; ai < 2; ++ai)
; #pragma unroll
;         for (int m = 0; m < 4; ++m) part[ai][m] = *(const f32x4*)(sp + (size_t)(ai * HALF + m * 16) * 16);
; #pragma unroll
;     for (int ai = 0; ai < 2; ++ai)
; #pragma unroll
;         for (int m = 0; m < 4; ++m) { float t = (part[ai][m][0] + part[ai][m][1]) + (part[ai][m][2] + part[ai][m][3]);
;             t += __shfl_xor(t, 16); t += __shfl_xor(t, 32);
;             rs[ai][m] = 1.0f / sqrtf(t * (1.0f / 1024.0f) + 1e-6f); }
; }
;     __device__ __forceinline__ void operator()(f32x4 (&acc)[2][2][4][2], const Unit& u, int wr, int wc, int fr, int fq) const {
;     ...
;         if (u.pn >= t_lo && u.pn < t_hi) {
;             if (ssp) { float rs[2][4]; load_row_scales(ssp, row0, fq, rs);
; #pragma unroll
;                 for (int ai = 0; ai < 2; ++ai)
; #pragma unroll
;                     for (int m = 0; m < 4; ++m)
; #pragma unroll
;                         for (int bj = 0; bj < 2; ++bj)
; #pragma unroll
;                             for (int n = 0; n < 2; ++n) acc[ai][bj][m][n] = acc[ai][bj][m][n] * rs[ai][m];
	v_add_f32_e32 v142, v142, v143
	v_mov_b32_e32 v143, v142
	s_nop 1
	v_permlane32_swap_b32_e32 v143, v142
	v_pk_mul_f32 v[56:57], v[56:57], v[150:151] op_sel_hi:[1,0]
	v_pk_mul_f32 v[54:55], v[54:55], v[150:151] op_sel_hi:[1,0]
	v_pk_mul_f32 v[24:25], v[24:25], v[150:151] op_sel_hi:[1,0]
	v_pk_mul_f32 v[22:23], v[22:23], v[150:151] op_sel_hi:[1,0]
	s_waitcnt lgkmcnt(0)
	v_add_f32_e32 v142, v142, v143
	v_fmamk_f32 v142, v142, 0x3a800000, v230
	v_mov_b32_e32 v144, v139
	v_mov_b32_e32 v145, v140
	v_mov_b32_e32 v139, v141
	v_pk_add_f32 v[138:139], v[144:145], v[138:139]
	v_rsq_f32_e32 v142, v142
	s_nop 0
	v_add_f32_e32 v138, v138, v139
	v_mov_b32_e32 v139, v138
	s_nop 1
	v_permlane16_swap_b32_e32 v139, v138
	v_pk_mul_f32 v[116:117], v[116:117], v[146:147] op_sel_hi:[1,0]
	v_pk_mul_f32 v[114:115], v[114:115], v[146:147] op_sel_hi:[1,0]
	v_pk_mul_f32 v[84:85], v[84:85], v[146:147] op_sel_hi:[1,0]
	v_pk_mul_f32 v[82:83], v[82:83], v[146:147] op_sel_hi:[1,0]
	s_waitcnt lgkmcnt(0)
	v_add_f32_e32 v138, v138, v139
	v_mov_b32_e32 v139, v138
	s_nop 1
	v_permlane32_swap_b32_e32 v139, v138
	v_pk_mul_f32 v[52:53], v[52:53], v[146:147] op_sel_hi:[1,0]
	v_pk_mul_f32 v[50:51], v[50:51], v[146:147] op_sel_hi:[1,0]
	v_pk_mul_f32 v[20:21], v[20:21], v[146:147] op_sel_hi:[1,0]
	v_pk_mul_f32 v[18:19], v[18:19], v[146:147] op_sel_hi:[1,0]
	s_waitcnt lgkmcnt(0)
	v_add_f32_e32 v138, v138, v139
	v_fmamk_f32 v138, v138, 0x3a800000, v230
	v_mov_b32_e32 v140, v135
	v_mov_b32_e32 v141, v136
	v_mov_b32_e32 v135, v137
	v_pk_add_f32 v[134:135], v[140:141], v[134:135]
	v_rsq_f32_e32 v138, v138
	s_nop 0
	v_add_f32_e32 v134, v134, v135
	v_mov_b32_e32 v135, v134
	s_nop 1
	v_permlane16_swap_b32_e32 v135, v134
	v_pk_mul_f32 v[112:113], v[112:113], v[142:143] op_sel_hi:[1,0]
	v_pk_mul_f32 v[110:111], v[110:111], v[142:143] op_sel_hi:[1,0]
	v_pk_mul_f32 v[80:81], v[80:81], v[142:143] op_sel_hi:[1,0]
	v_pk_mul_f32 v[78:79], v[78:79], v[142:143] op_sel_hi:[1,0]
	s_waitcnt lgkmcnt(0)
	v_add_f32_e32 v134, v134, v135
	v_mov_b32_e32 v135, v134
	s_nop 1
	v_permlane32_swap_b32_e32 v135, v134
	v_pk_mul_f32 v[48:49], v[48:49], v[142:143] op_sel_hi:[1,0]
	v_pk_mul_f32 v[46:47], v[46:47], v[142:143] op_sel_hi:[1,0]
	v_pk_mul_f32 v[16:17], v[16:17], v[142:143] op_sel_hi:[1,0]
	v_pk_mul_f32 v[14:15], v[14:15], v[142:143] op_sel_hi:[1,0]
	s_waitcnt lgkmcnt(0)
	v_add_f32_e32 v134, v134, v135
	v_fmamk_f32 v134, v134, 0x3a800000, v230
	v_mov_b32_e32 v136, v131
	v_mov_b32_e32 v137, v132
	v_mov_b32_e32 v131, v133
	v_pk_add_f32 v[130:131], v[136:137], v[130:131]
	v_rsq_f32_e32 v134, v134
	s_nop 0
	v_add_f32_e32 v130, v130, v131
	v_mov_b32_e32 v131, v130
	s_nop 1
	v_permlane16_swap_b32_e32 v131, v130
	v_pk_mul_f32 v[108:109], v[108:109], v[138:139] op_sel_hi:[1,0]
	v_pk_mul_f32 v[106:107], v[106:107], v[138:139] op_sel_hi:[1,0]
	v_pk_mul_f32 v[76:77], v[76:77], v[138:139] op_sel_hi:[1,0]
	v_pk_mul_f32 v[74:75], v[74:75], v[138:139] op_sel_hi:[1,0]
	s_waitcnt lgkmcnt(0)
	v_add_f32_e32 v130, v130, v131
	v_mov_b32_e32 v131, v130
	s_nop 1
	v_permlane32_swap_b32_e32 v131, v130
	v_pk_mul_f32 v[44:45], v[44:45], v[138:139] op_sel_hi:[1,0]
	v_pk_mul_f32 v[42:43], v[42:43], v[138:139] op_sel_hi:[1,0]
	v_pk_mul_f32 v[12:13], v[12:13], v[138:139] op_sel_hi:[1,0]
	v_pk_mul_f32 v[10:11], v[10:11], v[138:139] op_sel_hi:[1,0]
	s_waitcnt lgkmcnt(0)
	v_add_f32_e32 v130, v130, v131
	v_fmamk_f32 v130, v130, 0x3a800000, v230
	v_rsq_f32_e32 v130, v130
	s_nop 0
	v_pk_mul_f32 v[104:105], v[104:105], v[134:135] op_sel_hi:[1,0]
	v_pk_mul_f32 v[102:103], v[102:103], v[134:135] op_sel_hi:[1,0]
	v_pk_mul_f32 v[72:73], v[72:73], v[134:135] op_sel_hi:[1,0]
	v_pk_mul_f32 v[70:71], v[70:71], v[134:135] op_sel_hi:[1,0]
	v_pk_mul_f32 v[40:41], v[40:41], v[134:135] op_sel_hi:[1,0]
	v_pk_mul_f32 v[38:39], v[38:39], v[134:135] op_sel_hi:[1,0]
	v_pk_mul_f32 v[8:9], v[8:9], v[134:135] op_sel_hi:[1,0]
	v_pk_mul_f32 v[6:7], v[6:7], v[134:135] op_sel_hi:[1,0]
	v_pk_mul_f32 v[100:101], v[100:101], v[130:131] op_sel_hi:[1,0]
	v_pk_mul_f32 v[98:99], v[98:99], v[130:131] op_sel_hi:[1,0]
	v_pk_mul_f32 v[68:69], v[68:69], v[130:131] op_sel_hi:[1,0]
	v_pk_mul_f32 v[66:67], v[66:67], v[130:131] op_sel_hi:[1,0]
	v_pk_mul_f32 v[36:37], v[36:37], v[130:131] op_sel_hi:[1,0]
	v_pk_mul_f32 v[34:35], v[34:35], v[130:131] op_sel_hi:[1,0]
	v_pk_mul_f32 v[4:5], v[4:5], v[130:131] op_sel_hi:[1,0]
	v_pk_mul_f32 v[2:3], v[2:3], v[130:131] op_sel_hi:[1,0]

; __device__ __forceinline__ float swap32_add(float v) { auto rr = __builtin_amdgcn_permlane32_swap(__float_as_uint(v), __float_as_uint(v), false, false); return __uint_as_float(rr[0]) + __uint_as_float(rr[1]); }
; template <int D, int DV, bool TAB, bool BITS, int KT> ...
;     ...
;     const float lt = swap32_add(l_run);
;     if (hi == 0) wsf[r32] = 1.0f / fmaxf(lt, 1e-30f);
;     __builtin_amdgcn_fence(__ATOMIC_RELEASE, "wavefront"); __builtin_amdgcn_wave_barrier();
; #pragma unroll
;     for (int j = 0; j < 4; ++j) { const f32x4 a4 = *(const f32x4*)(wsf + 8 * j + 4 * hi);
; #pragma unroll
;         for (int dt = 0; dt < DV / 32; ++dt) { o[dt][4 * j + 0] *= a4[0]; o[dt][4 * j + 1] *= a4[1]; o[dt][4 * j + 2] *= a4[2]; o[dt][4 * j + 3] *= a4[3]; } }
; __device__ __forceinline__ void unitA(unsigned char* lds, const MixCtx& c, int b, int h, int qb, bool ltab) {
;     ...
;     { const float* st = c.stash + (size_t)blockIdx.x * 512 + tid_o; asm volatile("" : "+v"(st) :: "memory");
; #pragma unroll
;       for (int dt = 0; dt < 4; ++dt)
; #pragma unroll
;           for (int r = 0; r < 16; ++r) oa[dt][r] = st[(size_t)(dt * 16 + r) * c.nthr]; }
.LBB0_336:
	s_waitcnt lgkmcnt(0)
	v_mul_f32_e32 v92, v48, v80
	v_mul_f32_e32 v48, v44, v76
	v_mul_f32_e32 v44, v40, v72
	v_mul_f32_e32 v40, v36, v68
	v_mul_f32_e32 v36, v2, v66
	v_mov_b32_e32 v2, v228
	v_readlane_b32 s4, v254, 30
	v_mul_f32_e32 v96, v32, v80
	v_mul_f32_e32 v32, v30, v78
	v_mul_f32_e32 v30, v60, v76
	v_mul_f32_e32 v60, v55, v71
	v_mul_f32_e32 v55, v3, v67
	v_readlane_b32 s5, v254, 31
	v_ashrrev_i32_e32 v3, 31, v2
	v_mul_f32_e32 v91, v65, v81
	v_mul_f32_e32 v65, v28, v76
	v_mul_f32_e32 v28, v41, v73
	v_mul_f32_e32 v41, v37, v69
	v_mul_f32_e32 v37, v35, v67
	v_mul_f32_e32 v0, v34, v66
	v_lshl_add_u64 v[34:35], v[2:3], 2, s[4:5]
	v_mul_f32_e32 v94, v64, v80
	v_mul_f32_e32 v64, v59, v75
	v_mul_f32_e32 v59, v54, v70
	flat_load_dword v54, v[34:35]
	v_lshl_add_u64 v[34:35], s[66:67], 2, v[34:35]
	flat_load_dword v3, v[34:35]
	v_lshl_add_u64 v[34:35], v[34:35], 0, s[68:69]
	v_mul_f32_e32 v93, v33, v81
	v_mul_f32_e32 v33, v31, v79
	v_mul_f32_e32 v31, v61, v77
	v_mul_f32_e32 v61, v56, v72
	flat_load_dword v56, v[34:35]
	v_lshl_add_u64 v[34:35], v[34:35], 0, s[68:69]
	v_mul_f32_e32 v90, v49, v81
	s_waitcnt vmcnt(0)
	v_mul_f32_e32 v98, v46, v78
	v_mul_f32_e32 v49, v45, v77
	v_mul_f32_e32 v46, v42, v74
	v_mul_f32_e32 v42, v38, v70
	v_mul_f32_e32 v45, v25, v73
	v_mul_f32_e32 v25, v24, v72
	v_mul_f32_e32 v24, v23, v71
	v_mul_f32_e32 v23, v22, v70
	v_mul_f32_e32 v6, v6, v70
	flat_load_dword v70, v[34:35]
	v_lshl_add_u64 v[34:35], v[34:35], 0, s[68:69]
	v_mul_f32_e32 v97, v63, v79
	v_mul_f32_e32 v63, v58, v74
	flat_load_dword v58, v[34:35]
	v_lshl_add_u64 v[34:35], v[34:35], 0, s[68:69]
	v_mul_f32_e32 v22, v53, v69
	v_mul_f32_e32 v53, v21, v69
	v_mul_f32_e32 v5, v5, v69
	flat_load_dword v69, v[34:35]
	v_lshl_add_u64 v[34:35], v[34:35], 0, s[68:69]
	v_mul_f32_e32 v99, v62, v78
	v_mul_f32_e32 v14, v14, v78
	v_mul_f32_e32 v78, v29, v77
	v_mul_f32_e32 v29, v27, v75
	v_mul_f32_e32 v27, v57, v73
	v_mul_f32_e32 v57, v52, v68
	v_mul_f32_e32 v21, v20, v68
	v_mul_f32_e32 v4, v4, v68
	flat_load_dword v68, v[34:35]
	v_lshl_add_u64 v[34:35], v[34:35], 0, s[68:69]
	v_mul_f32_e32 v95, v47, v79
	v_mul_f32_e32 v47, v43, v75
	v_mul_f32_e32 v43, v39, v71
	v_mul_f32_e32 v39, v51, v67
	v_mul_f32_e32 v20, v19, v67
	flat_load_dword v67, v[34:35]
	v_lshl_add_u64 v[34:35], v[34:35], 0, s[68:69]
	flat_load_dword v62, v[34:35]
	v_lshl_add_u64 v[34:35], v[34:35], 0, s[68:69]
	v_mul_f32_e32 v38, v50, v66
	v_mul_f32_e32 v19, v18, v66
	flat_load_dword v66, v[34:35]
	v_lshl_add_u64 v[34:35], v[34:35], 0, s[68:69]
	flat_load_dword v52, v[34:35]
	v_lshl_add_u64 v[34:35], v[34:35], 0, s[68:69]
	flat_load_dword v51, v[34:35]
	v_lshl_add_u64 v[34:35], v[34:35], 0, s[68:69]
	v_mul_f32_e32 v9, v9, v73
	v_mul_f32_e32 v8, v8, v72
	v_lshl_add_u64 v[72:73], v[34:35], 0, s[68:69]
	flat_load_dword v50, v[34:35]
	v_mul_f32_e32 v7, v7, v71
	flat_load_dword v35, v[72:73]
	v_lshl_add_u64 v[72:73], v[72:73], 0, s[68:69]
	flat_load_dword v34, v[72:73]
	v_lshl_add_u64 v[72:73], v[72:73], 0, s[68:69]
	flat_load_dword v18, v[72:73]
	v_lshl_add_u64 v[72:73], v[72:73], 0, s[68:69]
	flat_load_dword v71, v[72:73]
	v_lshl_add_u64 v[72:73], v[72:73], 0, s[68:69]
	v_mul_f32_e32 v26, v26, v74
	v_mul_f32_e32 v10, v10, v74
	flat_load_dword v74, v[72:73]
	v_lshl_add_u64 v[72:73], v[72:73], 0, s[68:69]
	v_mul_f32_e32 v11, v11, v75
	flat_load_dword v75, v[72:73]
	v_lshl_add_u64 v[72:73], v[72:73], 0, s[68:69]
	v_mul_f32_e32 v12, v12, v76
	flat_load_dword v76, v[72:73]
	v_lshl_add_u64 v[72:73], v[72:73], 0, s[68:69]
	v_mul_f32_e32 v13, v13, v77
	flat_load_dword v77, v[72:73]
	v_lshl_add_u64 v[72:73], v[72:73], 0, s[68:69]
	v_mul_f32_e32 v15, v15, v79
	flat_load_dword v79, v[72:73]
	v_lshl_add_u64 v[72:73], v[72:73], 0, s[68:69]
	v_mul_f32_e32 v16, v16, v80
	flat_load_dword v80, v[72:73]
	v_lshl_add_u64 v[72:73], v[72:73], 0, s[68:69]
	v_mul_f32_e32 v17, v17, v81
	flat_load_dword v81, v[72:73]
	v_lshl_add_u64 v[72:73], v[72:73], 0, s[68:69]
	flat_load_dword v83, v[72:73]
	v_lshl_add_u64 v[72:73], v[72:73], 0, s[68:69]
	flat_load_dword v85, v[72:73]
	v_lshl_add_u64 v[72:73], v[72:73], 0, s[68:69]
	flat_load_dword v87, v[72:73]
	v_lshl_add_u64 v[72:73], v[72:73], 0, s[68:69]
	flat_load_dword v101, v[72:73]
	v_lshl_add_u64 v[72:73], v[72:73], 0, s[68:69]
	flat_load_dword v102, v[72:73]
	v_lshl_add_u64 v[72:73], v[72:73], 0, s[68:69]
	flat_load_dword v103, v[72:73]
	v_lshl_add_u64 v[72:73], v[72:73], 0, s[68:69]
	flat_load_dword v104, v[72:73]
	v_lshl_add_u64 v[72:73], v[72:73], 0, s[68:69]
	flat_load_dword v105, v[72:73]
	v_lshl_add_u64 v[72:73], v[72:73], 0, s[68:69]
	flat_load_dword v82, v[72:73]
	v_lshl_add_u64 v[72:73], v[72:73], 0, s[68:69]
	flat_load_dword v84, v[72:73]
	v_lshl_add_u64 v[72:73], v[72:73], 0, s[68:69]
	flat_load_dword v86, v[72:73]
	v_lshl_add_u64 v[72:73], v[72:73], 0, s[68:69]
	flat_load_dword v106, v[72:73]
	v_lshl_add_u64 v[72:73], v[72:73], 0, s[68:69]
	flat_load_dword v107, v[72:73]
	v_lshl_add_u64 v[72:73], v[72:73], 0, s[68:69]
	flat_load_dword v108, v[72:73]
	v_lshl_add_u64 v[72:73], v[72:73], 0, s[68:69]
	flat_load_dword v109, v[72:73]
	v_lshl_add_u64 v[72:73], v[72:73], 0, s[68:69]
	flat_load_dword v110, v[72:73]
	v_lshl_add_u64 v[72:73], v[72:73], 0, s[68:69]
	flat_load_dword v111, v[72:73]
	v_lshl_add_u64 v[72:73], v[72:73], 0, s[68:69]
	flat_load_dword v112, v[72:73]
	v_lshl_add_u64 v[72:73], v[72:73], 0, s[68:69]
	flat_load_dword v113, v[72:73]
	v_lshl_add_u64 v[72:73], v[72:73], 0, s[68:69]
	flat_load_dword v114, v[72:73]
	v_lshl_add_u64 v[72:73], v[72:73], 0, s[68:69]
	flat_load_dword v115, v[72:73]
	v_lshl_add_u64 v[72:73], v[72:73], 0, s[68:69]
	flat_load_dword v116, v[72:73]
; __device__ __forceinline__ void unitA(unsigned char* lds, const MixCtx& c, int b, int h, int qb, bool ltab) {
;     ...
;     float ss[16];
; #pragma unroll
;     for (int r = 0; r < 16; ++r) { float s = 0.f;
; #pragma unroll
;         for (int dt = 0; dt < 4; ++dt) { const float v = oa[dt][r] - lam * ob[dt][r]; oa[dt][r] = v; s += v * v; }
;         ss[r] = s; }
; #pragma unroll
;     for (int r = 0; r < 16; ++r) {
; #pragma unroll
;         for (int o = 1; o < 32; o <<= 1) ss[r] += __shfl_xor(ss[r], o);
;         ss[r] = (1.0f - lam_init) / sqrtf(ss[r] * (1.f / 128.f) + EPSN); }
	v_lshl_add_u64 v[72:73], v[72:73], 0, s[68:69]
	flat_load_dword v117, v[72:73]
	v_lshl_add_u64 v[72:73], v[72:73], 0, s[68:69]
	flat_load_dword v118, v[72:73]
	v_lshl_add_u64 v[72:73], v[72:73], 0, s[68:69]
	flat_load_dword v100, v[72:73]
	v_lshl_add_u64 v[72:73], v[72:73], 0, s[68:69]
	flat_load_dword v119, v[72:73]
	v_lshl_add_u64 v[72:73], v[72:73], 0, s[68:69]
	flat_load_dword v120, v[72:73]
	v_lshl_add_u64 v[72:73], v[72:73], 0, s[68:69]
	flat_load_dword v121, v[72:73]
	v_lshl_add_u64 v[72:73], v[72:73], 0, s[68:69]
	flat_load_dword v122, v[72:73]
	v_lshl_add_u64 v[72:73], v[72:73], 0, s[68:69]
	flat_load_dword v123, v[72:73]
	v_lshl_add_u64 v[72:73], v[72:73], 0, s[68:69]
	flat_load_dword v124, v[72:73]
	v_lshl_add_u64 v[72:73], v[72:73], 0, s[68:69]
	flat_load_dword v125, v[72:73]
	v_lshl_add_u64 v[72:73], v[72:73], 0, s[68:69]
	flat_load_dword v126, v[72:73]
	v_lshl_add_u64 v[72:73], v[72:73], 0, s[68:69]
	flat_load_dword v127, v[72:73]
	v_lshl_add_u64 v[72:73], v[72:73], 0, s[68:69]
	flat_load_dword v128, v[72:73]
	v_lshl_add_u64 v[72:73], v[72:73], 0, s[68:69]
	flat_load_dword v129, v[72:73]
	v_lshl_add_u64 v[72:73], v[72:73], 0, s[68:69]
	flat_load_dword v130, v[72:73]
	v_lshl_add_u64 v[72:73], v[72:73], 0, s[68:69]
	flat_load_dword v131, v[72:73]
	v_lshl_add_u64 v[72:73], v[72:73], 0, s[68:69]
	flat_load_dword v132, v[72:73]
	v_lshl_add_u64 v[72:73], v[72:73], 0, s[68:69]
	flat_load_dword v73, v[72:73]
	s_waitcnt lgkmcnt(0)
	v_fma_f32 v54, -v36, v89, v54
	s_waitcnt vmcnt(0)
	v_fma_f32 v36, -v19, v89, v71
	v_mul_f32_e32 v133, v36, v36
	v_fma_f32 v58, -v6, v89, v58
	v_fmac_f32_e32 v133, v54, v54
	v_fma_f32 v62, -v10, v89, v62
	s_lshl_b32 s0, s0, 7
	s_ashr_i32 s1, s0, 31
	v_readlane_b32 s4, v253, 2
	s_lshl_b64 s[0:1], s[0:1], 2
	v_readlane_b32 s6, v253, 4
	v_readlane_b32 s5, v253, 3
	v_readlane_b32 s7, v253, 5
	s_add_u32 s4, s6, s0
	v_fma_f32 v55, -v55, v89, v3
	v_fma_f32 v56, -v4, v89, v56
	s_addc_u32 s5, s7, s1
	v_fma_f32 v19, -v38, v89, v82
	v_fma_f32 v38, -v20, v89, v74
	v_fma_f32 v20, -v39, v89, v84
	v_fma_f32 v39, -v21, v89, v75
	v_fma_f32 v21, -v57, v89, v86
	v_fma_f32 v57, -v5, v89, v70
	v_fmac_f32_e32 v133, v19, v19
	v_fma_f32 v22, -v22, v89, v106
	v_and_b32_e32 v2, 31, v2
	v_readlane_b32 s16, v253, 14
	v_readlane_b32 s17, v253, 15
	v_readlane_b32 s18, v253, 16
	v_readlane_b32 s19, v253, 17
	s_mov_b64 s[16:17], s[24:25]
	v_fma_f32 v27, -v27, v89, v110
	s_mov_b64 s[18:19], s[50:51]
	v_readlane_b32 s8, v253, 6
	v_readlane_b32 s9, v253, 7
	v_readlane_b32 s10, v253, 8
	v_readlane_b32 s11, v253, 9
	v_fma_f32 v30, -v30, v89, v113
	v_readlane_b32 s12, v253, 10
	v_fma_f32 v31, -v31, v89, v114
	v_readlane_b32 s13, v253, 11
	v_readlane_b32 s14, v253, 12
	v_readlane_b32 s15, v253, 13
	v_fma_f32 v0, -v0, v89, v100
	v_fmac_f32_e32 v133, v0, v0
	v_fma_f32 v3, -v37, v89, v119
	v_mul_f32_e32 v100, v38, v38
	v_fma_f32 v4, -v40, v89, v120
	v_fma_f32 v40, -v53, v89, v76
	v_fma_f32 v5, -v41, v89, v121
	v_fma_f32 v41, -v23, v89, v77
	v_fma_f32 v23, -v59, v89, v107
	v_fma_f32 v59, -v7, v89, v69
	v_fma_f32 v69, -v17, v89, v18
	v_and_b32_e32 v18, 64, v229
	v_fma_f32 v6, -v42, v89, v122
	v_fma_f32 v42, -v24, v89, v79
	v_fma_f32 v24, -v60, v89, v108
	v_fma_f32 v60, -v8, v89, v68
	v_fma_f32 v8, -v44, v89, v124
	v_fma_f32 v44, -v45, v89, v81
	v_fma_f32 v45, -v26, v89, v83
	v_add_u32_e32 v18, 64, v18
	v_xor_b32_e32 v26, 1, v229
	v_cmp_lt_i32_e32 vcc, v26, v18
	v_xor_b32_e32 v77, 2, v229
	v_fma_f32 v10, -v46, v89, v126
	v_cndmask_b32_e32 v26, v229, v26, vcc
	v_lshlrev_b32_e32 v75, 2, v26
	v_cmp_lt_i32_e32 vcc, v77, v18
	v_fma_f32 v46, -v29, v89, v85
	v_fma_f32 v29, -v64, v89, v112
	v_cndmask_b32_e32 v77, v229, v77, vcc
	s_waitcnt lgkmcnt(0)
	s_nop 1
	v_add_f32_dpp v26, v133, v133 quad_perm:[1,0,3,2] row_mask:0xf bank_mask:0xf
	v_lshlrev_b32_e32 v77, 2, v77
	v_fma_f32 v64, -v12, v89, v52
	v_fma_f32 v12, -v48, v89, v128
	v_fma_f32 v48, -v78, v89, v101
	v_fma_f32 v7, -v43, v89, v123
	v_fma_f32 v43, -v25, v89, v80
	v_fma_f32 v17, -v90, v89, v73
	v_sub_f32_e32 v73, 1.0, v88
	s_waitcnt lgkmcnt(0)
	s_nop 1
	v_add_f32_dpp v26, v26, v26 quad_perm:[2,3,0,1] row_mask:0xf bank_mask:0xf
	v_xor_b32_e32 v78, 4, v229
	v_cmp_lt_i32_e32 vcc, v78, v18
	v_fma_f32 v25, -v61, v89, v109
	v_fma_f32 v61, -v9, v89, v67
	v_cndmask_b32_e32 v78, v229, v78, vcc
	v_lshlrev_b32_e32 v78, 2, v78
	v_fma_f32 v9, -v28, v89, v125
	v_fma_f32 v28, -v63, v89, v111
	v_fma_f32 v63, -v11, v89, v66
	v_fma_f32 v11, -v47, v89, v127
	s_waitcnt lgkmcnt(0)
	s_nop 1
	v_add_f32_dpp v26, v26, v26 row_half_mirror row_mask:0xf bank_mask:0xf
	v_xor_b32_e32 v79, 8, v229
	v_cmp_lt_i32_e32 vcc, v79, v18
	v_fma_f32 v47, -v65, v89, v87
	v_fma_f32 v65, -v13, v89, v51
	v_cndmask_b32_e32 v79, v229, v79, vcc
	v_lshlrev_b32_e32 v79, 2, v79
	v_fma_f32 v13, -v49, v89, v129
	v_fma_f32 v66, -v14, v89, v50
	v_fma_f32 v49, -v32, v89, v102
	v_fma_f32 v32, -v99, v89, v115
	s_waitcnt lgkmcnt(0)
	s_nop 1
	v_add_f32_dpp v26, v26, v26 row_mirror row_mask:0xf bank_mask:0xf
	v_xor_b32_e32 v80, 16, v229
	v_cmp_lt_i32_e32 vcc, v80, v18
	v_fma_f32 v14, -v98, v89, v130
	v_fma_f32 v67, -v15, v89, v35
	v_cndmask_b32_e32 v18, v229, v80, vcc
	v_lshlrev_b32_e32 v80, 2, v18
	v_mov_b32_e32 v18, v26
	s_nop 1
	v_permlane16_swap_b32_e32 v18, v26
	v_fma_f32 v50, -v33, v89, v103
	v_fma_f32 v33, -v97, v89, v116
	v_fma_f32 v15, -v95, v89, v131
	v_fma_f32 v68, -v16, v89, v34
	s_waitcnt lgkmcnt(0)
; __device__ __forceinline__ void unitA(unsigned char* lds, const MixCtx& c, int b, int h, int qb, bool ltab) {
;     ...
;     for (int r = 0; r < 16; ++r) { float s = 0.f;
; #pragma unroll
;         for (int dt = 0; dt < 4; ++dt) { const float v = oa[dt][r] - lam * ob[dt][r]; oa[dt][r] = v; s += v * v; }
;         ss[r] = s; }
; #pragma unroll
;     for (int r = 0; r < 16; ++r) {
; #pragma unroll
;         for (int o = 1; o < 32; o <<= 1) ss[r] += __shfl_xor(ss[r], o);
;         ss[r] = (1.0f - lam_init) / sqrtf(ss[r] * (1.f / 128.f) + EPSN); }
; #pragma unroll
;     for (int dt = 0; dt < 4; ++dt) { const float g = subln[dt * 32 + r32];
; #pragma unroll
;         for (int r = 0; r < 16; ++r) oa[dt][r] = oa[dt][r] * ss[r] * g; }
	v_add_f32_e32 v18, v26, v18
	v_fmamk_f32 v18, v18, 0x3c000000, v230
	v_fma_f32 v51, -v96, v89, v104
	v_fma_f32 v34, -v94, v89, v117
	v_fma_f32 v16, -v92, v89, v132
	v_fma_f32 v52, -v93, v89, v105
	v_fma_f32 v35, -v91, v89, v118
	v_fmac_f32_e32 v100, v55, v55
	v_fmac_f32_e32 v100, v20, v20
	v_fmac_f32_e32 v100, v3, v3
	v_mul_f32_e32 v37, v39, v39
	v_fmac_f32_e32 v37, v56, v56
	v_fmac_f32_e32 v37, v21, v21
	v_fmac_f32_e32 v37, v4, v4
	v_mul_f32_e32 v53, v40, v40
	v_rsq_f32_e32 v18, v18
	s_nop 0
	v_mul_f32_e32 v18, v73, v18
	v_fmac_f32_e32 v53, v57, v57
	v_fmac_f32_e32 v53, v22, v22
	v_fmac_f32_e32 v53, v5, v5
	v_mul_f32_e32 v70, v41, v41
	s_waitcnt lgkmcnt(0)
	s_nop 1
	v_add_f32_dpp v26, v100, v100 quad_perm:[1,0,3,2] row_mask:0xf bank_mask:0xf
	v_fmac_f32_e32 v70, v58, v58
	v_fmac_f32_e32 v70, v23, v23
	v_fmac_f32_e32 v70, v6, v6
	v_mul_f32_e32 v71, v42, v42
	s_waitcnt lgkmcnt(0)
	s_nop 1
	v_add_f32_dpp v26, v26, v26 quad_perm:[2,3,0,1] row_mask:0xf bank_mask:0xf
	v_fmac_f32_e32 v71, v59, v59
	v_fmac_f32_e32 v71, v24, v24
	v_fmac_f32_e32 v71, v7, v7
	v_mul_f32_e32 v76, v43, v43
	s_waitcnt lgkmcnt(0)
	s_nop 1
	v_add_f32_dpp v26, v26, v26 row_half_mirror row_mask:0xf bank_mask:0xf
	v_fmac_f32_e32 v76, v60, v60
	v_fmac_f32_e32 v76, v25, v25
	v_fmac_f32_e32 v76, v8, v8
	v_mul_f32_e32 v82, v44, v44
	s_waitcnt lgkmcnt(0)
	s_nop 1
	v_add_f32_dpp v26, v26, v26 row_mirror row_mask:0xf bank_mask:0xf
	v_mov_b32_e32 v88, v26
	s_nop 1
	v_permlane16_swap_b32_e32 v88, v26
	v_fmac_f32_e32 v82, v61, v61
	v_fmac_f32_e32 v82, v27, v27
	v_fmac_f32_e32 v82, v9, v9
	v_mul_f32_e32 v84, v45, v45
	s_waitcnt lgkmcnt(0)
	v_add_f32_e32 v26, v26, v88
	v_fmamk_f32 v26, v26, 0x3c000000, v230
	v_fmac_f32_e32 v84, v62, v62
	v_fmac_f32_e32 v84, v28, v28
	v_fmac_f32_e32 v84, v10, v10
	v_mul_f32_e32 v86, v46, v46
	v_fmac_f32_e32 v86, v63, v63
	v_fmac_f32_e32 v86, v29, v29
	v_fmac_f32_e32 v86, v11, v11
	v_mul_f32_e32 v87, v47, v47
	v_fmac_f32_e32 v87, v64, v64
	v_fmac_f32_e32 v87, v30, v30
	v_fmac_f32_e32 v87, v12, v12
	v_mul_f32_e32 v85, v48, v48
	v_rsq_f32_e32 v26, v26
	s_nop 0
	v_mul_f32_e32 v26, v73, v26
	v_fmac_f32_e32 v85, v65, v65
	v_fmac_f32_e32 v85, v31, v31
	v_fmac_f32_e32 v85, v13, v13
	v_mul_f32_e32 v83, v49, v49
	s_waitcnt lgkmcnt(0)
	s_nop 1
	v_add_f32_dpp v37, v37, v37 quad_perm:[1,0,3,2] row_mask:0xf bank_mask:0xf
	v_fmac_f32_e32 v83, v66, v66
	v_fmac_f32_e32 v83, v32, v32
	v_fmac_f32_e32 v83, v14, v14
	v_mul_f32_e32 v81, v50, v50
	s_waitcnt lgkmcnt(0)
	s_nop 1
	v_add_f32_dpp v37, v37, v37 quad_perm:[2,3,0,1] row_mask:0xf bank_mask:0xf
	v_fmac_f32_e32 v81, v67, v67
	v_fmac_f32_e32 v81, v33, v33
	v_fmac_f32_e32 v81, v15, v15
	v_mul_f32_e32 v74, v51, v51
	s_waitcnt lgkmcnt(0)
	s_nop 1
	v_add_f32_dpp v37, v37, v37 row_half_mirror row_mask:0xf bank_mask:0xf
	v_fmac_f32_e32 v74, v68, v68
	v_fmac_f32_e32 v74, v34, v34
	v_fmac_f32_e32 v74, v16, v16
	v_mul_f32_e32 v72, v52, v52
	s_waitcnt lgkmcnt(0)
	s_nop 1
	v_add_f32_dpp v37, v37, v37 row_mirror row_mask:0xf bank_mask:0xf
	v_mov_b32_e32 v88, v37
	s_nop 1
	v_permlane16_swap_b32_e32 v88, v37
	v_fmac_f32_e32 v72, v69, v69
	v_fmac_f32_e32 v72, v35, v35
	v_fmac_f32_e32 v72, v17, v17
	v_mul_f32_e32 v54, v54, v18
	s_waitcnt lgkmcnt(0)
	v_add_f32_e32 v37, v37, v88
	v_fmamk_f32 v37, v37, 0x3c000000, v230
	v_mul_f32_e32 v36, v36, v18
	v_mul_f32_e32 v38, v38, v26
	v_mul_f32_e32 v19, v19, v18
	v_mul_f32_e32 v20, v20, v26
	v_mul_f32_e32 v0, v0, v18
	v_rsq_f32_e32 v37, v37
	s_nop 0
	v_mul_f32_e32 v37, v73, v37
	v_mul_f32_e32 v39, v39, v37
	v_mul_f32_e32 v21, v21, v37
	s_waitcnt lgkmcnt(0)
	s_nop 1
	v_add_f32_dpp v53, v53, v53 quad_perm:[1,0,3,2] row_mask:0xf bank_mask:0xf
	s_waitcnt lgkmcnt(0)
	s_nop 1
	v_add_f32_dpp v53, v53, v53 quad_perm:[2,3,0,1] row_mask:0xf bank_mask:0xf
	s_waitcnt lgkmcnt(0)
	s_nop 1
	v_add_f32_dpp v53, v53, v53 row_half_mirror row_mask:0xf bank_mask:0xf
	s_waitcnt lgkmcnt(0)
	s_nop 1
	v_add_f32_dpp v53, v53, v53 row_mirror row_mask:0xf bank_mask:0xf
	v_mov_b32_e32 v88, v53
	s_nop 1
	v_permlane16_swap_b32_e32 v88, v53
	s_waitcnt lgkmcnt(0)
	v_add_f32_e32 v53, v53, v88
	v_fmamk_f32 v53, v53, 0x3c000000, v230
	v_rsq_f32_e32 v53, v53
	s_nop 0
	v_mul_f32_e32 v53, v73, v53
	v_mul_f32_e32 v40, v40, v53
	v_mul_f32_e32 v22, v22, v53
	s_waitcnt lgkmcnt(0)
	s_nop 1
	v_add_f32_dpp v70, v70, v70 quad_perm:[1,0,3,2] row_mask:0xf bank_mask:0xf
	s_waitcnt lgkmcnt(0)
	s_nop 1
	v_add_f32_dpp v70, v70, v70 quad_perm:[2,3,0,1] row_mask:0xf bank_mask:0xf
	s_waitcnt lgkmcnt(0)
	s_nop 1
	v_add_f32_dpp v70, v70, v70 row_half_mirror row_mask:0xf bank_mask:0xf
	s_waitcnt lgkmcnt(0)
	s_nop 1
	v_add_f32_dpp v70, v70, v70 row_mirror row_mask:0xf bank_mask:0xf
	v_mov_b32_e32 v88, v70
	s_nop 1
	v_permlane16_swap_b32_e32 v88, v70
	s_waitcnt lgkmcnt(0)
	v_add_f32_e32 v70, v70, v88
	v_fmamk_f32 v70, v70, 0x3c000000, v230
	v_rsq_f32_e32 v70, v70
	s_nop 0
	v_mul_f32_e32 v70, v73, v70
	v_mul_f32_e32 v41, v41, v70
	v_mul_f32_e32 v23, v23, v70
	s_waitcnt lgkmcnt(0)
	s_nop 1
	v_add_f32_dpp v71, v71, v71 quad_perm:[1,0,3,2] row_mask:0xf bank_mask:0xf
	s_waitcnt lgkmcnt(0)
	s_nop 1
	v_add_f32_dpp v71, v71, v71 quad_perm:[2,3,0,1] row_mask:0xf bank_mask:0xf
	s_waitcnt lgkmcnt(0)
	s_nop 1
	v_add_f32_dpp v71, v71, v71 row_half_mirror row_mask:0xf bank_mask:0xf
	s_waitcnt lgkmcnt(0)
	s_nop 1
	v_add_f32_dpp v71, v71, v71 row_mirror row_mask:0xf bank_mask:0xf
	v_mov_b32_e32 v88, v71
	s_nop 1
	v_permlane16_swap_b32_e32 v88, v71
	s_waitcnt lgkmcnt(0)
	v_add_f32_e32 v71, v71, v88
	v_fmamk_f32 v71, v71, 0x3c000000, v230
	v_rsq_f32_e32 v71, v71
	s_nop 0
	v_mul_f32_e32 v71, v73, v71
	v_mul_f32_e32 v42, v42, v71
	v_mul_f32_e32 v24, v24, v71
	s_waitcnt lgkmcnt(0)
; __device__ __forceinline__ void unitA(unsigned char* lds, const MixCtx& c, int b, int h, int qb, bool ltab) {
;     ...
;     for (int r = 0; r < 16; ++r) {
; #pragma unroll
;         for (int o = 1; o < 32; o <<= 1) ss[r] += __shfl_xor(ss[r], o);
;         ss[r] = (1.0f - lam_init) / sqrtf(ss[r] * (1.f / 128.f) + EPSN); }
; #pragma unroll
;     for (int dt = 0; dt < 4; ++dt) { const float g = subln[dt * 32 + r32];
; #pragma unroll
;         for (int r = 0; r < 16; ++r) oa[dt][r] = oa[dt][r] * ss[r] * g; }
	s_nop 1
	v_add_f32_dpp v76, v76, v76 quad_perm:[1,0,3,2] row_mask:0xf bank_mask:0xf
	s_waitcnt lgkmcnt(0)
	s_nop 1
	v_add_f32_dpp v76, v76, v76 quad_perm:[2,3,0,1] row_mask:0xf bank_mask:0xf
	s_waitcnt lgkmcnt(0)
	s_nop 1
	v_add_f32_dpp v76, v76, v76 row_half_mirror row_mask:0xf bank_mask:0xf
	s_waitcnt lgkmcnt(0)
	s_nop 1
	v_add_f32_dpp v76, v76, v76 row_mirror row_mask:0xf bank_mask:0xf
	v_mov_b32_e32 v88, v76
	s_nop 1
	v_permlane16_swap_b32_e32 v88, v76
	s_waitcnt lgkmcnt(0)
	v_add_f32_e32 v76, v76, v88
	v_fmamk_f32 v76, v76, 0x3c000000, v230
	v_rsq_f32_e32 v76, v76
	s_nop 0
	v_mul_f32_e32 v76, v73, v76
	v_mul_f32_e32 v43, v43, v76
	v_mul_f32_e32 v25, v25, v76
	s_waitcnt lgkmcnt(0)
	s_nop 1
	v_add_f32_dpp v82, v82, v82 quad_perm:[1,0,3,2] row_mask:0xf bank_mask:0xf
	s_waitcnt lgkmcnt(0)
	s_nop 1
	v_add_f32_dpp v82, v82, v82 quad_perm:[2,3,0,1] row_mask:0xf bank_mask:0xf
	s_waitcnt lgkmcnt(0)
	s_nop 1
	v_add_f32_dpp v82, v82, v82 row_half_mirror row_mask:0xf bank_mask:0xf
	s_waitcnt lgkmcnt(0)
	s_nop 1
	v_add_f32_dpp v82, v82, v82 row_mirror row_mask:0xf bank_mask:0xf
	v_mov_b32_e32 v88, v82
	s_nop 1
	v_permlane16_swap_b32_e32 v88, v82
	s_waitcnt lgkmcnt(0)
	v_add_f32_e32 v82, v82, v88
	v_fmamk_f32 v82, v82, 0x3c000000, v230
	v_rsq_f32_e32 v82, v82
	s_nop 0
	v_mul_f32_e32 v82, v73, v82
	v_mul_f32_e32 v44, v44, v82
	v_mul_f32_e32 v27, v27, v82
	s_waitcnt lgkmcnt(0)
	s_nop 1
	v_add_f32_dpp v84, v84, v84 quad_perm:[1,0,3,2] row_mask:0xf bank_mask:0xf
	s_waitcnt lgkmcnt(0)
	s_nop 1
	v_add_f32_dpp v84, v84, v84 quad_perm:[2,3,0,1] row_mask:0xf bank_mask:0xf
	s_waitcnt lgkmcnt(0)
	s_nop 1
	v_add_f32_dpp v84, v84, v84 row_half_mirror row_mask:0xf bank_mask:0xf
	s_waitcnt lgkmcnt(0)
	s_nop 1
	v_add_f32_dpp v84, v84, v84 row_mirror row_mask:0xf bank_mask:0xf
	v_mov_b32_e32 v88, v84
	s_nop 1
	v_permlane16_swap_b32_e32 v88, v84
	s_waitcnt lgkmcnt(0)
	v_add_f32_e32 v84, v84, v88
	v_fmamk_f32 v84, v84, 0x3c000000, v230
	v_rsq_f32_e32 v84, v84
	s_nop 0
	v_mul_f32_e32 v84, v73, v84
	v_mul_f32_e32 v45, v45, v84
	v_mul_f32_e32 v28, v28, v84
	s_waitcnt lgkmcnt(0)
	s_nop 1
	v_add_f32_dpp v86, v86, v86 quad_perm:[1,0,3,2] row_mask:0xf bank_mask:0xf
	s_waitcnt lgkmcnt(0)
	s_nop 1
	v_add_f32_dpp v86, v86, v86 quad_perm:[2,3,0,1] row_mask:0xf bank_mask:0xf
	s_waitcnt lgkmcnt(0)
	s_nop 1
	v_add_f32_dpp v86, v86, v86 row_half_mirror row_mask:0xf bank_mask:0xf
	s_waitcnt lgkmcnt(0)
	s_nop 1
	v_add_f32_dpp v86, v86, v86 row_mirror row_mask:0xf bank_mask:0xf
	v_mov_b32_e32 v88, v86
	s_nop 1
	v_permlane16_swap_b32_e32 v88, v86
	s_waitcnt lgkmcnt(0)
	v_add_f32_e32 v86, v86, v88
	v_fmamk_f32 v86, v86, 0x3c000000, v230
	v_rsq_f32_e32 v86, v86
	s_nop 0
	v_mul_f32_e32 v86, v73, v86
	v_mul_f32_e32 v46, v46, v86
	v_mul_f32_e32 v29, v29, v86
	s_waitcnt lgkmcnt(0)
	s_nop 1
	v_add_f32_dpp v87, v87, v87 quad_perm:[1,0,3,2] row_mask:0xf bank_mask:0xf
	s_waitcnt lgkmcnt(0)
	s_nop 1
	v_add_f32_dpp v87, v87, v87 quad_perm:[2,3,0,1] row_mask:0xf bank_mask:0xf
	s_waitcnt lgkmcnt(0)
	s_nop 1
	v_add_f32_dpp v87, v87, v87 row_half_mirror row_mask:0xf bank_mask:0xf
	s_waitcnt lgkmcnt(0)
	s_nop 1
	v_add_f32_dpp v87, v87, v87 row_mirror row_mask:0xf bank_mask:0xf
	v_mov_b32_e32 v88, v87
	s_nop 1
	v_permlane16_swap_b32_e32 v88, v87
	s_waitcnt lgkmcnt(0)
	v_add_f32_e32 v87, v87, v88
	v_fmamk_f32 v87, v87, 0x3c000000, v230
	v_rsq_f32_e32 v87, v87
	s_nop 0
	v_mul_f32_e32 v87, v73, v87
	v_mul_f32_e32 v47, v47, v87
	v_mul_f32_e32 v30, v30, v87
	s_waitcnt lgkmcnt(0)
	s_nop 1
	v_add_f32_dpp v85, v85, v85 quad_perm:[1,0,3,2] row_mask:0xf bank_mask:0xf
	s_waitcnt lgkmcnt(0)
	s_nop 1
	v_add_f32_dpp v85, v85, v85 quad_perm:[2,3,0,1] row_mask:0xf bank_mask:0xf
	s_waitcnt lgkmcnt(0)
	s_nop 1
	v_add_f32_dpp v85, v85, v85 row_half_mirror row_mask:0xf bank_mask:0xf
	s_waitcnt lgkmcnt(0)
	s_nop 1
	v_add_f32_dpp v85, v85, v85 row_mirror row_mask:0xf bank_mask:0xf
	v_mov_b32_e32 v88, v85
	s_nop 1
	v_permlane16_swap_b32_e32 v88, v85
	s_waitcnt lgkmcnt(0)
	v_add_f32_e32 v85, v85, v88
	v_fmamk_f32 v85, v85, 0x3c000000, v230
	v_rsq_f32_e32 v85, v85
	s_nop 0
	v_mul_f32_e32 v85, v73, v85
	v_mul_f32_e32 v48, v48, v85
	v_mul_f32_e32 v31, v31, v85
	s_waitcnt lgkmcnt(0)
	s_nop 1
	v_add_f32_dpp v83, v83, v83 quad_perm:[1,0,3,2] row_mask:0xf bank_mask:0xf
	s_waitcnt lgkmcnt(0)
	s_nop 1
	v_add_f32_dpp v83, v83, v83 quad_perm:[2,3,0,1] row_mask:0xf bank_mask:0xf
	s_waitcnt lgkmcnt(0)
	s_nop 1
	v_add_f32_dpp v83, v83, v83 row_half_mirror row_mask:0xf bank_mask:0xf
	s_waitcnt lgkmcnt(0)
	s_nop 1
	v_add_f32_dpp v83, v83, v83 row_mirror row_mask:0xf bank_mask:0xf
	v_mov_b32_e32 v88, v83
	s_nop 1
	v_permlane16_swap_b32_e32 v88, v83
	s_waitcnt lgkmcnt(0)
	v_add_f32_e32 v83, v83, v88
	v_fmamk_f32 v83, v83, 0x3c000000, v230
	v_rsq_f32_e32 v83, v83
	s_nop 0
	v_mul_f32_e32 v83, v73, v83
	v_mul_f32_e32 v49, v49, v83
	v_mul_f32_e32 v32, v32, v83
	s_waitcnt lgkmcnt(0)
	s_nop 1
	v_add_f32_dpp v81, v81, v81 quad_perm:[1,0,3,2] row_mask:0xf bank_mask:0xf
	s_waitcnt lgkmcnt(0)
	s_nop 1
	v_add_f32_dpp v81, v81, v81 quad_perm:[2,3,0,1] row_mask:0xf bank_mask:0xf
	s_waitcnt lgkmcnt(0)
	s_nop 1
	v_add_f32_dpp v81, v81, v81 row_half_mirror row_mask:0xf bank_mask:0xf
	s_waitcnt lgkmcnt(0)
	s_nop 1
	v_add_f32_dpp v81, v81, v81 row_mirror row_mask:0xf bank_mask:0xf
	v_mov_b32_e32 v88, v81
	s_nop 1
	v_permlane16_swap_b32_e32 v88, v81
	s_waitcnt lgkmcnt(0)
	v_add_f32_e32 v81, v81, v88
	v_fmamk_f32 v81, v81, 0x3c000000, v230
	v_rsq_f32_e32 v81, v81
	s_nop 0
	v_mul_f32_e32 v81, v73, v81
	v_mul_f32_e32 v50, v50, v81
	v_mul_f32_e32 v33, v33, v81
	s_waitcnt lgkmcnt(0)
	s_nop 1
	v_add_f32_dpp v74, v74, v74 quad_perm:[1,0,3,2] row_mask:0xf bank_mask:0xf
	s_waitcnt lgkmcnt(0)
; __device__ __forceinline__ unsigned cvtpk(float lo, float hi) { f32x2_t v = {lo, hi}; bf16x2_t b = __builtin_convertvector(v, bf16x2_t); return __builtin_bit_cast(unsigned, b); }
; __device__ __forceinline__ int crowc(int r) { return (r & 3) + 8 * (r >> 2); }
; template <int DV>
; __device__ __forceinline__ void attn_store(const f32x16 (&o)[DV / 32], bf16_t* Op, int ldo) {
;     ...
;         for (int r = 0; r < 16; ++r) { const int row = 32 * wid + crowc(r) + 4 * hi; Op[(size_t)row * ldo + dt * 32 + r32] = (bf16_t)(cvtpk(o[dt][r], 0.f) & 0xffffu); }
; __device__ __forceinline__ void unitA(unsigned char* lds, const MixCtx& c, int b, int h, int qb, bool ltab) {
;     ...
;     for (int r = 0; r < 16; ++r) {
; #pragma unroll
;         for (int o = 1; o < 32; o <<= 1) ss[r] += __shfl_xor(ss[r], o);
;         ss[r] = (1.0f - lam_init) / sqrtf(ss[r] * (1.f / 128.f) + EPSN); }
; #pragma unroll
;     for (int dt = 0; dt < 4; ++dt) { const float g = subln[dt * 32 + r32];
; #pragma unroll
;         for (int r = 0; r < 16; ++r) oa[dt][r] = oa[dt][r] * ss[r] * g; }
;     attn_store<128>(oa, c.MIX + (tokb + q0) * DM + h * 128, DM);
	s_nop 1
	v_add_f32_dpp v72, v72, v72 quad_perm:[1,0,3,2] row_mask:0xf bank_mask:0xf
	s_waitcnt lgkmcnt(0)
	s_nop 1
	v_add_f32_dpp v74, v74, v74 quad_perm:[2,3,0,1] row_mask:0xf bank_mask:0xf
	s_waitcnt lgkmcnt(0)
	s_nop 1
	v_add_f32_dpp v72, v72, v72 quad_perm:[2,3,0,1] row_mask:0xf bank_mask:0xf
	s_waitcnt lgkmcnt(0)
	s_nop 1
	v_add_f32_dpp v74, v74, v74 row_half_mirror row_mask:0xf bank_mask:0xf
	s_waitcnt lgkmcnt(0)
	s_nop 1
	v_add_f32_dpp v72, v72, v72 row_half_mirror row_mask:0xf bank_mask:0xf
	s_waitcnt lgkmcnt(0)
	s_nop 1
	v_add_f32_dpp v74, v74, v74 row_mirror row_mask:0xf bank_mask:0xf
	v_mov_b32_e32 v88, v74
	s_nop 1
	v_permlane16_swap_b32_e32 v88, v74
	s_waitcnt lgkmcnt(0)
	s_nop 1
	v_add_f32_dpp v72, v72, v72 row_mirror row_mask:0xf bank_mask:0xf
	v_mov_b32_e32 v75, v72
	s_nop 1
	v_permlane16_swap_b32_e32 v75, v72
	s_waitcnt lgkmcnt(0)
	v_add_f32_e32 v74, v74, v88
	v_fmamk_f32 v74, v74, 0x3c000000, v230
	s_waitcnt lgkmcnt(0)
	v_add_f32_e32 v72, v72, v75
	v_fmamk_f32 v72, v72, 0x3c000000, v230
	v_lshlrev_b32_e32 v89, 2, v2
	global_load_dword v2, v89, s[4:5]
	v_rsq_f32_e32 v74, v74
	s_nop 0
	v_mul_f32_e32 v74, v73, v74
	v_mul_f32_e32 v51, v51, v74
	v_mul_f32_e32 v34, v34, v74
	s_waitcnt vmcnt(0)
	v_mul_f32_e32 v88, v54, v2
	v_mul_f32_e32 v54, v55, v26
	s_lshl_b64 s[0:1], s[54:55], 11
	s_add_u32 s0, s2, s0
	s_addc_u32 s1, s3, s1
	v_mul_f32_e32 v80, v54, v2
	v_mul_f32_e32 v54, v56, v37
	v_mul_f32_e32 v79, v54, v2
	v_mul_f32_e32 v54, v57, v53
	v_mul_f32_e32 v78, v54, v2
	v_mul_f32_e32 v54, v58, v70
	v_mul_f32_e32 v77, v54, v2
	v_mul_f32_e32 v54, v59, v71
	v_rsq_f32_e32 v72, v72
	s_nop 0
	v_mul_f32_e32 v72, v73, v72
	v_mul_f32_e32 v75, v54, v2
	v_mul_f32_e32 v54, v60, v76
	v_mul_f32_e32 v73, v54, v2
	v_mul_f32_e32 v54, v61, v82
	v_mul_f32_e32 v61, v54, v2
	v_mul_f32_e32 v54, v62, v84
	v_mul_f32_e32 v60, v54, v2
	v_mul_f32_e32 v54, v63, v86
	v_mul_f32_e32 v59, v54, v2
	v_mul_f32_e32 v54, v64, v87
	v_mul_f32_e32 v58, v54, v2
	v_mul_f32_e32 v54, v65, v85
	v_mul_f32_e32 v57, v54, v2
	v_mul_f32_e32 v54, v66, v83
	v_mul_f32_e32 v56, v54, v2
	v_mul_f32_e32 v54, v67, v81
	v_mul_f32_e32 v55, v54, v2
	v_mul_f32_e32 v54, v68, v74
	v_mul_f32_e32 v62, v69, v72
	v_mul_f32_e32 v54, v2, v54
	v_mul_f32_e32 v2, v2, v62
	global_load_dword v62, v89, s[4:5] offset:128
	v_mul_f32_e32 v52, v52, v72
	v_mul_f32_e32 v35, v35, v72
	s_waitcnt vmcnt(0)
	v_mul_f32_e32 v36, v36, v62
	v_mul_f32_e32 v38, v38, v62
	v_mul_f32_e32 v39, v39, v62
	v_mul_f32_e32 v40, v40, v62
	v_mul_f32_e32 v41, v41, v62
	v_mul_f32_e32 v42, v42, v62
	v_mul_f32_e32 v43, v43, v62
	v_mul_f32_e32 v44, v44, v62
	v_mul_f32_e32 v45, v45, v62
	v_mul_f32_e32 v46, v46, v62
	v_mul_f32_e32 v47, v47, v62
	v_mul_f32_e32 v48, v48, v62
	v_mul_f32_e32 v49, v49, v62
	v_mul_f32_e32 v50, v50, v62
	v_mul_f32_e32 v51, v62, v51
	v_mul_f32_e32 v52, v62, v52
	global_load_dword v62, v89, s[4:5] offset:256
	s_waitcnt vmcnt(0)
	v_mul_f32_e32 v19, v19, v62
	v_mul_f32_e32 v20, v20, v62
	v_mul_f32_e32 v21, v21, v62
	v_mul_f32_e32 v22, v22, v62
	v_mul_f32_e32 v23, v23, v62
	v_mul_f32_e32 v24, v24, v62
	v_mul_f32_e32 v25, v25, v62
	v_mul_f32_e32 v27, v27, v62
	v_mul_f32_e32 v28, v28, v62
	v_mul_f32_e32 v29, v29, v62
	v_mul_f32_e32 v30, v30, v62
	v_mul_f32_e32 v31, v31, v62
	v_mul_f32_e32 v32, v32, v62
	v_mul_f32_e32 v33, v33, v62
	v_mul_f32_e32 v34, v34, v62
	v_mul_f32_e32 v35, v62, v35
	global_load_dword v62, v89, s[4:5] offset:384
	s_lshl_b32 s4, s72, 1
	s_add_u32 s0, s0, s4
	s_addc_u32 s1, s1, 0
	s_add_i32 s78, s78, s34
	s_add_i32 s76, s76, s34
	s_cmpk_lt_i32 s78, 0x400
	s_waitcnt vmcnt(0)
	v_mul_f32_e32 v18, v0, v62
	v_mul_f32_e32 v0, v3, v26
	v_mul_f32_e32 v26, v0, v62
	v_mul_f32_e32 v0, v4, v37
	v_mul_f32_e32 v37, v0, v62
	v_mul_f32_e32 v0, v5, v53
	v_mul_f32_e32 v53, v0, v62
	v_mul_f32_e32 v0, v6, v70
	v_mul_f32_e32 v89, v0, v62
	v_mul_f32_e32 v0, v7, v71
	v_mul_f32_e32 v90, v0, v62
	v_mul_f32_e32 v0, v8, v76
	v_mul_f32_e32 v76, v0, v62
	v_mul_f32_e32 v0, v9, v82
	v_mul_f32_e32 v82, v0, v62
	v_mul_f32_e32 v0, v10, v84
	v_mul_f32_e32 v84, v0, v62
	v_mul_f32_e32 v0, v11, v86
	v_mul_f32_e32 v86, v0, v62
	v_mul_f32_e32 v0, v12, v87
	v_mul_f32_e32 v87, v0, v62
	v_mul_f32_e32 v0, v13, v85
	v_mul_f32_e32 v85, v0, v62
	v_mul_f32_e32 v0, v14, v83
	v_mul_f32_e32 v83, v0, v62
	v_mul_f32_e32 v0, v15, v81
	v_mul_f32_e32 v81, v0, v62
	v_mul_f32_e32 v0, v16, v74
	v_mul_f32_e32 v91, v0, v62
	v_mul_f32_e32 v0, v17, v72
	v_mul_f32_e32 v92, v62, v0
	v_mov_b32_e32 v0, v228
	s_nop 0
	v_ashrrev_i32_e32 v4, 1, v0
	v_and_b32_e32 v3, 31, v0
	v_and_b32_e32 v4, 0xffffffe0, v4
	v_lshrrev_b32_e32 v0, 3, v0
	v_and_or_b32 v4, v0, 4, v4
	v_lshlrev_b32_e32 v0, 1, v3
	v_ashrrev_i32_e32 v5, 31, v4
	v_or_b32_e32 v10, 1, v4
	v_lshl_add_u64 v[6:7], s[0:1], 0, v[0:1]
	v_lshlrev_b64 v[8:9], 11, v[4:5]
	v_ashrrev_i32_e32 v11, 31, v10
	v_or_b32_e32 v12, 2, v4
	v_cvt_pk_bf16_f32 v0, v88, s0
	v_lshl_add_u64 v[8:9], v[6:7], 0, v[8:9]
	v_lshlrev_b64 v[10:11], 11, v[10:11]
	v_ashrrev_i32_e32 v13, 31, v12
	v_or_b32_e32 v14, 3, v4
	global_store_short v[8:9], v0, off
	v_cvt_pk_bf16_f32 v0, v80, s0
	v_lshl_add_u64 v[10:11], v[6:7], 0, v[10:11]
	v_lshlrev_b64 v[12:13], 11, v[12:13]
	v_ashrrev_i32_e32 v15, 31, v14
	v_or_b32_e32 v16, 8, v4
	global_store_short v[10:11], v0, off
	v_cvt_pk_bf16_f32 v0, v79, s0
	v_lshl_add_u64 v[12:13], v[6:7], 0, v[12:13]
	v_lshlrev_b64 v[14:15], 11, v[14:15]
	v_ashrrev_i32_e32 v17, 31, v16
	v_or_b32_e32 v62, 9, v4
	global_store_short v[12:13], v0, off
	v_cvt_pk_bf16_f32 v0, v78, s0
	v_lshl_add_u64 v[14:15], v[6:7], 0, v[14:15]
	v_lshlrev_b64 v[16:17], 11, v[16:17]
	v_ashrrev_i32_e32 v63, 31, v62
	v_or_b32_e32 v64, 10, v4
; __device__ __forceinline__ unsigned cvtpk(float lo, float hi) { f32x2_t v = {lo, hi}; bf16x2_t b = __builtin_convertvector(v, bf16x2_t); return __builtin_bit_cast(unsigned, b); }
; __device__ __forceinline__ int crowc(int r) { return (r & 3) + 8 * (r >> 2); }
; template <int DV>
; __device__ __forceinline__ void attn_store(const f32x16 (&o)[DV / 32], bf16_t* Op, int ldo) {
;     int tid_o = threadIdx.x; asm volatile("" : "+v"(tid_o));
;     const int lane = tid_o & 63, wid = tid_o >> 6, r32 = lane & 31, hi = lane >> 5;
; #pragma unroll
;     for (int dt = 0; dt < DV / 32; ++dt)
; #pragma unroll
;         for (int r = 0; r < 16; ++r) { const int row = 32 * wid + crowc(r) + 4 * hi; Op[(size_t)row * ldo + dt * 32 + r32] = (bf16_t)(cvtpk(o[dt][r], 0.f) & 0xffffu); }
; }
	global_store_short v[14:15], v0, off
	v_cvt_pk_bf16_f32 v0, v77, s0
	v_lshl_add_u64 v[16:17], v[6:7], 0, v[16:17]
	v_lshlrev_b64 v[62:63], 11, v[62:63]
	v_ashrrev_i32_e32 v65, 31, v64
	v_or_b32_e32 v66, 11, v4
	global_store_short v[16:17], v0, off
	v_cvt_pk_bf16_f32 v0, v75, s0
	v_lshl_add_u64 v[62:63], v[6:7], 0, v[62:63]
	v_lshlrev_b64 v[64:65], 11, v[64:65]
	v_ashrrev_i32_e32 v67, 31, v66
	global_store_short v[62:63], v0, off
	v_cvt_pk_bf16_f32 v0, v73, s0
	v_lshl_add_u64 v[64:65], v[6:7], 0, v[64:65]
	v_lshlrev_b64 v[66:67], 11, v[66:67]
	v_or_b32_e32 v68, 16, v4
	global_store_short v[64:65], v0, off
	v_cvt_pk_bf16_f32 v0, v61, s0
	v_lshl_add_u64 v[66:67], v[6:7], 0, v[66:67]
	v_ashrrev_i32_e32 v69, 31, v68
	global_store_short v[66:67], v0, off
	v_cvt_pk_bf16_f32 v0, v60, s0
	v_lshlrev_b64 v[60:61], 11, v[68:69]
	v_or_b32_e32 v68, 17, v4
	v_ashrrev_i32_e32 v69, 31, v68
	v_lshl_add_u64 v[60:61], v[6:7], 0, v[60:61]
	v_lshlrev_b64 v[68:69], 11, v[68:69]
	v_or_b32_e32 v70, 18, v4
	global_store_short v[60:61], v0, off
	v_cvt_pk_bf16_f32 v0, v59, s0
	v_lshl_add_u64 v[68:69], v[6:7], 0, v[68:69]
	v_ashrrev_i32_e32 v71, 31, v70
	global_store_short v[68:69], v0, off
	v_cvt_pk_bf16_f32 v0, v58, s0
	v_lshlrev_b64 v[58:59], 11, v[70:71]
	v_or_b32_e32 v70, 19, v4
	v_ashrrev_i32_e32 v71, 31, v70
	v_lshl_add_u64 v[58:59], v[6:7], 0, v[58:59]
	v_lshlrev_b64 v[70:71], 11, v[70:71]
	v_or_b32_e32 v72, 24, v4
	global_store_short v[58:59], v0, off
	v_cvt_pk_bf16_f32 v0, v57, s0
	v_lshl_add_u64 v[70:71], v[6:7], 0, v[70:71]
	v_ashrrev_i32_e32 v73, 31, v72
	global_store_short v[70:71], v0, off
	v_cvt_pk_bf16_f32 v0, v56, s0
	v_lshlrev_b64 v[56:57], 11, v[72:73]
	v_or_b32_e32 v72, 25, v4
	v_ashrrev_i32_e32 v73, 31, v72
	v_lshl_add_u64 v[56:57], v[6:7], 0, v[56:57]
	v_lshlrev_b64 v[72:73], 11, v[72:73]
	v_or_b32_e32 v74, 26, v4
	global_store_short v[56:57], v0, off
	v_cvt_pk_bf16_f32 v0, v55, s0
	v_lshl_add_u64 v[72:73], v[6:7], 0, v[72:73]
	v_ashrrev_i32_e32 v75, 31, v74
	global_store_short v[72:73], v0, off
	v_cvt_pk_bf16_f32 v0, v54, s0
	v_lshlrev_b64 v[54:55], 11, v[74:75]
	v_or_b32_e32 v4, 27, v4
	v_lshl_add_u64 v[54:55], v[6:7], 0, v[54:55]
	v_ashrrev_i32_e32 v5, 31, v4
	global_store_short v[54:55], v0, off
	v_cvt_pk_bf16_f32 v0, v2, s0
	v_lshlrev_b64 v[2:3], 11, v[4:5]
	v_lshl_add_u64 v[2:3], v[6:7], 0, v[2:3]
	global_store_short v[2:3], v0, off
	v_cvt_pk_bf16_f32 v0, v36, s0
	global_store_short v[8:9], v0, off offset:64
	v_cvt_pk_bf16_f32 v0, v38, s0
	global_store_short v[10:11], v0, off offset:64
	v_cvt_pk_bf16_f32 v0, v39, s0
	global_store_short v[12:13], v0, off offset:64
	v_cvt_pk_bf16_f32 v0, v40, s0
	global_store_short v[14:15], v0, off offset:64
	v_cvt_pk_bf16_f32 v0, v41, s0
	global_store_short v[16:17], v0, off offset:64
	v_cvt_pk_bf16_f32 v0, v42, s0
	global_store_short v[62:63], v0, off offset:64
	v_cvt_pk_bf16_f32 v0, v43, s0
	global_store_short v[64:65], v0, off offset:64
	v_cvt_pk_bf16_f32 v0, v44, s0
	global_store_short v[66:67], v0, off offset:64
	v_cvt_pk_bf16_f32 v0, v45, s0
	global_store_short v[60:61], v0, off offset:64
	v_cvt_pk_bf16_f32 v0, v46, s0
	global_store_short v[68:69], v0, off offset:64
	v_cvt_pk_bf16_f32 v0, v47, s0
	global_store_short v[58:59], v0, off offset:64
	v_cvt_pk_bf16_f32 v0, v48, s0
	global_store_short v[70:71], v0, off offset:64
	v_cvt_pk_bf16_f32 v0, v49, s0
	global_store_short v[56:57], v0, off offset:64
	v_cvt_pk_bf16_f32 v0, v50, s0
	global_store_short v[72:73], v0, off offset:64
	v_cvt_pk_bf16_f32 v0, v51, s0
	global_store_short v[54:55], v0, off offset:64
	v_cvt_pk_bf16_f32 v0, v52, s0
	global_store_short v[2:3], v0, off offset:64
	v_cvt_pk_bf16_f32 v0, v19, s0
	global_store_short v[8:9], v0, off offset:128
	v_cvt_pk_bf16_f32 v0, v20, s0
	global_store_short v[10:11], v0, off offset:128
	v_cvt_pk_bf16_f32 v0, v21, s0
	global_store_short v[12:13], v0, off offset:128
	v_cvt_pk_bf16_f32 v0, v22, s0
	global_store_short v[14:15], v0, off offset:128
	v_cvt_pk_bf16_f32 v0, v23, s0
	global_store_short v[16:17], v0, off offset:128
	v_cvt_pk_bf16_f32 v0, v24, s0
	global_store_short v[62:63], v0, off offset:128
	v_cvt_pk_bf16_f32 v0, v25, s0
	global_store_short v[64:65], v0, off offset:128
	v_cvt_pk_bf16_f32 v0, v27, s0
	global_store_short v[66:67], v0, off offset:128
	v_cvt_pk_bf16_f32 v0, v28, s0
	global_store_short v[60:61], v0, off offset:128
	v_cvt_pk_bf16_f32 v0, v29, s0
	global_store_short v[68:69], v0, off offset:128
	v_cvt_pk_bf16_f32 v0, v30, s0
	global_store_short v[58:59], v0, off offset:128
	v_cvt_pk_bf16_f32 v0, v31, s0
	global_store_short v[70:71], v0, off offset:128
	v_cvt_pk_bf16_f32 v0, v32, s0
	global_store_short v[56:57], v0, off offset:128
	v_cvt_pk_bf16_f32 v0, v33, s0
	global_store_short v[72:73], v0, off offset:128
	v_cvt_pk_bf16_f32 v0, v34, s0
	global_store_short v[54:55], v0, off offset:128
	v_cvt_pk_bf16_f32 v0, v35, s0
	global_store_short v[2:3], v0, off offset:128
	v_cvt_pk_bf16_f32 v0, v18, s0
	global_store_short v[8:9], v0, off offset:192
	v_cvt_pk_bf16_f32 v0, v26, s0
	global_store_short v[10:11], v0, off offset:192
	v_cvt_pk_bf16_f32 v0, v37, s0
	global_store_short v[12:13], v0, off offset:192
	v_cvt_pk_bf16_f32 v0, v53, s0
	global_store_short v[14:15], v0, off offset:192
	v_cvt_pk_bf16_f32 v0, v89, s0
	global_store_short v[16:17], v0, off offset:192
	v_cvt_pk_bf16_f32 v0, v90, s0
	global_store_short v[62:63], v0, off offset:192
	v_cvt_pk_bf16_f32 v0, v76, s0
	global_store_short v[64:65], v0, off offset:192
	v_cvt_pk_bf16_f32 v0, v82, s0
	global_store_short v[66:67], v0, off offset:192
	v_cvt_pk_bf16_f32 v0, v84, s0
	global_store_short v[60:61], v0, off offset:192
	v_cvt_pk_bf16_f32 v0, v86, s0
	global_store_short v[68:69], v0, off offset:192
	v_cvt_pk_bf16_f32 v0, v87, s0
	global_store_short v[58:59], v0, off offset:192
	v_cvt_pk_bf16_f32 v0, v85, s0
	global_store_short v[70:71], v0, off offset:192
	v_cvt_pk_bf16_f32 v0, v83, s0
	global_store_short v[56:57], v0, off offset:192
	v_cvt_pk_bf16_f32 v0, v81, s0
	global_store_short v[72:73], v0, off offset:192
	v_cvt_pk_bf16_f32 v0, v91, s0
	global_store_short v[54:55], v0, off offset:192
	v_cvt_pk_bf16_f32 v0, v92, s0
	global_store_short v[2:3], v0, off offset:192
	s_cbranch_scc0 .LBB0_863

; __device__ __forceinline__ unsigned cvt_pk_bf16(float lo, float hi) { unsigned r; asm volatile("v_cvt_pk_bf16_f32 %0, %1, %2" : "=v"(r) : "v"(lo), "v"(hi)); return r; }
;     __device__ __forceinline__ void operator()(f32x4 (&acc)[2][2][4][2], const Unit& u, int wr, int wc, int fr, int fq) const {
;     ...
;             for (int m = 0; m < 4; ++m) { const size_t off = (size_t)(u.pm * BM + ai * HALF + wr * 64 + m * 16 + fr) * ldc + col0;
; #pragma unroll
;                 for (int bj = 0; bj < 2; ++bj)
; #pragma unroll
;                     for (int n = 0; n < 2; ++n) old[m][bj][n] = *(const unsigned long long*)(xb + off + bj * HALF + n * 16); }
; #pragma unroll
;             for (int m = 0; m < 4; ++m) { const int row = u.pm * BM + ai * HALF + wr * 64 + m * 16 + fr; const size_t off = (size_t)row * ldc + col0; float sq = 0.f;
; #pragma unroll
;                 for (int bj = 0; bj < 2; ++bj)
; #pragma unroll
;                     for (int n = 0; n < 2; ++n) { const unsigned long long b = old[m][bj][n];
;                         const unsigned blo = (unsigned)b, bhi = (unsigned)(b >> 32);
;                         f32x4 v; v[0] = __builtin_bit_cast(float, blo << 16); v[1] = __builtin_bit_cast(float, blo & 0xffff0000u); v[2] = __builtin_bit_cast(float, bhi << 16); v[3] = __builtin_bit_cast(float, bhi & 0xffff0000u);
;                         v = v + acc[ai][bj][m][n];
;                         sq += (v[0] * v[0] + v[1] * v[1]) + (v[2] * v[2] + v[3] * v[3]);
;                         *(unsigned long long*)(xb + off + bj * HALF + n * 16) = (unsigned long long)cvt_pk_bf16(v[0], v[1]) | ((unsigned long long)cvt_pk_bf16(v[2], v[3]) << 32); }
;                 sq += __shfl_xor(sq, 16); sq += __shfl_xor(sq, 32);
;                 if (fq == 0) ssp[(size_t)row * 16 + 4 * u.pn + wc] = sq; }
.LBB0_1039:
	v_lshl_or_b32 v136, s12, 8, v174
	v_lshl_add_u32 v140, s13, 8, v172
	v_ashrrev_i32_e32 v137, 31, v136
	v_lshlrev_b64 v[176:177], 1, v[136:137]
	v_ashrrev_i32_e32 v141, 31, v140
	v_lshl_add_u64 v[138:139], s[42:43], 0, v[176:177]
	v_lshlrev_b64 v[178:179], 11, v[140:141]
	v_lshl_add_u64 v[142:143], v[138:139], 0, v[178:179]
	global_load_dwordx2 v[180:181], v[142:143], off
	global_load_dwordx2 v[182:183], v[142:143], off offset:32
	global_load_dwordx2 v[184:185], v[142:143], off offset:256
	global_load_dwordx2 v[188:189], v[142:143], off offset:288
	v_or_b32_e32 v160, 16, v140
	v_ashrrev_i32_e32 v161, 31, v160
	v_lshlrev_b64 v[142:143], 11, v[160:161]
	v_or_b32_e32 v146, 32, v140
	v_lshl_add_u64 v[142:143], v[138:139], 0, v[142:143]
	v_ashrrev_i32_e32 v147, 31, v146
	global_load_dwordx2 v[170:171], v[142:143], off
	global_load_dwordx2 v[168:169], v[142:143], off offset:32
	global_load_dwordx2 v[166:167], v[142:143], off offset:256
	global_load_dwordx2 v[164:165], v[142:143], off offset:288
	v_lshlrev_b64 v[142:143], 11, v[146:147]
	v_lshl_add_u64 v[142:143], v[138:139], 0, v[142:143]
	global_load_dwordx2 v[162:163], v[142:143], off
	global_load_dwordx2 v[158:159], v[142:143], off offset:32
	global_load_dwordx2 v[154:155], v[142:143], off offset:256
	global_load_dwordx2 v[150:151], v[142:143], off offset:288
	v_or_b32_e32 v142, 48, v140
	v_ashrrev_i32_e32 v143, 31, v142
	v_lshlrev_b64 v[144:145], 11, v[142:143]
	v_lshl_add_u64 v[144:145], v[138:139], 0, v[144:145]
	global_load_dwordx2 v[156:157], v[144:145], off
	global_load_dwordx2 v[152:153], v[144:145], off offset:32
	global_load_dwordx2 v[148:149], v[144:145], off offset:256
	s_nop 0
	global_load_dwordx2 v[144:145], v[144:145], off offset:288
	s_lshl_b32 s78, s12, 2
	s_ashr_i32 s79, s78, 31
	s_waitcnt vmcnt(0)
	v_lshlrev_b32_e32 v190, 16, v180
	v_and_b32_e32 v191, 0xffff0000, v180
	v_lshlrev_b32_e32 v180, 16, v181
	v_and_b32_e32 v181, 0xffff0000, v181
	v_pk_add_f32 v[128:129], v[128:129], v[180:181]
	v_pk_add_f32 v[126:127], v[126:127], v[190:191]
	v_mul_f32_e32 v181, v129, v129
	v_mul_f32_e32 v180, v127, v127
	v_fmac_f32_e32 v180, v126, v126
	v_fmac_f32_e32 v181, v128, v128
	v_cvt_pk_bf16_f32 v126, v126, v127
	v_cvt_pk_bf16_f32 v127, v128, v129
	v_lshl_add_u64 v[128:129], s[42:43], 0, v[178:179]
	v_lshl_add_u64 v[128:129], v[128:129], 0, v[176:177]
	global_store_dwordx2 v[128:129], v[126:127], off
	v_lshlrev_b32_e32 v126, 16, v182
	v_and_b32_e32 v127, 0xffff0000, v182
	v_pk_add_f32 v[122:123], v[122:123], v[126:127]
	v_lshlrev_b32_e32 v176, 16, v183
	v_and_b32_e32 v177, 0xffff0000, v183
	v_mul_f32_e32 v126, v123, v123
	v_pk_add_f32 v[124:125], v[124:125], v[176:177]
	v_fmac_f32_e32 v126, v122, v122
	v_cvt_pk_bf16_f32 v122, v122, v123
	v_cvt_pk_bf16_f32 v123, v124, v125
	v_mul_f32_e32 v127, v125, v125
	global_store_dwordx2 v[128:129], v[122:123], off offset:32
	v_lshlrev_b32_e32 v122, 16, v184
	v_and_b32_e32 v123, 0xffff0000, v184
	v_fmac_f32_e32 v127, v124, v124
	v_lshlrev_b32_e32 v124, 16, v185
	v_and_b32_e32 v125, 0xffff0000, v185
	v_pk_add_f32 v[118:119], v[118:119], v[122:123]
	v_pk_add_f32 v[120:121], v[120:121], v[124:125]
	v_mul_f32_e32 v122, v119, v119
	v_fmac_f32_e32 v122, v118, v118
	v_mul_f32_e32 v123, v121, v121
	v_cvt_pk_bf16_f32 v118, v118, v119
	v_cvt_pk_bf16_f32 v119, v120, v121
	v_fmac_f32_e32 v123, v120, v120
	global_store_dwordx2 v[128:129], v[118:119], off offset:256
	v_lshlrev_b32_e32 v118, 16, v188
	v_and_b32_e32 v119, 0xffff0000, v188
	v_lshlrev_b32_e32 v120, 16, v189
	v_and_b32_e32 v121, 0xffff0000, v189
	v_pk_add_f32 v[116:117], v[116:117], v[120:121]
	v_pk_add_f32 v[118:119], v[114:115], v[118:119]
	v_add_f32_e32 v180, v180, v181
	v_add_f32_e32 v126, v126, v127
	v_mul_f32_e32 v114, v119, v119
	v_mul_f32_e32 v115, v117, v117
	v_add_f32_e32 v126, v180, v126
	v_add_f32_e32 v122, v122, v123
	v_fmac_f32_e32 v114, v118, v118
	v_fmac_f32_e32 v115, v116, v116
	v_add_f32_e32 v122, v126, v122
	v_add_f32_e32 v114, v114, v115
	v_cvt_pk_bf16_f32 v118, v118, v119
	v_cvt_pk_bf16_f32 v119, v116, v117
	v_and_b32_e32 v116, 64, v229
	v_add_f32_e32 v115, v122, v114
	v_xor_b32_e32 v114, 16, v229
	v_add_u32_e32 v117, 64, v116
	v_cmp_lt_i32_e32 vcc, v114, v117
	global_store_dwordx2 v[128:129], v[118:119], off offset:288
	s_nop 0
	v_cndmask_b32_e32 v114, v229, v114, vcc
	v_lshlrev_b32_e32 v114, 2, v114
	v_mov_b32_e32 v116, v115
	s_nop 1
	v_permlane16_swap_b32_e32 v116, v115
	s_waitcnt lgkmcnt(0)
	v_add_f32_e32 v116, v115, v116
	v_xor_b32_e32 v115, 32, v229
	v_cmp_lt_i32_e32 vcc, v115, v117
	s_nop 1
	v_cndmask_b32_e32 v115, v229, v115, vcc
	v_lshlrev_b32_e32 v115, 2, v115
	ds_bpermute_b32 v117, v115, v116
	s_and_saveexec_b64 s[80:81], s[6:7]
	s_cbranch_execz .LBB0_1041
	v_readlane_b32 s12, v253, 40
	v_lshlrev_b64 v[118:119], 6, v[140:141]
	v_readlane_b32 s13, v253, 41
	s_lshl_b32 s64, s90, 2
	s_waitcnt lgkmcnt(0)
	v_add_f32_e32 v116, v116, v117
	v_lshl_add_u64 v[118:119], s[12:13], 0, v[118:119]
	v_lshl_add_u64 v[118:119], s[78:79], 2, v[118:119]
	v_lshl_add_u64 v[118:119], v[118:119], 0, s[64:65]
	global_store_dword v[118:119], v116, off
; __device__ __forceinline__ unsigned cvt_pk_bf16(float lo, float hi) { unsigned r; asm volatile("v_cvt_pk_bf16_f32 %0, %1, %2" : "=v"(r) : "v"(lo), "v"(hi)); return r; }
;     __device__ __forceinline__ void operator()(f32x4 (&acc)[2][2][4][2], const Unit& u, int wr, int wc, int fr, int fq) const {
;     ...
;             for (int m = 0; m < 4; ++m) { const size_t off = (size_t)(u.pm * BM + ai * HALF + wr * 64 + m * 16 + fr) * ldc + col0;
; #pragma unroll
;                 for (int bj = 0; bj < 2; ++bj)
; #pragma unroll
;                     for (int n = 0; n < 2; ++n) old[m][bj][n] = *(const unsigned long long*)(xb + off + bj * HALF + n * 16); }
; #pragma unroll
;             for (int m = 0; m < 4; ++m) { const int row = u.pm * BM + ai * HALF + wr * 64 + m * 16 + fr; const size_t off = (size_t)row * ldc + col0; float sq = 0.f;
; #pragma unroll
;                 for (int bj = 0; bj < 2; ++bj)
; #pragma unroll
;                     for (int n = 0; n < 2; ++n) { const unsigned long long b = old[m][bj][n];
;                         const unsigned blo = (unsigned)b, bhi = (unsigned)(b >> 32);
;                         f32x4 v; v[0] = __builtin_bit_cast(float, blo << 16); v[1] = __builtin_bit_cast(float, blo & 0xffff0000u); v[2] = __builtin_bit_cast(float, bhi << 16); v[3] = __builtin_bit_cast(float, bhi & 0xffff0000u);
;                         v = v + acc[ai][bj][m][n];
;                         sq += (v[0] * v[0] + v[1] * v[1]) + (v[2] * v[2] + v[3] * v[3]);
;                         *(unsigned long long*)(xb + off + bj * HALF + n * 16) = (unsigned long long)cvt_pk_bf16(v[0], v[1]) | ((unsigned long long)cvt_pk_bf16(v[2], v[3]) << 32); }
;                 sq += __shfl_xor(sq, 16); sq += __shfl_xor(sq, 32);
;                 if (fq == 0) ssp[(size_t)row * 16 + 4 * u.pn + wc] = sq; }
.LBB0_1041:
	s_or_b64 exec, exec, s[80:81]
	v_lshlrev_b32_e32 v118, 16, v170
	v_and_b32_e32 v119, 0xffff0000, v170
	v_lshlrev_b32_e32 v120, 16, v171
	v_and_b32_e32 v121, 0xffff0000, v171
	v_pk_add_f32 v[112:113], v[112:113], v[120:121]
	v_pk_add_f32 v[110:111], v[110:111], v[118:119]
	s_waitcnt lgkmcnt(0)
	v_lshlrev_b64 v[116:117], 10, v[160:161]
	v_mul_f32_e32 v118, v111, v111
	v_mul_f32_e32 v119, v113, v113
	v_fmac_f32_e32 v118, v110, v110
	v_fmac_f32_e32 v119, v112, v112
	v_cvt_pk_bf16_f32 v110, v110, v111
	v_cvt_pk_bf16_f32 v111, v112, v113
	v_lshl_add_u64 v[112:113], v[116:117], 1, s[42:43]
	v_lshl_add_u64 v[112:113], v[136:137], 1, v[112:113]
	global_store_dwordx2 v[112:113], v[110:111], off
	v_lshlrev_b32_e32 v110, 16, v168
	v_and_b32_e32 v111, 0xffff0000, v168
	v_lshlrev_b32_e32 v116, 16, v169
	v_and_b32_e32 v117, 0xffff0000, v169
	v_pk_add_f32 v[108:109], v[108:109], v[116:117]
	v_pk_add_f32 v[106:107], v[106:107], v[110:111]
	v_mul_f32_e32 v111, v109, v109
	v_mul_f32_e32 v110, v107, v107
	v_fmac_f32_e32 v110, v106, v106
	v_fmac_f32_e32 v111, v108, v108
	v_add_f32_e32 v118, v118, v119
	v_add_f32_e32 v110, v110, v111
	v_add_f32_e32 v118, v118, v110
	v_lshlrev_b32_e32 v110, 16, v166
	v_and_b32_e32 v111, 0xffff0000, v166
	v_lshlrev_b32_e32 v116, 16, v167
	v_and_b32_e32 v117, 0xffff0000, v167
	v_pk_add_f32 v[104:105], v[104:105], v[116:117]
	v_pk_add_f32 v[102:103], v[102:103], v[110:111]
	v_cvt_pk_bf16_f32 v106, v106, v107
	v_mul_f32_e32 v110, v105, v105
	v_mul_f32_e32 v107, v103, v103
	v_fmac_f32_e32 v107, v102, v102
	v_fmac_f32_e32 v110, v104, v104
	v_add_f32_e32 v107, v107, v110
	v_lshlrev_b32_e32 v110, 16, v164
	v_and_b32_e32 v111, 0xffff0000, v164
	v_lshlrev_b32_e32 v116, 16, v165
	v_and_b32_e32 v117, 0xffff0000, v165
	v_pk_add_f32 v[100:101], v[100:101], v[116:117]
	v_pk_add_f32 v[110:111], v[98:99], v[110:111]
	v_mul_f32_e32 v99, v101, v101
	v_mul_f32_e32 v98, v111, v111
	v_fmac_f32_e32 v98, v110, v110
	v_fmac_f32_e32 v99, v100, v100
	v_add_f32_e32 v107, v118, v107
	v_add_f32_e32 v98, v98, v99
	v_add_f32_e32 v98, v107, v98
	v_mov_b32_e32 v99, v98
	s_nop 1
	v_permlane16_swap_b32_e32 v99, v98
	v_cvt_pk_bf16_f32 v107, v108, v109
	global_store_dwordx2 v[112:113], v[106:107], off offset:32
	v_cvt_pk_bf16_f32 v102, v102, v103
	v_cvt_pk_bf16_f32 v103, v104, v105
	s_waitcnt lgkmcnt(0)
	v_add_f32_e32 v98, v98, v99
	ds_bpermute_b32 v99, v115, v98
	global_store_dwordx2 v[112:113], v[102:103], off offset:256
	v_cvt_pk_bf16_f32 v102, v110, v111
	v_cvt_pk_bf16_f32 v103, v100, v101
	global_store_dwordx2 v[112:113], v[102:103], off offset:288
	s_and_saveexec_b64 s[80:81], s[6:7]
	s_cbranch_execz .LBB0_1043
	v_readlane_b32 s12, v253, 40
	v_lshlrev_b64 v[100:101], 6, v[160:161]
	v_readlane_b32 s13, v253, 41
	s_lshl_b32 s64, s90, 2
	s_waitcnt lgkmcnt(0)
	v_add_f32_e32 v98, v98, v99
	v_lshl_add_u64 v[100:101], s[12:13], 0, v[100:101]
	v_lshl_add_u64 v[100:101], s[78:79], 2, v[100:101]
	v_lshl_add_u64 v[100:101], v[100:101], 0, s[64:65]
	global_store_dword v[100:101], v98, off
; __device__ __forceinline__ unsigned cvt_pk_bf16(float lo, float hi) { unsigned r; asm volatile("v_cvt_pk_bf16_f32 %0, %1, %2" : "=v"(r) : "v"(lo), "v"(hi)); return r; }
;     __device__ __forceinline__ void operator()(f32x4 (&acc)[2][2][4][2], const Unit& u, int wr, int wc, int fr, int fq) const {
;     ...
;             for (int m = 0; m < 4; ++m) { const size_t off = (size_t)(u.pm * BM + ai * HALF + wr * 64 + m * 16 + fr) * ldc + col0;
; #pragma unroll
;                 for (int bj = 0; bj < 2; ++bj)
; #pragma unroll
;                     for (int n = 0; n < 2; ++n) old[m][bj][n] = *(const unsigned long long*)(xb + off + bj * HALF + n * 16); }
; #pragma unroll
;             for (int m = 0; m < 4; ++m) { const int row = u.pm * BM + ai * HALF + wr * 64 + m * 16 + fr; const size_t off = (size_t)row * ldc + col0; float sq = 0.f;
; #pragma unroll
;                 for (int bj = 0; bj < 2; ++bj)
; #pragma unroll
;                     for (int n = 0; n < 2; ++n) { const unsigned long long b = old[m][bj][n];
;                         const unsigned blo = (unsigned)b, bhi = (unsigned)(b >> 32);
;                         f32x4 v; v[0] = __builtin_bit_cast(float, blo << 16); v[1] = __builtin_bit_cast(float, blo & 0xffff0000u); v[2] = __builtin_bit_cast(float, bhi << 16); v[3] = __builtin_bit_cast(float, bhi & 0xffff0000u);
;                         v = v + acc[ai][bj][m][n];
;                         sq += (v[0] * v[0] + v[1] * v[1]) + (v[2] * v[2] + v[3] * v[3]);
;                         *(unsigned long long*)(xb + off + bj * HALF + n * 16) = (unsigned long long)cvt_pk_bf16(v[0], v[1]) | ((unsigned long long)cvt_pk_bf16(v[2], v[3]) << 32); }
;                 sq += __shfl_xor(sq, 16); sq += __shfl_xor(sq, 32);
;                 if (fq == 0) ssp[(size_t)row * 16 + 4 * u.pn + wc] = sq; }
.LBB0_1043:
	s_or_b64 exec, exec, s[80:81]
	v_lshlrev_b32_e32 v100, 16, v162
	v_and_b32_e32 v101, 0xffff0000, v162
	v_lshlrev_b32_e32 v102, 16, v163
	v_and_b32_e32 v103, 0xffff0000, v163
	v_pk_add_f32 v[96:97], v[96:97], v[102:103]
	v_pk_add_f32 v[94:95], v[94:95], v[100:101]
	s_waitcnt lgkmcnt(0)
	v_lshlrev_b64 v[98:99], 10, v[146:147]
	v_mul_f32_e32 v100, v95, v95
	v_mul_f32_e32 v101, v97, v97
	v_fmac_f32_e32 v100, v94, v94
	v_fmac_f32_e32 v101, v96, v96
	v_cvt_pk_bf16_f32 v94, v94, v95
	v_cvt_pk_bf16_f32 v95, v96, v97
	v_lshl_add_u64 v[96:97], v[98:99], 1, s[42:43]
	v_lshl_add_u64 v[96:97], v[136:137], 1, v[96:97]
	global_store_dwordx2 v[96:97], v[94:95], off
	v_lshlrev_b32_e32 v94, 16, v158
	v_and_b32_e32 v95, 0xffff0000, v158
	v_lshlrev_b32_e32 v98, 16, v159
	v_and_b32_e32 v99, 0xffff0000, v159
	v_pk_add_f32 v[92:93], v[92:93], v[98:99]
	v_pk_add_f32 v[90:91], v[90:91], v[94:95]
	v_mul_f32_e32 v95, v93, v93
	v_mul_f32_e32 v94, v91, v91
	v_fmac_f32_e32 v94, v90, v90
	v_fmac_f32_e32 v95, v92, v92
	v_add_f32_e32 v100, v100, v101
	v_add_f32_e32 v94, v94, v95
	v_add_f32_e32 v100, v100, v94
	v_lshlrev_b32_e32 v94, 16, v154
	v_and_b32_e32 v95, 0xffff0000, v154
	v_lshlrev_b32_e32 v98, 16, v155
	v_and_b32_e32 v99, 0xffff0000, v155
	v_pk_add_f32 v[88:89], v[88:89], v[98:99]
	v_pk_add_f32 v[86:87], v[86:87], v[94:95]
	v_cvt_pk_bf16_f32 v90, v90, v91
	v_mul_f32_e32 v94, v89, v89
	v_mul_f32_e32 v91, v87, v87
	v_fmac_f32_e32 v91, v86, v86
	v_fmac_f32_e32 v94, v88, v88
	v_add_f32_e32 v91, v91, v94
	v_lshlrev_b32_e32 v94, 16, v150
	v_and_b32_e32 v95, 0xffff0000, v150
	v_lshlrev_b32_e32 v98, 16, v151
	v_and_b32_e32 v99, 0xffff0000, v151
	v_pk_add_f32 v[84:85], v[84:85], v[98:99]
	v_pk_add_f32 v[94:95], v[82:83], v[94:95]
	v_mul_f32_e32 v83, v85, v85
	v_mul_f32_e32 v82, v95, v95
	v_fmac_f32_e32 v82, v94, v94
	v_fmac_f32_e32 v83, v84, v84
	v_add_f32_e32 v91, v100, v91
	v_add_f32_e32 v82, v82, v83
	v_add_f32_e32 v82, v91, v82
	v_mov_b32_e32 v83, v82
	s_nop 1
	v_permlane16_swap_b32_e32 v83, v82
	v_cvt_pk_bf16_f32 v91, v92, v93
	global_store_dwordx2 v[96:97], v[90:91], off offset:32
	v_cvt_pk_bf16_f32 v86, v86, v87
	v_cvt_pk_bf16_f32 v87, v88, v89
	s_waitcnt lgkmcnt(0)
	v_add_f32_e32 v82, v82, v83
	ds_bpermute_b32 v83, v115, v82
	global_store_dwordx2 v[96:97], v[86:87], off offset:256
	v_cvt_pk_bf16_f32 v86, v94, v95
	v_cvt_pk_bf16_f32 v87, v84, v85
	global_store_dwordx2 v[96:97], v[86:87], off offset:288
	s_and_saveexec_b64 s[80:81], s[6:7]
	v_readlane_b32 s85, v255, 27
	s_cbranch_execz .LBB0_1045
	v_readlane_b32 s12, v253, 40
	v_lshlrev_b64 v[84:85], 6, v[146:147]
	v_readlane_b32 s13, v253, 41
	s_lshl_b32 s64, s90, 2
	s_waitcnt lgkmcnt(0)
	v_add_f32_e32 v82, v82, v83
	v_lshl_add_u64 v[84:85], s[12:13], 0, v[84:85]
	v_lshl_add_u64 v[84:85], s[78:79], 2, v[84:85]
	v_lshl_add_u64 v[84:85], v[84:85], 0, s[64:65]
	global_store_dword v[84:85], v82, off
.LBB0_1045:
	s_or_b64 exec, exec, s[80:81]
	v_lshlrev_b32_e32 v84, 16, v156
	v_and_b32_e32 v85, 0xffff0000, v156
	v_lshlrev_b32_e32 v86, 16, v157
	v_and_b32_e32 v87, 0xffff0000, v157
	v_pk_add_f32 v[80:81], v[80:81], v[86:87]
	v_pk_add_f32 v[78:79], v[78:79], v[84:85]
	s_waitcnt lgkmcnt(0)
	v_lshlrev_b64 v[82:83], 10, v[142:143]
	v_mul_f32_e32 v84, v79, v79
	v_mul_f32_e32 v85, v81, v81
	v_fmac_f32_e32 v84, v78, v78
	v_fmac_f32_e32 v85, v80, v80
	v_cvt_pk_bf16_f32 v78, v78, v79
	v_cvt_pk_bf16_f32 v79, v80, v81
	v_lshl_add_u64 v[80:81], v[82:83], 1, s[42:43]
	v_lshl_add_u64 v[80:81], v[136:137], 1, v[80:81]
	global_store_dwordx2 v[80:81], v[78:79], off
	v_lshlrev_b32_e32 v78, 16, v152
	v_and_b32_e32 v79, 0xffff0000, v152
	v_lshlrev_b32_e32 v82, 16, v153
	v_and_b32_e32 v83, 0xffff0000, v153
	v_pk_add_f32 v[76:77], v[76:77], v[82:83]
	v_pk_add_f32 v[74:75], v[74:75], v[78:79]
	v_mul_f32_e32 v79, v77, v77
	v_mul_f32_e32 v78, v75, v75
	v_fmac_f32_e32 v78, v74, v74
	v_fmac_f32_e32 v79, v76, v76
	v_add_f32_e32 v84, v84, v85
	v_add_f32_e32 v78, v78, v79
	v_add_f32_e32 v84, v84, v78
	v_lshlrev_b32_e32 v78, 16, v148
	v_and_b32_e32 v79, 0xffff0000, v148
	v_lshlrev_b32_e32 v82, 16, v149
	v_and_b32_e32 v83, 0xffff0000, v149
	v_pk_add_f32 v[72:73], v[72:73], v[82:83]
	v_pk_add_f32 v[70:71], v[70:71], v[78:79]
	v_cvt_pk_bf16_f32 v74, v74, v75
	v_mul_f32_e32 v78, v73, v73
	v_mul_f32_e32 v75, v71, v71
	v_fmac_f32_e32 v75, v70, v70
	v_fmac_f32_e32 v78, v72, v72
	v_add_f32_e32 v75, v75, v78
	v_lshlrev_b32_e32 v78, 16, v144
	v_and_b32_e32 v79, 0xffff0000, v144
	v_lshlrev_b32_e32 v82, 16, v145
	v_and_b32_e32 v83, 0xffff0000, v145
	v_pk_add_f32 v[68:69], v[68:69], v[82:83]
	v_pk_add_f32 v[78:79], v[66:67], v[78:79]
	v_mul_f32_e32 v67, v69, v69
	v_mul_f32_e32 v66, v79, v79
	v_fmac_f32_e32 v66, v78, v78
	v_fmac_f32_e32 v67, v68, v68
	v_add_f32_e32 v75, v84, v75
	v_add_f32_e32 v66, v66, v67
	v_add_f32_e32 v66, v75, v66
	v_mov_b32_e32 v67, v66
	s_nop 1
	v_permlane16_swap_b32_e32 v67, v66
	v_cvt_pk_bf16_f32 v75, v76, v77
	global_store_dwordx2 v[80:81], v[74:75], off offset:32
	v_cvt_pk_bf16_f32 v70, v70, v71
	v_cvt_pk_bf16_f32 v71, v72, v73
	s_waitcnt lgkmcnt(0)
	v_add_f32_e32 v66, v66, v67
	ds_bpermute_b32 v67, v115, v66
	global_store_dwordx2 v[80:81], v[70:71], off offset:256
	v_cvt_pk_bf16_f32 v70, v78, v79
	v_cvt_pk_bf16_f32 v71, v68, v69
	global_store_dwordx2 v[80:81], v[70:71], off offset:288
	s_and_saveexec_b64 s[80:81], s[6:7]
	s_cbranch_execz .LBB0_1047
	v_readlane_b32 s12, v253, 40
	v_lshlrev_b64 v[68:69], 6, v[142:143]
	v_readlane_b32 s13, v253, 41
	s_lshl_b32 s64, s90, 2
	s_waitcnt lgkmcnt(0)
	v_add_f32_e32 v66, v66, v67
	v_lshl_add_u64 v[68:69], s[12:13], 0, v[68:69]
	v_lshl_add_u64 v[68:69], s[78:79], 2, v[68:69]
	v_lshl_add_u64 v[68:69], v[68:69], 0, s[64:65]
	global_store_dword v[68:69], v66, off

; __device__ __forceinline__ unsigned cvt_pk_bf16(float lo, float hi) { unsigned r; asm volatile("v_cvt_pk_bf16_f32 %0, %1, %2" : "=v"(r) : "v"(lo), "v"(hi)); return r; }
;     __device__ __forceinline__ void operator()(f32x4 (&acc)[2][2][4][2], const Unit& u, int wr, int wc, int fr, int fq) const {
;     ...
;             for (int m = 0; m < 4; ++m) { const size_t off = (size_t)(u.pm * BM + ai * HALF + wr * 64 + m * 16 + fr) * ldc + col0;
; #pragma unroll
;                 for (int bj = 0; bj < 2; ++bj)
; #pragma unroll
;                     for (int n = 0; n < 2; ++n) old[m][bj][n] = *(const unsigned long long*)(xb + off + bj * HALF + n * 16); }
; #pragma unroll
;             for (int m = 0; m < 4; ++m) { const int row = u.pm * BM + ai * HALF + wr * 64 + m * 16 + fr; const size_t off = (size_t)row * ldc + col0; float sq = 0.f;
; #pragma unroll
;                 for (int bj = 0; bj < 2; ++bj)
; #pragma unroll
;                     for (int n = 0; n < 2; ++n) { const unsigned long long b = old[m][bj][n];
;                         const unsigned blo = (unsigned)b, bhi = (unsigned)(b >> 32);
;                         f32x4 v; v[0] = __builtin_bit_cast(float, blo << 16); v[1] = __builtin_bit_cast(float, blo & 0xffff0000u); v[2] = __builtin_bit_cast(float, bhi << 16); v[3] = __builtin_bit_cast(float, bhi & 0xffff0000u);
;                         v = v + acc[ai][bj][m][n];
;                         sq += (v[0] * v[0] + v[1] * v[1]) + (v[2] * v[2] + v[3] * v[3]);
;                         *(unsigned long long*)(xb + off + bj * HALF + n * 16) = (unsigned long long)cvt_pk_bf16(v[0], v[1]) | ((unsigned long long)cvt_pk_bf16(v[2], v[3]) << 32); }
;                 sq += __shfl_xor(sq, 16); sq += __shfl_xor(sq, 32);
;                 if (fq == 0) ssp[(size_t)row * 16 + 4 * u.pn + wc] = sq; }
.LBB0_1049:
	s_or_b64 exec, exec, s[80:81]
	s_waitcnt vmcnt(15)
	v_lshlrev_b32_e32 v52, 16, v94
	v_and_b32_e32 v53, 0xffff0000, v94
	v_lshlrev_b32_e32 v54, 16, v95
	v_and_b32_e32 v55, 0xffff0000, v95
	v_pk_add_f32 v[48:49], v[48:49], v[54:55]
	v_pk_add_f32 v[46:47], v[46:47], v[52:53]
	s_waitcnt lgkmcnt(0)
	v_lshlrev_b64 v[50:51], 10, v[84:85]
	v_mul_f32_e32 v52, v47, v47
	v_mul_f32_e32 v53, v49, v49
	v_fmac_f32_e32 v52, v46, v46
	v_fmac_f32_e32 v53, v48, v48
	v_cvt_pk_bf16_f32 v46, v46, v47
	v_cvt_pk_bf16_f32 v47, v48, v49
	v_lshl_add_u64 v[48:49], v[50:51], 1, s[42:43]
	v_lshl_add_u64 v[48:49], v[136:137], 1, v[48:49]
	global_store_dwordx2 v[48:49], v[46:47], off
	s_waitcnt vmcnt(15)
	v_lshlrev_b32_e32 v46, 16, v92
	v_and_b32_e32 v47, 0xffff0000, v92
	v_lshlrev_b32_e32 v50, 16, v93
	v_and_b32_e32 v51, 0xffff0000, v93
	v_pk_add_f32 v[44:45], v[44:45], v[50:51]
	v_pk_add_f32 v[42:43], v[42:43], v[46:47]
	v_mul_f32_e32 v47, v45, v45
	v_mul_f32_e32 v46, v43, v43
	v_fmac_f32_e32 v46, v42, v42
	v_fmac_f32_e32 v47, v44, v44
	v_add_f32_e32 v52, v52, v53
	v_add_f32_e32 v46, v46, v47
	v_add_f32_e32 v52, v52, v46
	s_waitcnt vmcnt(14)
	v_lshlrev_b32_e32 v46, 16, v90
	v_and_b32_e32 v47, 0xffff0000, v90
	v_lshlrev_b32_e32 v50, 16, v91
	v_and_b32_e32 v51, 0xffff0000, v91
	v_pk_add_f32 v[40:41], v[40:41], v[50:51]
	v_pk_add_f32 v[38:39], v[38:39], v[46:47]
	v_cvt_pk_bf16_f32 v42, v42, v43
	v_mul_f32_e32 v46, v41, v41
	v_mul_f32_e32 v43, v39, v39
	v_fmac_f32_e32 v43, v38, v38
	v_fmac_f32_e32 v46, v40, v40
	v_add_f32_e32 v43, v43, v46
	s_waitcnt vmcnt(13)
	v_lshlrev_b32_e32 v46, 16, v88
	v_and_b32_e32 v47, 0xffff0000, v88
	v_lshlrev_b32_e32 v50, 16, v89
	v_and_b32_e32 v51, 0xffff0000, v89
	v_pk_add_f32 v[36:37], v[36:37], v[50:51]
	v_pk_add_f32 v[46:47], v[34:35], v[46:47]
	v_mul_f32_e32 v35, v37, v37
	v_mul_f32_e32 v34, v47, v47
	v_fmac_f32_e32 v34, v46, v46
	v_fmac_f32_e32 v35, v36, v36
	v_add_f32_e32 v43, v52, v43
	v_add_f32_e32 v34, v34, v35
	v_add_f32_e32 v34, v43, v34
	v_mov_b32_e32 v35, v34
	s_nop 1
	v_permlane16_swap_b32_e32 v35, v34
	v_cvt_pk_bf16_f32 v43, v44, v45
	global_store_dwordx2 v[48:49], v[42:43], off offset:32
	v_cvt_pk_bf16_f32 v38, v38, v39
	v_cvt_pk_bf16_f32 v39, v40, v41
	s_waitcnt lgkmcnt(0)
	v_add_f32_e32 v34, v34, v35
	ds_bpermute_b32 v35, v115, v34
	global_store_dwordx2 v[48:49], v[38:39], off offset:256
	v_cvt_pk_bf16_f32 v38, v46, v47
	v_cvt_pk_bf16_f32 v39, v36, v37
	global_store_dwordx2 v[48:49], v[38:39], off offset:288
	s_and_saveexec_b64 s[80:81], s[6:7]
	s_cbranch_execz .LBB0_1051
	v_readlane_b32 s12, v253, 40
	v_lshlrev_b64 v[36:37], 6, v[84:85]
	v_readlane_b32 s13, v253, 41
	s_lshl_b32 s64, s90, 2
	s_waitcnt lgkmcnt(0)
	v_add_f32_e32 v34, v34, v35
	v_lshl_add_u64 v[36:37], s[12:13], 0, v[36:37]
	v_lshl_add_u64 v[36:37], s[78:79], 2, v[36:37]
	v_lshl_add_u64 v[36:37], v[36:37], 0, s[64:65]
	global_store_dword v[36:37], v34, off
; __device__ __forceinline__ unsigned cvt_pk_bf16(float lo, float hi) { unsigned r; asm volatile("v_cvt_pk_bf16_f32 %0, %1, %2" : "=v"(r) : "v"(lo), "v"(hi)); return r; }
;     __device__ __forceinline__ void operator()(f32x4 (&acc)[2][2][4][2], const Unit& u, int wr, int wc, int fr, int fq) const {
;     ...
;             for (int m = 0; m < 4; ++m) { const size_t off = (size_t)(u.pm * BM + ai * HALF + wr * 64 + m * 16 + fr) * ldc + col0;
; #pragma unroll
;                 for (int bj = 0; bj < 2; ++bj)
; #pragma unroll
;                     for (int n = 0; n < 2; ++n) old[m][bj][n] = *(const unsigned long long*)(xb + off + bj * HALF + n * 16); }
; #pragma unroll
;             for (int m = 0; m < 4; ++m) { const int row = u.pm * BM + ai * HALF + wr * 64 + m * 16 + fr; const size_t off = (size_t)row * ldc + col0; float sq = 0.f;
; #pragma unroll
;                 for (int bj = 0; bj < 2; ++bj)
; #pragma unroll
;                     for (int n = 0; n < 2; ++n) { const unsigned long long b = old[m][bj][n];
;                         const unsigned blo = (unsigned)b, bhi = (unsigned)(b >> 32);
;                         f32x4 v; v[0] = __builtin_bit_cast(float, blo << 16); v[1] = __builtin_bit_cast(float, blo & 0xffff0000u); v[2] = __builtin_bit_cast(float, bhi << 16); v[3] = __builtin_bit_cast(float, bhi & 0xffff0000u);
;                         v = v + acc[ai][bj][m][n];
;                         sq += (v[0] * v[0] + v[1] * v[1]) + (v[2] * v[2] + v[3] * v[3]);
;                         *(unsigned long long*)(xb + off + bj * HALF + n * 16) = (unsigned long long)cvt_pk_bf16(v[0], v[1]) | ((unsigned long long)cvt_pk_bf16(v[2], v[3]) << 32); }
;                 sq += __shfl_xor(sq, 16); sq += __shfl_xor(sq, 32);
;                 if (fq == 0) ssp[(size_t)row * 16 + 4 * u.pn + wc] = sq; }
.LBB0_1051:
	s_or_b64 exec, exec, s[80:81]
	s_waitcnt vmcnt(15)
	v_lshlrev_b32_e32 v36, 16, v86
	v_and_b32_e32 v37, 0xffff0000, v86
	v_lshlrev_b32_e32 v38, 16, v87
	v_and_b32_e32 v39, 0xffff0000, v87
	v_pk_add_f32 v[32:33], v[32:33], v[38:39]
	v_pk_add_f32 v[30:31], v[30:31], v[36:37]
	s_waitcnt lgkmcnt(0)
	v_lshlrev_b64 v[34:35], 10, v[70:71]
	v_mul_f32_e32 v36, v31, v31
	v_mul_f32_e32 v37, v33, v33
	v_fmac_f32_e32 v36, v30, v30
	v_fmac_f32_e32 v37, v32, v32
	v_cvt_pk_bf16_f32 v30, v30, v31
	v_cvt_pk_bf16_f32 v31, v32, v33
	v_lshl_add_u64 v[32:33], v[34:35], 1, s[42:43]
	v_lshl_add_u64 v[32:33], v[136:137], 1, v[32:33]
	global_store_dwordx2 v[32:33], v[30:31], off
	s_waitcnt vmcnt(15)
	v_lshlrev_b32_e32 v30, 16, v82
	v_and_b32_e32 v31, 0xffff0000, v82
	v_lshlrev_b32_e32 v34, 16, v83
	v_and_b32_e32 v35, 0xffff0000, v83
	v_pk_add_f32 v[28:29], v[28:29], v[34:35]
	v_pk_add_f32 v[26:27], v[26:27], v[30:31]
	v_mul_f32_e32 v31, v29, v29
	v_mul_f32_e32 v30, v27, v27
	v_fmac_f32_e32 v30, v26, v26
	v_fmac_f32_e32 v31, v28, v28
	v_add_f32_e32 v36, v36, v37
	v_add_f32_e32 v30, v30, v31
	v_add_f32_e32 v36, v36, v30
	s_waitcnt vmcnt(14)
	v_lshlrev_b32_e32 v30, 16, v78
	v_and_b32_e32 v31, 0xffff0000, v78
	v_lshlrev_b32_e32 v34, 16, v79
	v_and_b32_e32 v35, 0xffff0000, v79
	v_pk_add_f32 v[24:25], v[24:25], v[34:35]
	v_pk_add_f32 v[22:23], v[22:23], v[30:31]
	v_cvt_pk_bf16_f32 v26, v26, v27
	v_mul_f32_e32 v30, v25, v25
	v_mul_f32_e32 v27, v23, v23
	v_fmac_f32_e32 v27, v22, v22
	v_fmac_f32_e32 v30, v24, v24
	v_add_f32_e32 v27, v27, v30
	s_waitcnt vmcnt(13)
	v_lshlrev_b32_e32 v30, 16, v74
	v_and_b32_e32 v31, 0xffff0000, v74
	v_lshlrev_b32_e32 v34, 16, v75
	v_and_b32_e32 v35, 0xffff0000, v75
	v_pk_add_f32 v[20:21], v[20:21], v[34:35]
	v_pk_add_f32 v[30:31], v[18:19], v[30:31]
	v_mul_f32_e32 v19, v21, v21
	v_mul_f32_e32 v18, v31, v31
	v_fmac_f32_e32 v18, v30, v30
	v_fmac_f32_e32 v19, v20, v20
	v_add_f32_e32 v27, v36, v27
	v_add_f32_e32 v18, v18, v19
	v_add_f32_e32 v18, v27, v18
	v_mov_b32_e32 v19, v18
	s_nop 1
	v_permlane16_swap_b32_e32 v19, v18
	v_cvt_pk_bf16_f32 v27, v28, v29
	global_store_dwordx2 v[32:33], v[26:27], off offset:32
	v_cvt_pk_bf16_f32 v22, v22, v23
	v_cvt_pk_bf16_f32 v23, v24, v25
	s_waitcnt lgkmcnt(0)
	v_add_f32_e32 v18, v18, v19
	ds_bpermute_b32 v19, v115, v18
	global_store_dwordx2 v[32:33], v[22:23], off offset:256
	v_cvt_pk_bf16_f32 v22, v30, v31
	v_cvt_pk_bf16_f32 v23, v20, v21
	global_store_dwordx2 v[32:33], v[22:23], off offset:288
	s_and_saveexec_b64 s[80:81], s[6:7]
	s_cbranch_execz .LBB0_1053
	v_readlane_b32 s12, v253, 40
	v_lshlrev_b64 v[20:21], 6, v[70:71]
	v_readlane_b32 s13, v253, 41
	s_lshl_b32 s64, s90, 2
	s_waitcnt lgkmcnt(0)
	v_add_f32_e32 v18, v18, v19
	v_lshl_add_u64 v[20:21], s[12:13], 0, v[20:21]
	v_lshl_add_u64 v[20:21], s[78:79], 2, v[20:21]
	v_lshl_add_u64 v[20:21], v[20:21], 0, s[64:65]
	global_store_dword v[20:21], v18, off
.LBB0_1053:
	s_or_b64 exec, exec, s[80:81]
	s_waitcnt vmcnt(15)
	v_lshlrev_b32_e32 v20, 16, v80
	v_and_b32_e32 v21, 0xffff0000, v80
	v_lshlrev_b32_e32 v22, 16, v81
	v_and_b32_e32 v23, 0xffff0000, v81
	v_pk_add_f32 v[16:17], v[16:17], v[22:23]
	v_pk_add_f32 v[14:15], v[14:15], v[20:21]
	s_waitcnt lgkmcnt(0)
	v_lshlrev_b64 v[18:19], 10, v[66:67]
	v_mul_f32_e32 v20, v15, v15
	v_mul_f32_e32 v21, v17, v17
	v_fmac_f32_e32 v20, v14, v14
	v_fmac_f32_e32 v21, v16, v16
	v_cvt_pk_bf16_f32 v14, v14, v15
	v_cvt_pk_bf16_f32 v15, v16, v17
	v_lshl_add_u64 v[16:17], v[18:19], 1, s[42:43]
	v_lshl_add_u64 v[16:17], v[136:137], 1, v[16:17]
	global_store_dwordx2 v[16:17], v[14:15], off
	s_waitcnt vmcnt(15)
	v_lshlrev_b32_e32 v14, 16, v76
	v_and_b32_e32 v15, 0xffff0000, v76
	v_lshlrev_b32_e32 v18, 16, v77
	v_and_b32_e32 v19, 0xffff0000, v77
	v_pk_add_f32 v[12:13], v[12:13], v[18:19]
	v_pk_add_f32 v[10:11], v[10:11], v[14:15]
	v_mul_f32_e32 v15, v13, v13
	v_mul_f32_e32 v14, v11, v11
	v_fmac_f32_e32 v14, v10, v10
	v_fmac_f32_e32 v15, v12, v12
	v_add_f32_e32 v20, v20, v21
	v_add_f32_e32 v14, v14, v15
	v_add_f32_e32 v20, v20, v14
	s_waitcnt vmcnt(14)
	v_lshlrev_b32_e32 v14, 16, v72
	v_and_b32_e32 v15, 0xffff0000, v72
	v_lshlrev_b32_e32 v18, 16, v73
	v_and_b32_e32 v19, 0xffff0000, v73
	v_pk_add_f32 v[8:9], v[8:9], v[18:19]
	v_pk_add_f32 v[6:7], v[6:7], v[14:15]
	v_cvt_pk_bf16_f32 v10, v10, v11
	v_mul_f32_e32 v14, v9, v9
	v_mul_f32_e32 v11, v7, v7
	v_fmac_f32_e32 v11, v6, v6
	v_fmac_f32_e32 v14, v8, v8
	v_add_f32_e32 v11, v11, v14
	s_waitcnt vmcnt(13)
	v_lshlrev_b32_e32 v14, 16, v68
	v_and_b32_e32 v15, 0xffff0000, v68
	v_lshlrev_b32_e32 v18, 16, v69
	v_and_b32_e32 v19, 0xffff0000, v69
	v_pk_add_f32 v[4:5], v[4:5], v[18:19]
	v_pk_add_f32 v[14:15], v[2:3], v[14:15]
	v_mul_f32_e32 v3, v5, v5
	v_mul_f32_e32 v2, v15, v15
	v_fmac_f32_e32 v2, v14, v14
	v_fmac_f32_e32 v3, v4, v4
	v_add_f32_e32 v11, v20, v11
	v_add_f32_e32 v2, v2, v3
	v_add_f32_e32 v2, v11, v2
	v_mov_b32_e32 v3, v2
	s_nop 1
	v_permlane16_swap_b32_e32 v3, v2
	v_cvt_pk_bf16_f32 v11, v12, v13
	global_store_dwordx2 v[16:17], v[10:11], off offset:32
	v_cvt_pk_bf16_f32 v6, v6, v7
	v_cvt_pk_bf16_f32 v7, v8, v9
	s_waitcnt lgkmcnt(0)
	v_add_f32_e32 v2, v2, v3
	ds_bpermute_b32 v3, v115, v2
	global_store_dwordx2 v[16:17], v[6:7], off offset:256
	v_cvt_pk_bf16_f32 v6, v14, v15
	v_cvt_pk_bf16_f32 v7, v4, v5
	global_store_dwordx2 v[16:17], v[6:7], off offset:288
	s_and_saveexec_b64 s[80:81], s[6:7]
	s_cbranch_execz .LBB0_1055
	v_readlane_b32 s12, v253, 40
	v_lshlrev_b64 v[4:5], 6, v[66:67]
	v_readlane_b32 s13, v253, 41
	s_lshl_b32 s64, s90, 2
	s_waitcnt lgkmcnt(0)
	v_add_f32_e32 v2, v2, v3
	v_lshl_add_u64 v[4:5], s[12:13], 0, v[4:5]
	v_lshl_add_u64 v[4:5], s[78:79], 2, v[4:5]
	v_lshl_add_u64 v[4:5], v[4:5], 0, s[64:65]
	global_store_dword v[4:5], v2, off

; __device__ __forceinline__ void load_row_scales(const float* ssp, int row0, int fq, float (&rs)[2][4]) {
;     ...
;     const float* sp = ssp + (size_t)row0 * 16 + 4 * fq;
; #pragma unroll
;     for (int ai = 0; ai < 2; ++ai)
; #pragma unroll
;         for (int m = 0; m < 4; ++m) part[ai][m] = *(const f32x4*)(sp + (size_t)(ai * HALF + m * 16) * 16);
; #pragma unroll
;     for (int ai = 0; ai < 2; ++ai)
; #pragma unroll
;         for (int m = 0; m < 4; ++m) { float t = (part[ai][m][0] + part[ai][m][1]) + (part[ai][m][2] + part[ai][m][3]);
;             t += __shfl_xor(t, 16); t += __shfl_xor(t, 32);
;             rs[ai][m] = 1.0f / sqrtf(t * (1.0f / 1024.0f) + 1e-6f); }
;     __device__ __forceinline__ void operator()(f32x4 (&acc)[2][2][4][2], const Unit& u, int wr, int wc, int fr, int fq) const {
;     ...
;                 for (int m = 0; m < 4; ++m) { const float rs = rsa[ai][m];
; #pragma unroll
;                     for (int bj = 0; bj < 2; ++bj) { const f32x4 v0 = acc[ai][bj][m][0] * rs, v1 = acc[ai][bj][m][1] * rs;
.LBB0_1127:
	v_lshl_add_u32 v130, s13, 8, v173
	v_ashrrev_i32_e32 v131, 31, v130
	v_lshlrev_b64 v[134:135], 11, v[130:131]
	v_lshlrev_b64 v[130:131], 6, v[130:131]
	v_lshl_add_u64 v[130:131], v[164:165], 0, v[130:131]
	global_load_dwordx4 v[180:183], v[130:131], off
	global_load_dwordx4 v[154:157], v[130:131], off offset:1024
	global_load_dwordx4 v[150:153], v[130:131], off offset:2048
	global_load_dwordx4 v[146:149], v[130:131], off offset:3072
	s_movk_i32 s0, 0x2000
	v_add_co_u32_e32 v130, vcc, s0, v130
	v_and_b32_e32 v177, 64, v229
	s_nop 0
	v_addc_co_u32_e32 v131, vcc, 0, v131, vcc
	v_xor_b32_e32 v172, 16, v229
	v_add_u32_e32 v178, 64, v177
	v_cmp_lt_i32_e32 vcc, v172, v178
	v_lshl_or_b32 v132, s12, 8, v175
	v_lshl_add_u64 v[134:135], s[46:47], 0, v[134:135]
	v_cndmask_b32_e32 v172, v229, v172, vcc
	v_lshlrev_b32_e32 v177, 2, v172
	v_xor_b32_e32 v172, 32, v229
	v_cmp_lt_i32_e32 vcc, v172, v178
	v_ashrrev_i32_e32 v133, 31, v132
	v_lshl_add_u64 v[170:171], v[132:133], 1, v[134:135]
	v_cndmask_b32_e32 v172, v229, v172, vcc
	v_lshlrev_b32_e32 v178, 2, v172
	global_load_dwordx4 v[142:145], v[130:131], off
	global_load_dwordx4 v[138:141], v[130:131], off offset:1024
	global_load_dwordx4 v[134:137], v[130:131], off offset:2048
	s_nop 0
	global_load_dwordx4 v[130:133], v[130:131], off offset:3072
	s_mov_b64 s[12:13], 0x8000
	s_waitcnt vmcnt(0)
	v_mov_b32_e32 v184, v181
	v_mov_b32_e32 v185, v182
	v_mov_b32_e32 v181, v183
	v_pk_add_f32 v[180:181], v[184:185], v[180:181]
	s_nop 0
	v_add_f32_e32 v172, v180, v181
	v_mov_b32_e32 v179, v172
	s_nop 1
	v_permlane16_swap_b32_e32 v179, v172
	s_waitcnt lgkmcnt(0)
	v_add_f32_e32 v172, v172, v179
	v_mov_b32_e32 v179, v172
	s_nop 1
	v_permlane32_swap_b32_e32 v179, v172
	s_waitcnt lgkmcnt(0)
	v_add_f32_e32 v172, v172, v179
	v_fmamk_f32 v172, v172, 0x3a800000, v230
	v_mov_b32_e32 v180, v155
	v_mov_b32_e32 v181, v156
	v_mov_b32_e32 v155, v157
	v_pk_add_f32 v[154:155], v[180:181], v[154:155]
	v_rsq_f32_e32 v172, v172
	s_nop 0
	v_add_f32_e32 v154, v154, v155
	v_mov_b32_e32 v155, v154
	s_nop 1
	v_permlane16_swap_b32_e32 v155, v154
	v_pk_mul_f32 v[128:129], v[128:129], v[172:173] op_sel_hi:[1,0]
	v_pk_mul_f32 v[126:127], v[126:127], v[172:173] op_sel_hi:[1,0]
	v_pk_mul_f32 v[120:121], v[120:121], v[172:173] op_sel_hi:[1,0]
	v_pk_mul_f32 v[118:119], v[118:119], v[172:173] op_sel_hi:[1,0]
	s_waitcnt lgkmcnt(0)
	v_add_f32_e32 v154, v154, v155
	v_mov_b32_e32 v155, v154
	s_nop 1
	v_permlane32_swap_b32_e32 v155, v154
	s_waitcnt lgkmcnt(0)
	v_add_f32_e32 v154, v154, v155
	v_fmamk_f32 v154, v154, 0x3a800000, v230
	v_mov_b32_e32 v156, v151
	v_mov_b32_e32 v157, v152
	v_mov_b32_e32 v151, v153
	v_pk_add_f32 v[150:151], v[156:157], v[150:151]
	v_rsq_f32_e32 v154, v154
	s_nop 0
	v_add_f32_e32 v150, v150, v151
	v_mov_b32_e32 v151, v150
	s_nop 1
	v_permlane16_swap_b32_e32 v151, v150
	s_waitcnt lgkmcnt(0)
	v_add_f32_e32 v150, v150, v151
	v_mov_b32_e32 v151, v150
	s_nop 1
	v_permlane32_swap_b32_e32 v151, v150
	s_waitcnt lgkmcnt(0)
	v_add_f32_e32 v150, v150, v151
	v_fmamk_f32 v150, v150, 0x3a800000, v230
	v_mov_b32_e32 v152, v147
	v_mov_b32_e32 v153, v148
	v_mov_b32_e32 v147, v149
	v_pk_add_f32 v[146:147], v[152:153], v[146:147]
	v_rsq_f32_e32 v150, v150
	s_nop 0
	v_add_f32_e32 v146, v146, v147
	v_mov_b32_e32 v147, v146
	s_nop 1
	v_permlane16_swap_b32_e32 v147, v146
	v_pk_mul_f32 v[114:115], v[114:115], v[154:155] op_sel_hi:[1,0]
	v_pk_mul_f32 v[104:105], v[104:105], v[154:155] op_sel_hi:[1,0]
	v_pk_mul_f32 v[102:103], v[102:103], v[154:155] op_sel_hi:[1,0]
	s_waitcnt lgkmcnt(0)
	v_add_f32_e32 v146, v146, v147
	v_mov_b32_e32 v147, v146
	s_nop 1
	v_permlane32_swap_b32_e32 v147, v146
	s_waitcnt lgkmcnt(0)
	v_add_f32_e32 v146, v146, v147
	v_fmamk_f32 v146, v146, 0x3a800000, v230
	v_mov_b32_e32 v148, v143
	v_mov_b32_e32 v149, v144
	v_mov_b32_e32 v143, v145
	v_pk_add_f32 v[142:143], v[148:149], v[142:143]
	v_rsq_f32_e32 v146, v146
	s_nop 0
	v_add_f32_e32 v142, v142, v143
	v_mov_b32_e32 v143, v142
	s_nop 1
	v_permlane16_swap_b32_e32 v143, v142
	v_pk_mul_f32 v[98:99], v[98:99], v[150:151] op_sel_hi:[1,0]
	v_pk_mul_f32 v[88:89], v[88:89], v[150:151] op_sel_hi:[1,0]
	v_pk_mul_f32 v[86:87], v[86:87], v[150:151] op_sel_hi:[1,0]
	s_waitcnt lgkmcnt(0)
	v_add_f32_e32 v142, v142, v143
	v_mov_b32_e32 v143, v142
	s_nop 1
	v_permlane32_swap_b32_e32 v143, v142
	s_waitcnt lgkmcnt(0)
	v_add_f32_e32 v142, v142, v143
	v_fmamk_f32 v142, v142, 0x3a800000, v230
	v_mov_b32_e32 v144, v139
	v_mov_b32_e32 v145, v140
	v_mov_b32_e32 v139, v141
	v_pk_add_f32 v[138:139], v[144:145], v[138:139]
	v_rsq_f32_e32 v142, v142
	s_nop 0
	v_add_f32_e32 v138, v138, v139
	v_mov_b32_e32 v139, v138
	s_nop 1
	v_permlane16_swap_b32_e32 v139, v138
	v_pk_mul_f32 v[82:83], v[82:83], v[146:147] op_sel_hi:[1,0]
	v_pk_mul_f32 v[72:73], v[72:73], v[146:147] op_sel_hi:[1,0]
	v_pk_mul_f32 v[70:71], v[70:71], v[146:147] op_sel_hi:[1,0]
	s_waitcnt lgkmcnt(0)
	v_add_f32_e32 v138, v138, v139
	v_mov_b32_e32 v139, v138
	s_nop 1
	v_permlane32_swap_b32_e32 v139, v138
	s_waitcnt lgkmcnt(0)
	v_add_f32_e32 v138, v138, v139
	v_fmamk_f32 v138, v138, 0x3a800000, v230
	v_mov_b32_e32 v140, v135
	v_mov_b32_e32 v141, v136
	v_mov_b32_e32 v135, v137
	v_pk_add_f32 v[134:135], v[140:141], v[134:135]
	v_rsq_f32_e32 v138, v138
	s_nop 0
	v_add_f32_e32 v134, v134, v135
	v_mov_b32_e32 v135, v134
	s_nop 1
	v_permlane16_swap_b32_e32 v135, v134
	v_pk_mul_f32 v[64:65], v[64:65], v[142:143] op_sel_hi:[1,0]
	v_pk_mul_f32 v[62:63], v[62:63], v[142:143] op_sel_hi:[1,0]
	v_pk_mul_f32 v[56:57], v[56:57], v[142:143] op_sel_hi:[1,0]
	v_pk_mul_f32 v[54:55], v[54:55], v[142:143] op_sel_hi:[1,0]
	s_waitcnt lgkmcnt(0)
; __device__ __forceinline__ void load_row_scales(const float* ssp, int row0, int fq, float (&rs)[2][4]) {
;     ...
;         for (int m = 0; m < 4; ++m) { float t = (part[ai][m][0] + part[ai][m][1]) + (part[ai][m][2] + part[ai][m][3]);
;             t += __shfl_xor(t, 16); t += __shfl_xor(t, 32);
;             rs[ai][m] = 1.0f / sqrtf(t * (1.0f / 1024.0f) + 1e-6f); }
;     __device__ __forceinline__ void operator()(f32x4 (&acc)[2][2][4][2], const Unit& u, int wr, int wc, int fr, int fq) const {
;     ...
;                 for (int m = 0; m < 4; ++m) { const float rs = rsa[ai][m];
; #pragma unroll
;                     for (int bj = 0; bj < 2; ++bj) { const f32x4 v0 = acc[ai][bj][m][0] * rs, v1 = acc[ai][bj][m][1] * rs;
	v_add_f32_e32 v134, v134, v135
	v_mov_b32_e32 v135, v134
	s_nop 1
	v_permlane32_swap_b32_e32 v135, v134
	s_waitcnt lgkmcnt(0)
	v_add_f32_e32 v134, v134, v135
	v_fmamk_f32 v134, v134, 0x3a800000, v230
	v_mov_b32_e32 v136, v131
	v_mov_b32_e32 v137, v132
	v_mov_b32_e32 v131, v133
	v_pk_add_f32 v[130:131], v[136:137], v[130:131]
	v_rsq_f32_e32 v134, v134
	s_nop 0
	v_add_f32_e32 v130, v130, v131
	v_mov_b32_e32 v131, v130
	s_nop 1
	v_permlane16_swap_b32_e32 v131, v130
	v_pk_mul_f32 v[50:51], v[50:51], v[138:139] op_sel_hi:[1,0]
	v_pk_mul_f32 v[40:41], v[40:41], v[138:139] op_sel_hi:[1,0]
	v_pk_mul_f32 v[38:39], v[38:39], v[138:139] op_sel_hi:[1,0]
	s_waitcnt lgkmcnt(0)
	v_add_f32_e32 v130, v130, v131
	v_mov_b32_e32 v131, v130
	s_nop 1
	v_permlane32_swap_b32_e32 v131, v130
	s_waitcnt lgkmcnt(0)
; __device__ __forceinline__ unsigned cvt_pk_bf16(float lo, float hi) { unsigned r; asm volatile("v_cvt_pk_bf16_f32 %0, %1, %2" : "=v"(r) : "v"(lo), "v"(hi)); return r; }
;     __device__ __forceinline__ void operator()(f32x4 (&acc)[2][2][4][2], const Unit& u, int wr, int wc, int fr, int fq) const {
;     ...
;                 for (int m = 0; m < 4; ++m) { const float rs = rsa[ai][m];
; #pragma unroll
;                     for (int bj = 0; bj < 2; ++bj) { const f32x4 v0 = acc[ai][bj][m][0] * rs, v1 = acc[ai][bj][m][1] * rs;
;                         u32x4 w; w.x = cvt_pk_bf16(v0[0], v0[1]); w.y = cvt_pk_bf16(v0[2], v0[3]); w.z = cvt_pk_bf16(v1[0], v1[1]); w.w = cvt_pk_bf16(v1[2], v1[3]);
;                         *(u32x4*)(rowp + bj * HALF) = w; }
;                     rowp += (size_t)16 * ldr; asm volatile("" : "+v"(rowp) :: "memory"); }
;                 rowp += (size_t)64 * ldr; asm volatile("" : "+v"(rowp)); }
	v_add_f32_e32 v130, v130, v131
	v_fmamk_f32 v130, v130, 0x3a800000, v230
	s_mov_b64 s[0:1], 0x20000
	v_pk_mul_f32 v[132:133], v[124:125], v[172:173] op_sel_hi:[1,0]
	v_pk_mul_f32 v[124:125], v[122:123], v[172:173] op_sel_hi:[1,0]
	v_cvt_pk_bf16_f32 v122, v126, v127
	v_cvt_pk_bf16_f32 v123, v128, v129
	v_pk_mul_f32 v[34:35], v[34:35], v[134:135] op_sel_hi:[1,0]
	v_cvt_pk_bf16_f32 v124, v124, v125
	v_cvt_pk_bf16_f32 v125, v132, v133
	global_store_dwordx4 v[170:171], v[122:125], off
	v_pk_mul_f32 v[24:25], v[24:25], v[134:135] op_sel_hi:[1,0]
	v_pk_mul_f32 v[22:23], v[22:23], v[134:135] op_sel_hi:[1,0]
	v_pk_mul_f32 v[122:123], v[112:113], v[172:173] op_sel_hi:[1,0]
	v_pk_mul_f32 v[112:113], v[110:111], v[172:173] op_sel_hi:[1,0]
	v_cvt_pk_bf16_f32 v110, v118, v119
	v_cvt_pk_bf16_f32 v111, v120, v121
	v_rsq_f32_e32 v130, v130
	s_nop 0
	v_cvt_pk_bf16_f32 v112, v112, v113
	v_cvt_pk_bf16_f32 v113, v122, v123
	global_store_dwordx4 v[170:171], v[110:113], off offset:256
	v_pk_mul_f32 v[18:19], v[18:19], v[130:131] op_sel_hi:[1,0]
	v_pk_mul_f32 v[8:9], v[8:9], v[130:131] op_sel_hi:[1,0]
	v_lshl_add_u64 v[110:111], v[170:171], 0, s[12:13]
	v_pk_mul_f32 v[112:113], v[116:117], v[154:155] op_sel_hi:[1,0]
	v_pk_mul_f32 v[116:117], v[108:109], v[154:155] op_sel_hi:[1,0]
	v_pk_mul_f32 v[108:109], v[106:107], v[154:155] op_sel_hi:[1,0]
	v_cvt_pk_bf16_f32 v106, v114, v115
	v_cvt_pk_bf16_f32 v107, v112, v113
	v_pk_mul_f32 v[6:7], v[6:7], v[130:131] op_sel_hi:[1,0]
	v_cvt_pk_bf16_f32 v108, v108, v109
	v_cvt_pk_bf16_f32 v109, v116, v117
	flat_store_dwordx4 v[110:111], v[106:109]
	s_andn2_b64 vcc, exec, s[6:7]
	s_nop 0
	v_pk_mul_f32 v[106:107], v[96:97], v[154:155] op_sel_hi:[1,0]
	v_pk_mul_f32 v[96:97], v[94:95], v[154:155] op_sel_hi:[1,0]
	v_cvt_pk_bf16_f32 v94, v102, v103
	v_cvt_pk_bf16_f32 v95, v104, v105
	s_nop 0
	v_cvt_pk_bf16_f32 v96, v96, v97
	v_cvt_pk_bf16_f32 v97, v106, v107
	flat_store_dwordx4 v[110:111], v[94:97] offset:256
	s_nop 1
	v_lshl_add_u64 v[94:95], v[110:111], 0, s[12:13]
	v_pk_mul_f32 v[96:97], v[100:101], v[150:151] op_sel_hi:[1,0]
	v_pk_mul_f32 v[100:101], v[92:93], v[150:151] op_sel_hi:[1,0]
	v_pk_mul_f32 v[92:93], v[90:91], v[150:151] op_sel_hi:[1,0]
	v_cvt_pk_bf16_f32 v90, v98, v99
	v_cvt_pk_bf16_f32 v91, v96, v97
	s_nop 0
	v_cvt_pk_bf16_f32 v92, v92, v93
	v_cvt_pk_bf16_f32 v93, v100, v101
	flat_store_dwordx4 v[94:95], v[90:93]
	s_nop 1
	v_pk_mul_f32 v[90:91], v[80:81], v[150:151] op_sel_hi:[1,0]
	v_pk_mul_f32 v[80:81], v[78:79], v[150:151] op_sel_hi:[1,0]
	v_cvt_pk_bf16_f32 v78, v86, v87
	v_cvt_pk_bf16_f32 v79, v88, v89
	s_nop 0
	v_cvt_pk_bf16_f32 v80, v80, v81
	v_cvt_pk_bf16_f32 v81, v90, v91
	flat_store_dwordx4 v[94:95], v[78:81] offset:256
	s_nop 1
	v_lshl_add_u64 v[78:79], v[94:95], 0, s[12:13]
	v_pk_mul_f32 v[80:81], v[84:85], v[146:147] op_sel_hi:[1,0]
	v_pk_mul_f32 v[84:85], v[76:77], v[146:147] op_sel_hi:[1,0]
	v_pk_mul_f32 v[76:77], v[74:75], v[146:147] op_sel_hi:[1,0]
	v_cvt_pk_bf16_f32 v74, v82, v83
	v_cvt_pk_bf16_f32 v75, v80, v81
	s_nop 0
	v_cvt_pk_bf16_f32 v76, v76, v77
	v_cvt_pk_bf16_f32 v77, v84, v85
	flat_store_dwordx4 v[78:79], v[74:77]
	s_nop 1
	v_pk_mul_f32 v[74:75], v[68:69], v[146:147] op_sel_hi:[1,0]
	v_pk_mul_f32 v[68:69], v[66:67], v[146:147] op_sel_hi:[1,0]
	v_cvt_pk_bf16_f32 v66, v70, v71
	v_cvt_pk_bf16_f32 v67, v72, v73
	s_nop 0
	v_cvt_pk_bf16_f32 v68, v68, v69
	v_cvt_pk_bf16_f32 v69, v74, v75
	flat_store_dwordx4 v[78:79], v[66:69] offset:256
	s_nop 1
	v_lshl_add_u64 v[66:67], v[78:79], 0, s[12:13]
	v_pk_mul_f32 v[68:69], v[60:61], v[142:143] op_sel_hi:[1,0]
	v_lshl_add_u64 v[66:67], v[66:67], 0, s[0:1]
	v_pk_mul_f32 v[60:61], v[58:59], v[142:143] op_sel_hi:[1,0]
	v_cvt_pk_bf16_f32 v58, v62, v63
	v_cvt_pk_bf16_f32 v59, v64, v65
	s_nop 0
	v_cvt_pk_bf16_f32 v60, v60, v61
	v_cvt_pk_bf16_f32 v61, v68, v69
	flat_store_dwordx4 v[66:67], v[58:61]
	s_nop 1
	v_pk_mul_f32 v[58:59], v[48:49], v[142:143] op_sel_hi:[1,0]
	v_pk_mul_f32 v[48:49], v[46:47], v[142:143] op_sel_hi:[1,0]
	v_cvt_pk_bf16_f32 v46, v54, v55
	v_cvt_pk_bf16_f32 v47, v56, v57
	s_nop 0
	v_cvt_pk_bf16_f32 v48, v48, v49
	v_cvt_pk_bf16_f32 v49, v58, v59
	flat_store_dwordx4 v[66:67], v[46:49] offset:256
	s_nop 1
	v_lshl_add_u64 v[46:47], v[66:67], 0, s[12:13]
	v_pk_mul_f32 v[48:49], v[52:53], v[138:139] op_sel_hi:[1,0]
	v_pk_mul_f32 v[52:53], v[44:45], v[138:139] op_sel_hi:[1,0]
	v_pk_mul_f32 v[44:45], v[42:43], v[138:139] op_sel_hi:[1,0]
	v_cvt_pk_bf16_f32 v42, v50, v51
	v_cvt_pk_bf16_f32 v43, v48, v49
	s_nop 0
	v_cvt_pk_bf16_f32 v44, v44, v45
	v_cvt_pk_bf16_f32 v45, v52, v53
	flat_store_dwordx4 v[46:47], v[42:45]
	s_nop 1
	v_pk_mul_f32 v[42:43], v[32:33], v[138:139] op_sel_hi:[1,0]
	v_pk_mul_f32 v[32:33], v[30:31], v[138:139] op_sel_hi:[1,0]
	v_cvt_pk_bf16_f32 v30, v38, v39
	v_cvt_pk_bf16_f32 v31, v40, v41
	s_nop 0
	v_cvt_pk_bf16_f32 v32, v32, v33
	v_cvt_pk_bf16_f32 v33, v42, v43
	flat_store_dwordx4 v[46:47], v[30:33] offset:256
	s_nop 1
	v_lshl_add_u64 v[30:31], v[46:47], 0, s[12:13]
	v_pk_mul_f32 v[32:33], v[36:37], v[134:135] op_sel_hi:[1,0]
	v_pk_mul_f32 v[36:37], v[28:29], v[134:135] op_sel_hi:[1,0]
	v_pk_mul_f32 v[28:29], v[26:27], v[134:135] op_sel_hi:[1,0]
	v_cvt_pk_bf16_f32 v26, v34, v35
	v_cvt_pk_bf16_f32 v27, v32, v33
	s_nop 0
	v_cvt_pk_bf16_f32 v28, v28, v29
	v_cvt_pk_bf16_f32 v29, v36, v37
	flat_store_dwordx4 v[30:31], v[26:29]
	s_nop 1
	v_pk_mul_f32 v[26:27], v[16:17], v[134:135] op_sel_hi:[1,0]
	v_pk_mul_f32 v[16:17], v[14:15], v[134:135] op_sel_hi:[1,0]
	v_cvt_pk_bf16_f32 v14, v22, v23
	v_cvt_pk_bf16_f32 v15, v24, v25
	s_nop 0
	v_cvt_pk_bf16_f32 v16, v16, v17
	v_cvt_pk_bf16_f32 v17, v26, v27
	flat_store_dwordx4 v[30:31], v[14:17] offset:256
	s_nop 1
	v_lshl_add_u64 v[14:15], v[30:31], 0, s[12:13]
	v_pk_mul_f32 v[16:17], v[20:21], v[130:131] op_sel_hi:[1,0]
	v_pk_mul_f32 v[20:21], v[12:13], v[130:131] op_sel_hi:[1,0]
	v_pk_mul_f32 v[12:13], v[10:11], v[130:131] op_sel_hi:[1,0]
	v_cvt_pk_bf16_f32 v10, v18, v19
	v_cvt_pk_bf16_f32 v11, v16, v17
	s_nop 0
	v_cvt_pk_bf16_f32 v12, v12, v13
	v_cvt_pk_bf16_f32 v13, v20, v21
	flat_store_dwordx4 v[14:15], v[10:13]
	s_nop 1
	v_pk_mul_f32 v[10:11], v[4:5], v[130:131] op_sel_hi:[1,0]
	v_pk_mul_f32 v[4:5], v[2:3], v[130:131] op_sel_hi:[1,0]
	v_cvt_pk_bf16_f32 v2, v6, v7
	v_cvt_pk_bf16_f32 v3, v8, v9
	s_nop 0
	v_cvt_pk_bf16_f32 v4, v4, v5
	v_cvt_pk_bf16_f32 v5, v10, v11
	flat_store_dwordx4 v[14:15], v[2:5] offset:256
	s_nop 1
	v_lshl_add_u64 v[2:3], v[14:15], 0, s[12:13]
	s_nop 0
	v_lshl_add_u64 v[2:3], v[2:3], 0, s[0:1]
	s_mov_b64 s[0:1], -1
	s_cbranch_vccnz .LBB0_1116
	s_andn2_b64 vcc, exec, s[4:5]
	s_cbranch_vccnz .LBB0_1115
	s_barrier
	s_branch .LBB0_1115

; __device__ __forceinline__ unsigned cvt_pk_bf16(float lo, float hi) { unsigned r; asm volatile("v_cvt_pk_bf16_f32 %0, %1, %2" : "=v"(r) : "v"(lo), "v"(hi)); return r; }
;     __device__ __forceinline__ void operator()(f32x4 (&acc)[2][2][4][2], const Unit& u, int wr, int wc, int fr, int fq) const {
;     ...
;             for (int m = 0; m < 4; ++m) { const size_t off = (size_t)(u.pm * BM + ai * HALF + wr * 64 + m * 16 + fr) * ldc + col0;
; #pragma unroll
;                 for (int bj = 0; bj < 2; ++bj)
; #pragma unroll
;                     for (int n = 0; n < 2; ++n) old[m][bj][n] = *(const unsigned long long*)(xb + off + bj * HALF + n * 16); }
; #pragma unroll
;             for (int m = 0; m < 4; ++m) { const int row = u.pm * BM + ai * HALF + wr * 64 + m * 16 + fr; const size_t off = (size_t)row * ldc + col0; float sq = 0.f;
; #pragma unroll
;                 for (int bj = 0; bj < 2; ++bj)
; #pragma unroll
;                     for (int n = 0; n < 2; ++n) { const unsigned long long b = old[m][bj][n];
;                         const unsigned blo = (unsigned)b, bhi = (unsigned)(b >> 32);
;                         f32x4 v; v[0] = __builtin_bit_cast(float, blo << 16); v[1] = __builtin_bit_cast(float, blo & 0xffff0000u); v[2] = __builtin_bit_cast(float, bhi << 16); v[3] = __builtin_bit_cast(float, bhi & 0xffff0000u);
;                         v = v + acc[ai][bj][m][n];
;                         sq += (v[0] * v[0] + v[1] * v[1]) + (v[2] * v[2] + v[3] * v[3]);
;                         *(unsigned long long*)(xb + off + bj * HALF + n * 16) = (unsigned long long)cvt_pk_bf16(v[0], v[1]) | ((unsigned long long)cvt_pk_bf16(v[2], v[3]) << 32); }
;                 sq += __shfl_xor(sq, 16); sq += __shfl_xor(sq, 32);
;                 if (fq == 0) ssp[(size_t)row * 16 + 4 * u.pn + wc] = sq; }
.LBB0_1266:
	v_lshl_or_b32 v136, s12, 8, v174
	v_lshl_add_u32 v140, s13, 8, v172
	v_ashrrev_i32_e32 v137, 31, v136
	v_lshlrev_b64 v[176:177], 1, v[136:137]
	v_ashrrev_i32_e32 v141, 31, v140
	v_lshl_add_u64 v[138:139], s[42:43], 0, v[176:177]
	v_lshlrev_b64 v[178:179], 11, v[140:141]
	v_lshl_add_u64 v[142:143], v[138:139], 0, v[178:179]
	global_load_dwordx2 v[180:181], v[142:143], off
	global_load_dwordx2 v[182:183], v[142:143], off offset:32
	global_load_dwordx2 v[184:185], v[142:143], off offset:256
	global_load_dwordx2 v[188:189], v[142:143], off offset:288
	v_or_b32_e32 v160, 16, v140
	v_ashrrev_i32_e32 v161, 31, v160
	v_lshlrev_b64 v[142:143], 11, v[160:161]
	v_or_b32_e32 v146, 32, v140
	v_lshl_add_u64 v[142:143], v[138:139], 0, v[142:143]
	v_ashrrev_i32_e32 v147, 31, v146
	global_load_dwordx2 v[170:171], v[142:143], off
	global_load_dwordx2 v[168:169], v[142:143], off offset:32
	global_load_dwordx2 v[166:167], v[142:143], off offset:256
	global_load_dwordx2 v[164:165], v[142:143], off offset:288
	v_lshlrev_b64 v[142:143], 11, v[146:147]
	v_lshl_add_u64 v[142:143], v[138:139], 0, v[142:143]
	global_load_dwordx2 v[162:163], v[142:143], off
	global_load_dwordx2 v[158:159], v[142:143], off offset:32
	global_load_dwordx2 v[154:155], v[142:143], off offset:256
	global_load_dwordx2 v[150:151], v[142:143], off offset:288
	v_or_b32_e32 v142, 48, v140
	v_ashrrev_i32_e32 v143, 31, v142
	v_lshlrev_b64 v[144:145], 11, v[142:143]
	v_lshl_add_u64 v[144:145], v[138:139], 0, v[144:145]
	global_load_dwordx2 v[156:157], v[144:145], off
	global_load_dwordx2 v[152:153], v[144:145], off offset:32
	global_load_dwordx2 v[148:149], v[144:145], off offset:256
	s_nop 0
	global_load_dwordx2 v[144:145], v[144:145], off offset:288
	s_lshl_b32 s76, s12, 2
	s_ashr_i32 s77, s76, 31
	s_waitcnt vmcnt(0)
	v_lshlrev_b32_e32 v190, 16, v180
	v_and_b32_e32 v191, 0xffff0000, v180
	v_lshlrev_b32_e32 v180, 16, v181
	v_and_b32_e32 v181, 0xffff0000, v181
	v_pk_add_f32 v[128:129], v[128:129], v[180:181]
	v_pk_add_f32 v[126:127], v[126:127], v[190:191]
	v_mul_f32_e32 v181, v129, v129
	v_mul_f32_e32 v180, v127, v127
	v_fmac_f32_e32 v180, v126, v126
	v_fmac_f32_e32 v181, v128, v128
	v_cvt_pk_bf16_f32 v126, v126, v127
	v_cvt_pk_bf16_f32 v127, v128, v129
	v_lshl_add_u64 v[128:129], s[42:43], 0, v[178:179]
	v_lshl_add_u64 v[128:129], v[128:129], 0, v[176:177]
	global_store_dwordx2 v[128:129], v[126:127], off
	v_lshlrev_b32_e32 v126, 16, v182
	v_and_b32_e32 v127, 0xffff0000, v182
	v_pk_add_f32 v[122:123], v[122:123], v[126:127]
	v_lshlrev_b32_e32 v176, 16, v183
	v_and_b32_e32 v177, 0xffff0000, v183
	v_mul_f32_e32 v126, v123, v123
	v_pk_add_f32 v[124:125], v[124:125], v[176:177]
	v_fmac_f32_e32 v126, v122, v122
	v_cvt_pk_bf16_f32 v122, v122, v123
	v_cvt_pk_bf16_f32 v123, v124, v125
	v_mul_f32_e32 v127, v125, v125
	global_store_dwordx2 v[128:129], v[122:123], off offset:32
	v_lshlrev_b32_e32 v122, 16, v184
	v_and_b32_e32 v123, 0xffff0000, v184
	v_fmac_f32_e32 v127, v124, v124
	v_lshlrev_b32_e32 v124, 16, v185
	v_and_b32_e32 v125, 0xffff0000, v185
	v_pk_add_f32 v[118:119], v[118:119], v[122:123]
	v_pk_add_f32 v[120:121], v[120:121], v[124:125]
	v_mul_f32_e32 v122, v119, v119
	v_fmac_f32_e32 v122, v118, v118
	v_mul_f32_e32 v123, v121, v121
	v_cvt_pk_bf16_f32 v118, v118, v119
	v_cvt_pk_bf16_f32 v119, v120, v121
	v_fmac_f32_e32 v123, v120, v120
	global_store_dwordx2 v[128:129], v[118:119], off offset:256
	v_lshlrev_b32_e32 v118, 16, v188
	v_and_b32_e32 v119, 0xffff0000, v188
	v_lshlrev_b32_e32 v120, 16, v189
	v_and_b32_e32 v121, 0xffff0000, v189
	v_pk_add_f32 v[116:117], v[116:117], v[120:121]
	v_pk_add_f32 v[118:119], v[114:115], v[118:119]
	v_add_f32_e32 v180, v180, v181
	v_add_f32_e32 v126, v126, v127
	v_mul_f32_e32 v114, v119, v119
	v_mul_f32_e32 v115, v117, v117
	v_add_f32_e32 v126, v180, v126
	v_add_f32_e32 v122, v122, v123
	v_fmac_f32_e32 v114, v118, v118
	v_fmac_f32_e32 v115, v116, v116
	v_add_f32_e32 v122, v126, v122
	v_add_f32_e32 v114, v114, v115
	v_cvt_pk_bf16_f32 v118, v118, v119
	v_cvt_pk_bf16_f32 v119, v116, v117
	v_and_b32_e32 v116, 64, v229
	v_add_f32_e32 v115, v122, v114
	v_xor_b32_e32 v114, 16, v229
	v_add_u32_e32 v117, 64, v116
	v_cmp_lt_i32_e32 vcc, v114, v117
	global_store_dwordx2 v[128:129], v[118:119], off offset:288
	s_nop 0
	v_cndmask_b32_e32 v114, v229, v114, vcc
	v_lshlrev_b32_e32 v114, 2, v114
	v_mov_b32_e32 v116, v115
	s_nop 1
	v_permlane16_swap_b32_e32 v116, v115
	s_waitcnt lgkmcnt(0)
	v_add_f32_e32 v116, v115, v116
	v_xor_b32_e32 v115, 32, v229
	v_cmp_lt_i32_e32 vcc, v115, v117
	s_nop 1
	v_cndmask_b32_e32 v115, v229, v115, vcc
	v_lshlrev_b32_e32 v115, 2, v115
	ds_bpermute_b32 v117, v115, v116
	s_and_saveexec_b64 s[78:79], s[6:7]
	s_cbranch_execz .LBB0_1268
	v_lshlrev_b64 v[118:119], 6, v[140:141]
	v_lshl_add_u64 v[118:119], s[14:15], 0, v[118:119]
	v_lshl_add_u64 v[118:119], s[76:77], 2, v[118:119]
	s_lshl_b32 s64, s86, 2
	v_lshl_add_u64 v[118:119], v[118:119], 0, s[64:65]
	s_waitcnt lgkmcnt(0)
	v_add_f32_e32 v116, v116, v117
	global_store_dword v[118:119], v116, off
; __device__ __forceinline__ unsigned cvt_pk_bf16(float lo, float hi) { unsigned r; asm volatile("v_cvt_pk_bf16_f32 %0, %1, %2" : "=v"(r) : "v"(lo), "v"(hi)); return r; }
;     __device__ __forceinline__ void operator()(f32x4 (&acc)[2][2][4][2], const Unit& u, int wr, int wc, int fr, int fq) const {
;     ...
;             for (int m = 0; m < 4; ++m) { const int row = u.pm * BM + ai * HALF + wr * 64 + m * 16 + fr; const size_t off = (size_t)row * ldc + col0; float sq = 0.f;
; #pragma unroll
;                 for (int bj = 0; bj < 2; ++bj)
; #pragma unroll
;                     for (int n = 0; n < 2; ++n) { const unsigned long long b = old[m][bj][n];
;                         const unsigned blo = (unsigned)b, bhi = (unsigned)(b >> 32);
;                         f32x4 v; v[0] = __builtin_bit_cast(float, blo << 16); v[1] = __builtin_bit_cast(float, blo & 0xffff0000u); v[2] = __builtin_bit_cast(float, bhi << 16); v[3] = __builtin_bit_cast(float, bhi & 0xffff0000u);
;                         v = v + acc[ai][bj][m][n];
;                         sq += (v[0] * v[0] + v[1] * v[1]) + (v[2] * v[2] + v[3] * v[3]);
;                         *(unsigned long long*)(xb + off + bj * HALF + n * 16) = (unsigned long long)cvt_pk_bf16(v[0], v[1]) | ((unsigned long long)cvt_pk_bf16(v[2], v[3]) << 32); }
;                 sq += __shfl_xor(sq, 16); sq += __shfl_xor(sq, 32);
;                 if (fq == 0) ssp[(size_t)row * 16 + 4 * u.pn + wc] = sq; }
.LBB0_1268:
	s_or_b64 exec, exec, s[78:79]
	v_lshlrev_b32_e32 v118, 16, v170
	v_and_b32_e32 v119, 0xffff0000, v170
	v_lshlrev_b32_e32 v120, 16, v171
	v_and_b32_e32 v121, 0xffff0000, v171
	v_pk_add_f32 v[112:113], v[112:113], v[120:121]
	v_pk_add_f32 v[110:111], v[110:111], v[118:119]
	s_waitcnt lgkmcnt(0)
	v_lshlrev_b64 v[116:117], 10, v[160:161]
	v_mul_f32_e32 v118, v111, v111
	v_mul_f32_e32 v119, v113, v113
	v_fmac_f32_e32 v118, v110, v110
	v_fmac_f32_e32 v119, v112, v112
	v_cvt_pk_bf16_f32 v110, v110, v111
	v_cvt_pk_bf16_f32 v111, v112, v113
	v_lshl_add_u64 v[112:113], v[116:117], 1, s[42:43]
	v_lshl_add_u64 v[112:113], v[136:137], 1, v[112:113]
	global_store_dwordx2 v[112:113], v[110:111], off
	v_lshlrev_b32_e32 v110, 16, v168
	v_and_b32_e32 v111, 0xffff0000, v168
	v_lshlrev_b32_e32 v116, 16, v169
	v_and_b32_e32 v117, 0xffff0000, v169
	v_pk_add_f32 v[108:109], v[108:109], v[116:117]
	v_pk_add_f32 v[106:107], v[106:107], v[110:111]
	v_mul_f32_e32 v111, v109, v109
	v_mul_f32_e32 v110, v107, v107
	v_fmac_f32_e32 v110, v106, v106
	v_fmac_f32_e32 v111, v108, v108
	v_add_f32_e32 v118, v118, v119
	v_add_f32_e32 v110, v110, v111
	v_add_f32_e32 v118, v118, v110
	v_lshlrev_b32_e32 v110, 16, v166
	v_and_b32_e32 v111, 0xffff0000, v166
	v_lshlrev_b32_e32 v116, 16, v167
	v_and_b32_e32 v117, 0xffff0000, v167
	v_pk_add_f32 v[104:105], v[104:105], v[116:117]
	v_pk_add_f32 v[102:103], v[102:103], v[110:111]
	v_cvt_pk_bf16_f32 v106, v106, v107
	v_mul_f32_e32 v110, v105, v105
	v_mul_f32_e32 v107, v103, v103
	v_fmac_f32_e32 v107, v102, v102
	v_fmac_f32_e32 v110, v104, v104
	v_add_f32_e32 v107, v107, v110
	v_lshlrev_b32_e32 v110, 16, v164
	v_and_b32_e32 v111, 0xffff0000, v164
	v_lshlrev_b32_e32 v116, 16, v165
	v_and_b32_e32 v117, 0xffff0000, v165
	v_pk_add_f32 v[100:101], v[100:101], v[116:117]
	v_pk_add_f32 v[110:111], v[98:99], v[110:111]
	v_mul_f32_e32 v99, v101, v101
	v_mul_f32_e32 v98, v111, v111
	v_fmac_f32_e32 v98, v110, v110
	v_fmac_f32_e32 v99, v100, v100
	v_add_f32_e32 v107, v118, v107
	v_add_f32_e32 v98, v98, v99
	v_add_f32_e32 v98, v107, v98
	v_mov_b32_e32 v99, v98
	s_nop 1
	v_permlane16_swap_b32_e32 v99, v98
	v_cvt_pk_bf16_f32 v107, v108, v109
	global_store_dwordx2 v[112:113], v[106:107], off offset:32
	v_cvt_pk_bf16_f32 v102, v102, v103
	v_cvt_pk_bf16_f32 v103, v104, v105
	s_waitcnt lgkmcnt(0)
	v_add_f32_e32 v98, v98, v99
	ds_bpermute_b32 v99, v115, v98
	global_store_dwordx2 v[112:113], v[102:103], off offset:256
	v_cvt_pk_bf16_f32 v102, v110, v111
	v_cvt_pk_bf16_f32 v103, v100, v101
	global_store_dwordx2 v[112:113], v[102:103], off offset:288
	s_and_saveexec_b64 s[78:79], s[6:7]
	s_cbranch_execz .LBB0_1270
	v_lshlrev_b64 v[100:101], 6, v[160:161]
	v_lshl_add_u64 v[100:101], s[14:15], 0, v[100:101]
	v_lshl_add_u64 v[100:101], s[76:77], 2, v[100:101]
	s_lshl_b32 s64, s86, 2
	v_lshl_add_u64 v[100:101], v[100:101], 0, s[64:65]
	s_waitcnt lgkmcnt(0)
	v_add_f32_e32 v98, v98, v99
	global_store_dword v[100:101], v98, off
; __device__ __forceinline__ unsigned cvt_pk_bf16(float lo, float hi) { unsigned r; asm volatile("v_cvt_pk_bf16_f32 %0, %1, %2" : "=v"(r) : "v"(lo), "v"(hi)); return r; }
;     __device__ __forceinline__ void operator()(f32x4 (&acc)[2][2][4][2], const Unit& u, int wr, int wc, int fr, int fq) const {
;     ...
;             for (int m = 0; m < 4; ++m) { const int row = u.pm * BM + ai * HALF + wr * 64 + m * 16 + fr; const size_t off = (size_t)row * ldc + col0; float sq = 0.f;
; #pragma unroll
;                 for (int bj = 0; bj < 2; ++bj)
; #pragma unroll
;                     for (int n = 0; n < 2; ++n) { const unsigned long long b = old[m][bj][n];
;                         const unsigned blo = (unsigned)b, bhi = (unsigned)(b >> 32);
;                         f32x4 v; v[0] = __builtin_bit_cast(float, blo << 16); v[1] = __builtin_bit_cast(float, blo & 0xffff0000u); v[2] = __builtin_bit_cast(float, bhi << 16); v[3] = __builtin_bit_cast(float, bhi & 0xffff0000u);
;                         v = v + acc[ai][bj][m][n];
;                         sq += (v[0] * v[0] + v[1] * v[1]) + (v[2] * v[2] + v[3] * v[3]);
;                         *(unsigned long long*)(xb + off + bj * HALF + n * 16) = (unsigned long long)cvt_pk_bf16(v[0], v[1]) | ((unsigned long long)cvt_pk_bf16(v[2], v[3]) << 32); }
;                 sq += __shfl_xor(sq, 16); sq += __shfl_xor(sq, 32);
;                 if (fq == 0) ssp[(size_t)row * 16 + 4 * u.pn + wc] = sq; }
.LBB0_1270:
	s_or_b64 exec, exec, s[78:79]
	v_lshlrev_b32_e32 v100, 16, v162
	v_and_b32_e32 v101, 0xffff0000, v162
	v_lshlrev_b32_e32 v102, 16, v163
	v_and_b32_e32 v103, 0xffff0000, v163
	v_pk_add_f32 v[96:97], v[96:97], v[102:103]
	v_pk_add_f32 v[94:95], v[94:95], v[100:101]
	s_waitcnt lgkmcnt(0)
	v_lshlrev_b64 v[98:99], 10, v[146:147]
	v_mul_f32_e32 v100, v95, v95
	v_mul_f32_e32 v101, v97, v97
	v_fmac_f32_e32 v100, v94, v94
	v_fmac_f32_e32 v101, v96, v96
	v_cvt_pk_bf16_f32 v94, v94, v95
	v_cvt_pk_bf16_f32 v95, v96, v97
	v_lshl_add_u64 v[96:97], v[98:99], 1, s[42:43]
	v_lshl_add_u64 v[96:97], v[136:137], 1, v[96:97]
	global_store_dwordx2 v[96:97], v[94:95], off
	v_lshlrev_b32_e32 v94, 16, v158
	v_and_b32_e32 v95, 0xffff0000, v158
	v_lshlrev_b32_e32 v98, 16, v159
	v_and_b32_e32 v99, 0xffff0000, v159
	v_pk_add_f32 v[92:93], v[92:93], v[98:99]
	v_pk_add_f32 v[90:91], v[90:91], v[94:95]
	v_mul_f32_e32 v95, v93, v93
	v_mul_f32_e32 v94, v91, v91
	v_fmac_f32_e32 v94, v90, v90
	v_fmac_f32_e32 v95, v92, v92
	v_add_f32_e32 v100, v100, v101
	v_add_f32_e32 v94, v94, v95
	v_add_f32_e32 v100, v100, v94
	v_lshlrev_b32_e32 v94, 16, v154
	v_and_b32_e32 v95, 0xffff0000, v154
	v_lshlrev_b32_e32 v98, 16, v155
	v_and_b32_e32 v99, 0xffff0000, v155
	v_pk_add_f32 v[88:89], v[88:89], v[98:99]
	v_pk_add_f32 v[86:87], v[86:87], v[94:95]
	v_cvt_pk_bf16_f32 v90, v90, v91
	v_mul_f32_e32 v94, v89, v89
	v_mul_f32_e32 v91, v87, v87
	v_fmac_f32_e32 v91, v86, v86
	v_fmac_f32_e32 v94, v88, v88
	v_add_f32_e32 v91, v91, v94
	v_lshlrev_b32_e32 v94, 16, v150
	v_and_b32_e32 v95, 0xffff0000, v150
	v_lshlrev_b32_e32 v98, 16, v151
	v_and_b32_e32 v99, 0xffff0000, v151
	v_pk_add_f32 v[84:85], v[84:85], v[98:99]
	v_pk_add_f32 v[94:95], v[82:83], v[94:95]
	v_mul_f32_e32 v83, v85, v85
	v_mul_f32_e32 v82, v95, v95
	v_fmac_f32_e32 v82, v94, v94
	v_fmac_f32_e32 v83, v84, v84
	v_add_f32_e32 v91, v100, v91
	v_add_f32_e32 v82, v82, v83
	v_add_f32_e32 v82, v91, v82
	v_mov_b32_e32 v83, v82
	s_nop 1
	v_permlane16_swap_b32_e32 v83, v82
	v_cvt_pk_bf16_f32 v91, v92, v93
	global_store_dwordx2 v[96:97], v[90:91], off offset:32
	v_cvt_pk_bf16_f32 v86, v86, v87
	v_cvt_pk_bf16_f32 v87, v88, v89
	s_waitcnt lgkmcnt(0)
	v_add_f32_e32 v82, v82, v83
	ds_bpermute_b32 v83, v115, v82
	global_store_dwordx2 v[96:97], v[86:87], off offset:256
	v_cvt_pk_bf16_f32 v86, v94, v95
	v_cvt_pk_bf16_f32 v87, v84, v85
	global_store_dwordx2 v[96:97], v[86:87], off offset:288
	s_and_saveexec_b64 s[78:79], s[6:7]
	s_cbranch_execz .LBB0_1272
	v_lshlrev_b64 v[84:85], 6, v[146:147]
	v_lshl_add_u64 v[84:85], s[14:15], 0, v[84:85]
	v_lshl_add_u64 v[84:85], s[76:77], 2, v[84:85]
	s_lshl_b32 s64, s86, 2
	v_lshl_add_u64 v[84:85], v[84:85], 0, s[64:65]
	s_waitcnt lgkmcnt(0)
	v_add_f32_e32 v82, v82, v83
	global_store_dword v[84:85], v82, off
.LBB0_1272:
	s_or_b64 exec, exec, s[78:79]
	v_lshlrev_b32_e32 v84, 16, v156
	v_and_b32_e32 v85, 0xffff0000, v156
	v_lshlrev_b32_e32 v86, 16, v157
	v_and_b32_e32 v87, 0xffff0000, v157
	v_pk_add_f32 v[80:81], v[80:81], v[86:87]
	v_pk_add_f32 v[78:79], v[78:79], v[84:85]
	s_waitcnt lgkmcnt(0)
	v_lshlrev_b64 v[82:83], 10, v[142:143]
	v_mul_f32_e32 v84, v79, v79
	v_mul_f32_e32 v85, v81, v81
	v_fmac_f32_e32 v84, v78, v78
	v_fmac_f32_e32 v85, v80, v80
	v_cvt_pk_bf16_f32 v78, v78, v79
	v_cvt_pk_bf16_f32 v79, v80, v81
	v_lshl_add_u64 v[80:81], v[82:83], 1, s[42:43]
	v_lshl_add_u64 v[80:81], v[136:137], 1, v[80:81]
	global_store_dwordx2 v[80:81], v[78:79], off
	v_lshlrev_b32_e32 v78, 16, v152
	v_and_b32_e32 v79, 0xffff0000, v152
	v_lshlrev_b32_e32 v82, 16, v153
	v_and_b32_e32 v83, 0xffff0000, v153
	v_pk_add_f32 v[76:77], v[76:77], v[82:83]
	v_pk_add_f32 v[74:75], v[74:75], v[78:79]
	v_mul_f32_e32 v79, v77, v77
	v_mul_f32_e32 v78, v75, v75
	v_fmac_f32_e32 v78, v74, v74
	v_fmac_f32_e32 v79, v76, v76
	v_add_f32_e32 v84, v84, v85
	v_add_f32_e32 v78, v78, v79
	v_add_f32_e32 v84, v84, v78
	v_lshlrev_b32_e32 v78, 16, v148
	v_and_b32_e32 v79, 0xffff0000, v148
	v_lshlrev_b32_e32 v82, 16, v149
	v_and_b32_e32 v83, 0xffff0000, v149
	v_pk_add_f32 v[72:73], v[72:73], v[82:83]
	v_pk_add_f32 v[70:71], v[70:71], v[78:79]
	v_cvt_pk_bf16_f32 v74, v74, v75
	v_mul_f32_e32 v78, v73, v73
	v_mul_f32_e32 v75, v71, v71
	v_fmac_f32_e32 v75, v70, v70
	v_fmac_f32_e32 v78, v72, v72
	v_add_f32_e32 v75, v75, v78
	v_lshlrev_b32_e32 v78, 16, v144
	v_and_b32_e32 v79, 0xffff0000, v144
	v_lshlrev_b32_e32 v82, 16, v145
	v_and_b32_e32 v83, 0xffff0000, v145
	v_pk_add_f32 v[68:69], v[68:69], v[82:83]
	v_pk_add_f32 v[78:79], v[66:67], v[78:79]
	v_mul_f32_e32 v67, v69, v69
	v_mul_f32_e32 v66, v79, v79
	v_fmac_f32_e32 v66, v78, v78
	v_fmac_f32_e32 v67, v68, v68
	v_add_f32_e32 v75, v84, v75
	v_add_f32_e32 v66, v66, v67
	v_add_f32_e32 v66, v75, v66
	v_mov_b32_e32 v67, v66
	s_nop 1
	v_permlane16_swap_b32_e32 v67, v66
	v_cvt_pk_bf16_f32 v75, v76, v77
	global_store_dwordx2 v[80:81], v[74:75], off offset:32
	v_cvt_pk_bf16_f32 v70, v70, v71
	v_cvt_pk_bf16_f32 v71, v72, v73
	s_waitcnt lgkmcnt(0)
	v_add_f32_e32 v66, v66, v67
	ds_bpermute_b32 v67, v115, v66
	global_store_dwordx2 v[80:81], v[70:71], off offset:256
	v_cvt_pk_bf16_f32 v70, v78, v79
	v_cvt_pk_bf16_f32 v71, v68, v69
	global_store_dwordx2 v[80:81], v[70:71], off offset:288
	s_and_saveexec_b64 s[78:79], s[6:7]
	s_cbranch_execz .LBB0_1274
	v_lshlrev_b64 v[68:69], 6, v[142:143]
	v_lshl_add_u64 v[68:69], s[14:15], 0, v[68:69]
	v_lshl_add_u64 v[68:69], s[76:77], 2, v[68:69]
	s_lshl_b32 s64, s86, 2
	v_lshl_add_u64 v[68:69], v[68:69], 0, s[64:65]
	s_waitcnt lgkmcnt(0)
	v_add_f32_e32 v66, v66, v67
	global_store_dword v[68:69], v66, off

; __device__ __forceinline__ unsigned cvt_pk_bf16(float lo, float hi) { unsigned r; asm volatile("v_cvt_pk_bf16_f32 %0, %1, %2" : "=v"(r) : "v"(lo), "v"(hi)); return r; }
;     __device__ __forceinline__ void operator()(f32x4 (&acc)[2][2][4][2], const Unit& u, int wr, int wc, int fr, int fq) const {
;     ...
;             for (int m = 0; m < 4; ++m) { const int row = u.pm * BM + ai * HALF + wr * 64 + m * 16 + fr; const size_t off = (size_t)row * ldc + col0; float sq = 0.f;
; #pragma unroll
;                 for (int bj = 0; bj < 2; ++bj)
; #pragma unroll
;                     for (int n = 0; n < 2; ++n) { const unsigned long long b = old[m][bj][n];
;                         const unsigned blo = (unsigned)b, bhi = (unsigned)(b >> 32);
;                         f32x4 v; v[0] = __builtin_bit_cast(float, blo << 16); v[1] = __builtin_bit_cast(float, blo & 0xffff0000u); v[2] = __builtin_bit_cast(float, bhi << 16); v[3] = __builtin_bit_cast(float, bhi & 0xffff0000u);
;                         v = v + acc[ai][bj][m][n];
;                         sq += (v[0] * v[0] + v[1] * v[1]) + (v[2] * v[2] + v[3] * v[3]);
;                         *(unsigned long long*)(xb + off + bj * HALF + n * 16) = (unsigned long long)cvt_pk_bf16(v[0], v[1]) | ((unsigned long long)cvt_pk_bf16(v[2], v[3]) << 32); }
;                 sq += __shfl_xor(sq, 16); sq += __shfl_xor(sq, 32);
;                 if (fq == 0) ssp[(size_t)row * 16 + 4 * u.pn + wc] = sq; }
.LBB0_1276:
	s_or_b64 exec, exec, s[78:79]
	s_waitcnt vmcnt(15)
	v_lshlrev_b32_e32 v52, 16, v94
	v_and_b32_e32 v53, 0xffff0000, v94
	v_lshlrev_b32_e32 v54, 16, v95
	v_and_b32_e32 v55, 0xffff0000, v95
	v_pk_add_f32 v[48:49], v[48:49], v[54:55]
	v_pk_add_f32 v[46:47], v[46:47], v[52:53]
	s_waitcnt lgkmcnt(0)
	v_lshlrev_b64 v[50:51], 10, v[84:85]
	v_mul_f32_e32 v52, v47, v47
	v_mul_f32_e32 v53, v49, v49
	v_fmac_f32_e32 v52, v46, v46
	v_fmac_f32_e32 v53, v48, v48
	v_cvt_pk_bf16_f32 v46, v46, v47
	v_cvt_pk_bf16_f32 v47, v48, v49
	v_lshl_add_u64 v[48:49], v[50:51], 1, s[42:43]
	v_lshl_add_u64 v[48:49], v[136:137], 1, v[48:49]
	global_store_dwordx2 v[48:49], v[46:47], off
	s_waitcnt vmcnt(15)
	v_lshlrev_b32_e32 v46, 16, v92
	v_and_b32_e32 v47, 0xffff0000, v92
	v_lshlrev_b32_e32 v50, 16, v93
	v_and_b32_e32 v51, 0xffff0000, v93
	v_pk_add_f32 v[44:45], v[44:45], v[50:51]
	v_pk_add_f32 v[42:43], v[42:43], v[46:47]
	v_mul_f32_e32 v47, v45, v45
	v_mul_f32_e32 v46, v43, v43
	v_fmac_f32_e32 v46, v42, v42
	v_fmac_f32_e32 v47, v44, v44
	v_add_f32_e32 v52, v52, v53
	v_add_f32_e32 v46, v46, v47
	v_add_f32_e32 v52, v52, v46
	s_waitcnt vmcnt(14)
	v_lshlrev_b32_e32 v46, 16, v90
	v_and_b32_e32 v47, 0xffff0000, v90
	v_lshlrev_b32_e32 v50, 16, v91
	v_and_b32_e32 v51, 0xffff0000, v91
	v_pk_add_f32 v[40:41], v[40:41], v[50:51]
	v_pk_add_f32 v[38:39], v[38:39], v[46:47]
	v_cvt_pk_bf16_f32 v42, v42, v43
	v_mul_f32_e32 v46, v41, v41
	v_mul_f32_e32 v43, v39, v39
	v_fmac_f32_e32 v43, v38, v38
	v_fmac_f32_e32 v46, v40, v40
	v_add_f32_e32 v43, v43, v46
	s_waitcnt vmcnt(13)
	v_lshlrev_b32_e32 v46, 16, v88
	v_and_b32_e32 v47, 0xffff0000, v88
	v_lshlrev_b32_e32 v50, 16, v89
	v_and_b32_e32 v51, 0xffff0000, v89
	v_pk_add_f32 v[36:37], v[36:37], v[50:51]
	v_pk_add_f32 v[46:47], v[34:35], v[46:47]
	v_mul_f32_e32 v35, v37, v37
	v_mul_f32_e32 v34, v47, v47
	v_fmac_f32_e32 v34, v46, v46
	v_fmac_f32_e32 v35, v36, v36
	v_add_f32_e32 v43, v52, v43
	v_add_f32_e32 v34, v34, v35
	v_add_f32_e32 v34, v43, v34
	v_mov_b32_e32 v35, v34
	s_nop 1
	v_permlane16_swap_b32_e32 v35, v34
	v_cvt_pk_bf16_f32 v43, v44, v45
	global_store_dwordx2 v[48:49], v[42:43], off offset:32
	v_cvt_pk_bf16_f32 v38, v38, v39
	v_cvt_pk_bf16_f32 v39, v40, v41
	s_waitcnt lgkmcnt(0)
	v_add_f32_e32 v34, v34, v35
	ds_bpermute_b32 v35, v115, v34
	global_store_dwordx2 v[48:49], v[38:39], off offset:256
	v_cvt_pk_bf16_f32 v38, v46, v47
	v_cvt_pk_bf16_f32 v39, v36, v37
	global_store_dwordx2 v[48:49], v[38:39], off offset:288
	s_and_saveexec_b64 s[78:79], s[6:7]
	s_cbranch_execz .LBB0_1278
	v_lshlrev_b64 v[36:37], 6, v[84:85]
	v_lshl_add_u64 v[36:37], s[14:15], 0, v[36:37]
	v_lshl_add_u64 v[36:37], s[76:77], 2, v[36:37]
	s_lshl_b32 s64, s86, 2
	v_lshl_add_u64 v[36:37], v[36:37], 0, s[64:65]
	s_waitcnt lgkmcnt(0)
	v_add_f32_e32 v34, v34, v35
	global_store_dword v[36:37], v34, off
; __device__ __forceinline__ unsigned cvt_pk_bf16(float lo, float hi) { unsigned r; asm volatile("v_cvt_pk_bf16_f32 %0, %1, %2" : "=v"(r) : "v"(lo), "v"(hi)); return r; }
;     __device__ __forceinline__ void operator()(f32x4 (&acc)[2][2][4][2], const Unit& u, int wr, int wc, int fr, int fq) const {
;     ...
;             for (int m = 0; m < 4; ++m) { const int row = u.pm * BM + ai * HALF + wr * 64 + m * 16 + fr; const size_t off = (size_t)row * ldc + col0; float sq = 0.f;
; #pragma unroll
;                 for (int bj = 0; bj < 2; ++bj)
; #pragma unroll
;                     for (int n = 0; n < 2; ++n) { const unsigned long long b = old[m][bj][n];
;                         const unsigned blo = (unsigned)b, bhi = (unsigned)(b >> 32);
;                         f32x4 v; v[0] = __builtin_bit_cast(float, blo << 16); v[1] = __builtin_bit_cast(float, blo & 0xffff0000u); v[2] = __builtin_bit_cast(float, bhi << 16); v[3] = __builtin_bit_cast(float, bhi & 0xffff0000u);
;                         v = v + acc[ai][bj][m][n];
;                         sq += (v[0] * v[0] + v[1] * v[1]) + (v[2] * v[2] + v[3] * v[3]);
;                         *(unsigned long long*)(xb + off + bj * HALF + n * 16) = (unsigned long long)cvt_pk_bf16(v[0], v[1]) | ((unsigned long long)cvt_pk_bf16(v[2], v[3]) << 32); }
;                 sq += __shfl_xor(sq, 16); sq += __shfl_xor(sq, 32);
;                 if (fq == 0) ssp[(size_t)row * 16 + 4 * u.pn + wc] = sq; }
.LBB0_1278:
	s_or_b64 exec, exec, s[78:79]
	s_waitcnt vmcnt(15)
	v_lshlrev_b32_e32 v36, 16, v86
	v_and_b32_e32 v37, 0xffff0000, v86
	v_lshlrev_b32_e32 v38, 16, v87
	v_and_b32_e32 v39, 0xffff0000, v87
	v_pk_add_f32 v[32:33], v[32:33], v[38:39]
	v_pk_add_f32 v[30:31], v[30:31], v[36:37]
	s_waitcnt lgkmcnt(0)
	v_lshlrev_b64 v[34:35], 10, v[70:71]
	v_mul_f32_e32 v36, v31, v31
	v_mul_f32_e32 v37, v33, v33
	v_fmac_f32_e32 v36, v30, v30
	v_fmac_f32_e32 v37, v32, v32
	v_cvt_pk_bf16_f32 v30, v30, v31
	v_cvt_pk_bf16_f32 v31, v32, v33
	v_lshl_add_u64 v[32:33], v[34:35], 1, s[42:43]
	v_lshl_add_u64 v[32:33], v[136:137], 1, v[32:33]
	global_store_dwordx2 v[32:33], v[30:31], off
	s_waitcnt vmcnt(15)
	v_lshlrev_b32_e32 v30, 16, v82
	v_and_b32_e32 v31, 0xffff0000, v82
	v_lshlrev_b32_e32 v34, 16, v83
	v_and_b32_e32 v35, 0xffff0000, v83
	v_pk_add_f32 v[28:29], v[28:29], v[34:35]
	v_pk_add_f32 v[26:27], v[26:27], v[30:31]
	v_mul_f32_e32 v31, v29, v29
	v_mul_f32_e32 v30, v27, v27
	v_fmac_f32_e32 v30, v26, v26
	v_fmac_f32_e32 v31, v28, v28
	v_add_f32_e32 v36, v36, v37
	v_add_f32_e32 v30, v30, v31
	v_add_f32_e32 v36, v36, v30
	s_waitcnt vmcnt(14)
	v_lshlrev_b32_e32 v30, 16, v78
	v_and_b32_e32 v31, 0xffff0000, v78
	v_lshlrev_b32_e32 v34, 16, v79
	v_and_b32_e32 v35, 0xffff0000, v79
	v_pk_add_f32 v[24:25], v[24:25], v[34:35]
	v_pk_add_f32 v[22:23], v[22:23], v[30:31]
	v_cvt_pk_bf16_f32 v26, v26, v27
	v_mul_f32_e32 v30, v25, v25
	v_mul_f32_e32 v27, v23, v23
	v_fmac_f32_e32 v27, v22, v22
	v_fmac_f32_e32 v30, v24, v24
	v_add_f32_e32 v27, v27, v30
	s_waitcnt vmcnt(13)
	v_lshlrev_b32_e32 v30, 16, v74
	v_and_b32_e32 v31, 0xffff0000, v74
	v_lshlrev_b32_e32 v34, 16, v75
	v_and_b32_e32 v35, 0xffff0000, v75
	v_pk_add_f32 v[20:21], v[20:21], v[34:35]
	v_pk_add_f32 v[30:31], v[18:19], v[30:31]
	v_mul_f32_e32 v19, v21, v21
	v_mul_f32_e32 v18, v31, v31
	v_fmac_f32_e32 v18, v30, v30
	v_fmac_f32_e32 v19, v20, v20
	v_add_f32_e32 v27, v36, v27
	v_add_f32_e32 v18, v18, v19
	v_add_f32_e32 v18, v27, v18
	v_mov_b32_e32 v19, v18
	s_nop 1
	v_permlane16_swap_b32_e32 v19, v18
	v_cvt_pk_bf16_f32 v27, v28, v29
	global_store_dwordx2 v[32:33], v[26:27], off offset:32
	v_cvt_pk_bf16_f32 v22, v22, v23
	v_cvt_pk_bf16_f32 v23, v24, v25
	s_waitcnt lgkmcnt(0)
	v_add_f32_e32 v18, v18, v19
	ds_bpermute_b32 v19, v115, v18
	global_store_dwordx2 v[32:33], v[22:23], off offset:256
	v_cvt_pk_bf16_f32 v22, v30, v31
	v_cvt_pk_bf16_f32 v23, v20, v21
	global_store_dwordx2 v[32:33], v[22:23], off offset:288
	s_and_saveexec_b64 s[78:79], s[6:7]
	s_cbranch_execz .LBB0_1280
	v_lshlrev_b64 v[20:21], 6, v[70:71]
	v_lshl_add_u64 v[20:21], s[14:15], 0, v[20:21]
	v_lshl_add_u64 v[20:21], s[76:77], 2, v[20:21]
	s_lshl_b32 s64, s86, 2
	v_lshl_add_u64 v[20:21], v[20:21], 0, s[64:65]
	s_waitcnt lgkmcnt(0)
	v_add_f32_e32 v18, v18, v19
	global_store_dword v[20:21], v18, off
.LBB0_1280:
	s_or_b64 exec, exec, s[78:79]
	s_waitcnt vmcnt(15)
	v_lshlrev_b32_e32 v20, 16, v80
	v_and_b32_e32 v21, 0xffff0000, v80
	v_lshlrev_b32_e32 v22, 16, v81
	v_and_b32_e32 v23, 0xffff0000, v81
	v_pk_add_f32 v[16:17], v[16:17], v[22:23]
	v_pk_add_f32 v[14:15], v[14:15], v[20:21]
	s_waitcnt lgkmcnt(0)
	v_lshlrev_b64 v[18:19], 10, v[66:67]
	v_mul_f32_e32 v20, v15, v15
	v_mul_f32_e32 v21, v17, v17
	v_fmac_f32_e32 v20, v14, v14
	v_fmac_f32_e32 v21, v16, v16
	v_cvt_pk_bf16_f32 v14, v14, v15
	v_cvt_pk_bf16_f32 v15, v16, v17
	v_lshl_add_u64 v[16:17], v[18:19], 1, s[42:43]
	v_lshl_add_u64 v[16:17], v[136:137], 1, v[16:17]
	global_store_dwordx2 v[16:17], v[14:15], off
	s_waitcnt vmcnt(15)
	v_lshlrev_b32_e32 v14, 16, v76
	v_and_b32_e32 v15, 0xffff0000, v76
	v_lshlrev_b32_e32 v18, 16, v77
	v_and_b32_e32 v19, 0xffff0000, v77
	v_pk_add_f32 v[12:13], v[12:13], v[18:19]
	v_pk_add_f32 v[10:11], v[10:11], v[14:15]
	v_mul_f32_e32 v15, v13, v13
	v_mul_f32_e32 v14, v11, v11
	v_fmac_f32_e32 v14, v10, v10
	v_fmac_f32_e32 v15, v12, v12
	v_add_f32_e32 v20, v20, v21
	v_add_f32_e32 v14, v14, v15
	v_add_f32_e32 v20, v20, v14
	s_waitcnt vmcnt(14)
	v_lshlrev_b32_e32 v14, 16, v72
	v_and_b32_e32 v15, 0xffff0000, v72
	v_lshlrev_b32_e32 v18, 16, v73
	v_and_b32_e32 v19, 0xffff0000, v73
	v_pk_add_f32 v[8:9], v[8:9], v[18:19]
	v_pk_add_f32 v[6:7], v[6:7], v[14:15]
	v_cvt_pk_bf16_f32 v10, v10, v11
	v_mul_f32_e32 v14, v9, v9
	v_mul_f32_e32 v11, v7, v7
	v_fmac_f32_e32 v11, v6, v6
	v_fmac_f32_e32 v14, v8, v8
	v_add_f32_e32 v11, v11, v14
	s_waitcnt vmcnt(13)
	v_lshlrev_b32_e32 v14, 16, v68
	v_and_b32_e32 v15, 0xffff0000, v68
	v_lshlrev_b32_e32 v18, 16, v69
	v_and_b32_e32 v19, 0xffff0000, v69
	v_pk_add_f32 v[4:5], v[4:5], v[18:19]
	v_pk_add_f32 v[14:15], v[2:3], v[14:15]
	v_mul_f32_e32 v3, v5, v5
	v_mul_f32_e32 v2, v15, v15
	v_fmac_f32_e32 v2, v14, v14
	v_fmac_f32_e32 v3, v4, v4
	v_add_f32_e32 v11, v20, v11
	v_add_f32_e32 v2, v2, v3
	v_add_f32_e32 v2, v11, v2
	v_mov_b32_e32 v3, v2
	s_nop 1
	v_permlane16_swap_b32_e32 v3, v2
	v_cvt_pk_bf16_f32 v11, v12, v13
	global_store_dwordx2 v[16:17], v[10:11], off offset:32
	v_cvt_pk_bf16_f32 v6, v6, v7
	v_cvt_pk_bf16_f32 v7, v8, v9
	s_waitcnt lgkmcnt(0)
	v_add_f32_e32 v2, v2, v3
	ds_bpermute_b32 v3, v115, v2
	global_store_dwordx2 v[16:17], v[6:7], off offset:256
	v_cvt_pk_bf16_f32 v6, v14, v15
	v_cvt_pk_bf16_f32 v7, v4, v5
	global_store_dwordx2 v[16:17], v[6:7], off offset:288
	s_and_saveexec_b64 s[78:79], s[6:7]
	s_cbranch_execz .LBB0_1282
	v_lshlrev_b64 v[4:5], 6, v[66:67]
	v_lshl_add_u64 v[4:5], s[14:15], 0, v[4:5]
	v_lshl_add_u64 v[4:5], s[76:77], 2, v[4:5]
	s_lshl_b32 s64, s86, 2
	v_lshl_add_u64 v[4:5], v[4:5], 0, s[64:65]
	s_waitcnt lgkmcnt(0)
	v_add_f32_e32 v2, v2, v3
	global_store_dword v[4:5], v2, off

; __device__ __forceinline__ void load_row_scales(const float* ssp, int row0, int fq, float (&rs)[2][4]) {
;     ...
;     const float* sp = ssp + (size_t)row0 * 16 + 4 * fq;
; #pragma unroll
;     for (int ai = 0; ai < 2; ++ai)
; #pragma unroll
;         for (int m = 0; m < 4; ++m) part[ai][m] = *(const f32x4*)(sp + (size_t)(ai * HALF + m * 16) * 16);
; #pragma unroll
;     for (int ai = 0; ai < 2; ++ai)
; #pragma unroll
;         for (int m = 0; m < 4; ++m) { float t = (part[ai][m][0] + part[ai][m][1]) + (part[ai][m][2] + part[ai][m][3]);
;             t += __shfl_xor(t, 16); t += __shfl_xor(t, 32);
;             rs[ai][m] = 1.0f / sqrtf(t * (1.0f / 1024.0f) + 1e-6f); }
.LBB0_1350:
	s_lshl_b32 s13, s13, 8
	s_add_i32 s13, s13, s24
	v_or_b32_e32 v176, s13, v161
	v_ashrrev_i32_e32 v177, 31, v176
	v_lshlrev_b64 v[130:131], 6, v[176:177]
	v_lshl_add_u64 v[146:147], v[162:163], 0, v[130:131]
	global_load_dwordx4 v[130:133], v[146:147], off
	global_load_dwordx4 v[134:137], v[146:147], off offset:1024
	global_load_dwordx4 v[138:141], v[146:147], off offset:2048
	global_load_dwordx4 v[142:145], v[146:147], off offset:3072
	v_add_co_u32_e32 v168, vcc, 0x2000, v146
	v_mov_b32_e32 v177, v1
	s_nop 0
	v_addc_co_u32_e32 v169, vcc, 0, v147, vcc
	global_load_dwordx4 v[146:149], v[168:169], off
	global_load_dwordx4 v[150:153], v[168:169], off offset:1024
	global_load_dwordx4 v[170:173], v[168:169], off offset:2048
	global_load_dwordx4 v[178:181], v[168:169], off offset:3072
	v_and_b32_e32 v169, 64, v229
	v_xor_b32_e32 v168, 16, v229
	v_add_u32_e32 v169, 64, v169
	v_cmp_lt_i32_e32 vcc, v168, v169
	v_mov_b32_dpp v177, v177 row_ror:1 row_mask:0xf bank_mask:0xf
	v_mov_b32_e32 v189, v177
	v_cndmask_b32_e32 v168, v229, v168, vcc
	v_lshlrev_b32_e32 v174, 2, v168
	v_xor_b32_e32 v168, 32, v229
	v_cmp_lt_i32_e32 vcc, v168, v169
	s_waitcnt vmcnt(0)
	v_mov_b32_e32 v169, v132
	v_cndmask_b32_e32 v168, v229, v168, vcc
	v_lshlrev_b32_e32 v175, 2, v168
	v_mov_b32_e32 v168, v131
	v_mov_b32_e32 v131, v133
	v_pk_add_f32 v[130:131], v[168:169], v[130:131]
	s_nop 0
	v_add_f32_e32 v130, v130, v131
	v_mov_b32_e32 v131, v130
	s_nop 1
	v_permlane16_swap_b32_e32 v131, v130
	s_waitcnt lgkmcnt(0)
	v_add_f32_e32 v130, v130, v131
	v_mov_b32_e32 v131, v130
	s_nop 1
	v_permlane32_swap_b32_e32 v131, v130
	s_waitcnt lgkmcnt(0)
	v_add_f32_e32 v130, v130, v131
	v_fmamk_f32 v130, v130, 0x3a800000, v230
	s_ashr_i32 s0, s13, 5
	v_rsq_f32_e32 v168, v130
	s_nop 0
	v_mov_b32_e32 v130, v135
	v_mov_b32_e32 v131, v136
	v_mov_b32_e32 v135, v137
	v_pk_add_f32 v[130:131], v[130:131], v[134:135]
	s_nop 0
	v_add_f32_e32 v130, v130, v131
	v_mov_b32_e32 v131, v130
	s_nop 1
	v_permlane16_swap_b32_e32 v131, v130
	s_waitcnt lgkmcnt(0)
	v_add_f32_e32 v205, v130, v131
	v_mov_b32_e32 v130, v139
	v_mov_b32_e32 v131, v140
	v_mov_b32_e32 v139, v141
	v_pk_add_f32 v[130:131], v[130:131], v[138:139]
	ds_bpermute_b32 v206, v175, v205
	v_add_f32_e32 v130, v130, v131
	v_mov_b32_e32 v131, v130
	s_nop 1
	v_permlane16_swap_b32_e32 v131, v130
	s_waitcnt lgkmcnt(0)
	v_add_f32_e32 v203, v130, v131
	v_mov_b32_e32 v130, v143
	v_mov_b32_e32 v131, v144
	v_mov_b32_e32 v143, v145
	v_pk_add_f32 v[130:131], v[130:131], v[142:143]
	ds_bpermute_b32 v204, v175, v203
	v_add_f32_e32 v130, v130, v131
	v_mov_b32_e32 v131, v130
	s_nop 1
	v_permlane16_swap_b32_e32 v131, v130
	s_waitcnt lgkmcnt(0)
	v_add_f32_e32 v182, v130, v131
	v_mov_b32_e32 v130, v147
	v_mov_b32_e32 v131, v148
	v_mov_b32_e32 v147, v149
	v_pk_add_f32 v[130:131], v[130:131], v[146:147]
	ds_bpermute_b32 v202, v175, v182
	v_add_f32_e32 v130, v130, v131
	v_mov_b32_e32 v131, v130
	s_nop 1
	v_permlane16_swap_b32_e32 v131, v130
	s_waitcnt lgkmcnt(0)
	v_add_f32_e32 v244, v130, v131
	v_mov_b32_e32 v130, v151
	v_mov_b32_e32 v131, v152
	v_mov_b32_e32 v151, v153
	v_pk_add_f32 v[130:131], v[130:131], v[150:151]
	ds_bpermute_b32 v245, v175, v244
	v_add_f32_e32 v130, v130, v131
	v_mov_b32_e32 v131, v130
	s_nop 1
	v_permlane16_swap_b32_e32 v131, v130
	s_waitcnt lgkmcnt(0)
	v_add_f32_e32 v242, v130, v131
	v_mov_b32_e32 v130, v171
	v_mov_b32_e32 v131, v172
	v_mov_b32_e32 v171, v173
	v_pk_add_f32 v[130:131], v[130:131], v[170:171]
	v_lshl_or_b32 v170, s12, 7, v238
	v_add_f32_e32 v130, v130, v131
	v_mov_b32_e32 v131, v130
	s_nop 1
	v_permlane16_swap_b32_e32 v131, v130
	v_ashrrev_i32_e32 v171, 31, v170
	v_lshlrev_b64 v[150:151], 2, v[170:171]
	v_lshl_add_u64 v[172:173], s[70:71], 0, v[150:151]
	ds_bpermute_b32 v243, v175, v242
	s_waitcnt lgkmcnt(0)
	v_add_f32_e32 v240, v130, v131
	v_mov_b32_e32 v130, v179
	v_mov_b32_e32 v131, v180
	v_mov_b32_e32 v179, v181
	v_pk_add_f32 v[130:131], v[130:131], v[178:179]
	ds_bpermute_b32 v241, v175, v240
	v_add_f32_e32 v130, v130, v131
	v_mov_b32_e32 v131, v130
	s_nop 1
	v_permlane16_swap_b32_e32 v131, v130
	v_lshlrev_b64 v[178:179], 1, v[170:171]
	s_waitcnt lgkmcnt(0)
;     __device__ __forceinline__ void operator()(f32x4 (&acc)[2][2][4][2], const Unit& u, int wr, int wc, int fr, int fq) const {
;     ...
;         for (int n = 0; n < 2; ++n) {
;             const int gc0 = u.pn * 128 + wc * 32 + 8 * fq + 4 * n;
;             const float* cwp = cw + gc0; asm volatile("" : "+v"(cwp));
;             const f32x4 wg0 = *(const f32x4*)(cwp), wg1 = *(const f32x4*)(cwp + FF2c), wg2 = *(const f32x4*)(cwp + 2 * FF2c);
;             const f32x4 wv0 = *(const f32x4*)(cwp + FFc), wv1 = *(const f32x4*)(cwp + FF2c + FFc), wv2 = *(const f32x4*)(cwp + 2 * FF2c + FFc);
;             const f32x4 bg = *(const f32x4*)(cb + gc0), bv = *(const f32x4*)(cb + FFc + gc0);
;             bf16_t* gp = G + (size_t)row0 * FFc + gc0;
;             bf16_t* sb = Fb + ((size_t)(row0 >> 6) * 2 + (fr & 1)) * FF2c + gc0;
;             bf16_t* hb = Hb + ((size_t)(row0 >> 6) * 2 + (fr & 1)) * FF2c + gc0;
; #pragma unroll
;             for (int ai = 0; ai < 2; ++ai) {
; #pragma unroll
;                 for (int m = 0; m < 4; ++m) {
;                     float og[4];
; #pragma unroll
;                     for (int j = 0; j < 4; ++j) {
;                         const float vg = acc[ai][0][m][n][j], vv = acc[ai][1][m][n][j];
;                         const float pg = (m > 0) ? acc[ai][0][m - 1][n][j] : 0.f, pv = (m > 0) ? acc[ai][1][m - 1][n][j] : 0.f;
;                         const float g1 = dppf(dppf(0.f, pg, 2), vg, 0), g2 = dppf(dppf(0.f, pg, 3), vg, 1);
;                         const float v1 = dppf(dppf(0.f, pv, 2), vv, 0), v2 = dppf(dppf(0.f, pv, 3), vv, 1);
;                         const float cgate = bg[j] + wg0[j] * g2 + wg1[j] * g1 + wg2[j] * vg;
;                         const float cval = bv[j] + wv0[j] * v2 + wv1[j] * v1 + wv2[j] * vv;
;                         og[j] = cgate * __builtin_amdgcn_rcpf(1.0f + __builtin_amdgcn_exp2f(-1.4426950408889634f * cgate)) * cval; }
;                     const unsigned long long w = (unsigned long long)cvt_pk_bf16(og[0], og[1]) | ((unsigned long long)cvt_pk_bf16(og[2], og[3]) << 32);
;                     if (m == 0) {
;                         if (fr >= 2) *(unsigned long long*)gp = w;
;                         else { *(unsigned long long*)sb = (unsigned long long)cvt_pk_bf16(acc[ai][0][0][n][0], acc[ai][0][0][n][1]) | ((unsigned long long)cvt_pk_bf16(acc[ai][0][0][n][2], acc[ai][0][0][n][3]) << 32);
	v_add_f32_e32 v169, v130, v131
	v_pk_mul_f32 v[196:197], v[98:99], v[168:169] op_sel_hi:[1,0]
	v_or_b32_e32 v98, s0, v160
	v_mad_i64_i32 v[200:201], s[0:1], v98, s37, 0
	v_pk_mul_f32 v[198:199], v[102:103], v[168:169] op_sel_hi:[1,0]
	v_mov_b64_e32 v[102:103], v[172:173]
	s_movk_i32 s0, 0x5000
	ds_bpermute_b32 v183, v175, v169
	v_add_co_u32_e32 v98, vcc, s0, v102
	s_mov_b32 s0, 0xb000
	s_nop 0
	v_addc_co_u32_e32 v99, vcc, 0, v103, vcc
	flat_load_dwordx4 v[142:145], v[98:99] offset:2048
	v_add_co_u32_e32 v98, vcc, s0, v102
	s_movk_i32 s0, 0x2000
	s_nop 0
	v_addc_co_u32_e32 v99, vcc, 0, v103, vcc
	v_pk_mul_f32 v[194:195], v[104:105], v[168:169] op_sel_hi:[1,0]
	v_add_co_u32_e32 v104, vcc, s0, v102
	v_lshl_add_u64 v[174:175], s[72:73], 0, v[150:151]
	flat_load_dwordx4 v[138:141], v[102:103]
	v_addc_co_u32_e32 v105, vcc, 0, v103, vcc
	s_mov_b32 s0, 0x8000
	global_load_dwordx4 v[146:149], v[174:175], off
	flat_load_dwordx4 v[130:133], v[104:105] offset:3072
	v_add_co_u32_e32 v104, vcc, s0, v102
	v_lshl_add_u64 v[150:151], s[76:77], 0, v[150:151]
	v_pk_mul_f32 v[192:193], v[100:101], v[168:169] op_sel_hi:[1,0]
	flat_load_dwordx4 v[98:101], v[98:99]
	v_addc_co_u32_e32 v105, vcc, 0, v103, vcc
	global_load_dwordx4 v[150:153], v[150:151], off
	s_mov_b32 s0, 0xd000
	flat_load_dwordx4 v[134:137], v[104:105] offset:1024
	v_add_co_u32_e32 v102, vcc, s0, v102
	v_readlane_b32 s0, v253, 44
	s_nop 0
	v_addc_co_u32_e32 v103, vcc, 0, v103, vcc
	flat_load_dwordx4 v[102:105], v[102:103] offset:3072
	v_readlane_b32 s1, v253, 45
	v_mov_b32_dpp v189, v196 row_shr:1 row_mask:0xf bank_mask:0xf
	s_nop 0
	v_lshl_add_u64 v[180:181], v[200:201], 1, s[0:1]
	v_lshl_add_u64 v[184:185], v[180:181], 0, v[178:179]
	v_mov_b32_e32 v181, v1
	v_mov_b32_e32 v180, v177
	s_nop 0
	v_mov_b32_dpp v181, v181 row_ror:2 row_mask:0xf bank_mask:0xf
	v_mov_b32_e32 v188, v181
	v_mov_b32_dpp v180, v198 row_shr:1 row_mask:0xf bank_mask:0xf
	v_mov_b32_e32 v190, v181
	v_mov_b32_dpp v188, v198 row_shr:2 row_mask:0xf bank_mask:0xf
	v_mov_b32_e32 v191, v181
	v_mov_b32_dpp v190, v196 row_shr:2 row_mask:0xf bank_mask:0xf
	v_mov_b32_e32 v207, v181
	v_mov_b32_dpp v191, v197 row_shr:2 row_mask:0xf bank_mask:0xf
	s_waitcnt vmcnt(0) lgkmcnt(0)
	v_fma_f32 v188, v138, v188, v146
	v_fmac_f32_e32 v188, v142, v180
	v_mov_b32_dpp v207, v192 row_shr:2 row_mask:0xf bank_mask:0xf
	v_fmac_f32_e32 v188, v198, v98
	v_fma_f32 v180, v130, v190, v150
	v_mov_b32_e32 v190, v177
	v_fmac_f32_e32 v180, v134, v189
	v_mul_f32_e32 v189, 0xbfb8aa3b, v188
	v_exp_f32_e32 v189, v189
	v_mov_b32_dpp v190, v197 row_shr:1 row_mask:0xf bank_mask:0xf
	v_add_f32_e32 v189, 1.0, v189
	v_rcp_f32_e32 v189, v189
	v_fmac_f32_e32 v180, v196, v102
	v_mul_f32_e32 v188, v188, v189
	v_mov_b32_e32 v189, v181
	v_mul_f32_e32 v180, v180, v188
	v_mov_b32_e32 v188, v177
	v_mov_b32_dpp v189, v199 row_shr:2 row_mask:0xf bank_mask:0xf
	v_fma_f32 v189, v139, v189, v147
	v_mov_b32_dpp v188, v199 row_shr:1 row_mask:0xf bank_mask:0xf
	v_fmac_f32_e32 v189, v143, v188
	v_fmac_f32_e32 v189, v199, v99
	v_fma_f32 v188, v131, v191, v151
	v_fmac_f32_e32 v188, v135, v190
	v_mul_f32_e32 v190, 0xbfb8aa3b, v189
	v_exp_f32_e32 v190, v190
	v_fmac_f32_e32 v188, v197, v103
	v_mov_b32_e32 v191, v177
	v_add_f32_e32 v190, 1.0, v190
	v_rcp_f32_e32 v190, v190
	v_mov_b32_dpp v191, v192 row_shr:1 row_mask:0xf bank_mask:0xf
	v_mul_f32_e32 v189, v189, v190
	v_mov_b32_e32 v190, v181
	v_mul_f32_e32 v188, v188, v189
	v_mov_b32_e32 v189, v177
	v_mov_b32_dpp v190, v194 row_shr:2 row_mask:0xf bank_mask:0xf
	v_fma_f32 v190, v140, v190, v148
	v_mov_b32_dpp v189, v194 row_shr:1 row_mask:0xf bank_mask:0xf
	v_fmac_f32_e32 v190, v144, v189
	v_fmac_f32_e32 v190, v194, v100
	v_fma_f32 v189, v132, v207, v152
	v_fmac_f32_e32 v189, v136, v191
	v_mul_f32_e32 v191, 0xbfb8aa3b, v190
	v_exp_f32_e32 v191, v191
	v_fmac_f32_e32 v189, v192, v104
	v_cvt_pk_bf16_f32 v180, v180, v188
	v_add_f32_e32 v191, 1.0, v191
	v_rcp_f32_e32 v191, v191
	s_nop 0
	v_mul_f32_e32 v190, v190, v191
	v_mov_b32_e32 v191, v181
	v_mul_f32_e32 v189, v189, v190
	v_mov_b32_e32 v190, v177
	v_mov_b32_dpp v191, v195 row_shr:2 row_mask:0xf bank_mask:0xf
	v_fma_f32 v191, v141, v191, v149
	v_mov_b32_dpp v190, v195 row_shr:1 row_mask:0xf bank_mask:0xf
	v_mov_b32_dpp v181, v193 row_shr:2 row_mask:0xf bank_mask:0xf
	v_fmac_f32_e32 v191, v145, v190
	v_mov_b32_dpp v177, v193 row_shr:1 row_mask:0xf bank_mask:0xf
	v_fmac_f32_e32 v191, v195, v101
	v_fma_f32 v181, v133, v181, v153
	v_fmac_f32_e32 v181, v137, v177
	v_mul_f32_e32 v177, 0xbfb8aa3b, v191
	v_exp_f32_e32 v177, v177
	v_fmac_f32_e32 v181, v193, v105
	v_add_f32_e32 v177, 1.0, v177
	v_rcp_f32_e32 v177, v177
	s_nop 0
	v_mul_f32_e32 v177, v191, v177
	v_mul_f32_e32 v177, v181, v177
	v_cvt_pk_bf16_f32 v181, v189, v177
	s_and_saveexec_b64 s[0:1], s[6:7]
	s_xor_b64 s[0:1], exec, s[0:1]
	s_mov_b64 s[50:51], 0x16000
	s_mov_b64 s[52:53], 0x58000
	s_mov_b64 s[54:55], 0xb000
	s_cbranch_execz .LBB0_1352
	v_cvt_pk_bf16_f32 v180, v198, v199
	v_cvt_pk_bf16_f32 v181, v194, v195
	v_add_co_u32_e32 v188, vcc, 0x1000, v184
	global_store_dwordx2 v[184:185], v[180:181], off
	v_cvt_pk_bf16_f32 v180, v196, v197
	v_cvt_pk_bf16_f32 v181, v192, v193
	s_nop 0
	v_addc_co_u32_e32 v189, vcc, 0, v185, vcc
	global_store_dwordx2 v[188:189], v[180:181], off offset:1536

; __device__ __forceinline__ unsigned cvt_pk_bf16(float lo, float hi) { unsigned r; asm volatile("v_cvt_pk_bf16_f32 %0, %1, %2" : "=v"(r) : "v"(lo), "v"(hi)); return r; }
;     __device__ __forceinline__ void operator()(f32x4 (&acc)[2][2][4][2], const Unit& u, int wr, int wc, int fr, int fq) const {
;     ...
;             for (int m = 0; m < 4; ++m) { const size_t off = (size_t)(u.pm * BM + ai * HALF + wr * 64 + m * 16 + fr) * ldc + col0;
; #pragma unroll
;                 for (int bj = 0; bj < 2; ++bj)
; #pragma unroll
;                     for (int n = 0; n < 2; ++n) old[m][bj][n] = *(const unsigned long long*)(xb + off + bj * HALF + n * 16); }
; #pragma unroll
;             for (int m = 0; m < 4; ++m) { const int row = u.pm * BM + ai * HALF + wr * 64 + m * 16 + fr; const size_t off = (size_t)row * ldc + col0; float sq = 0.f;
; #pragma unroll
;                 for (int bj = 0; bj < 2; ++bj)
; #pragma unroll
;                     for (int n = 0; n < 2; ++n) { const unsigned long long b = old[m][bj][n];
;                         const unsigned blo = (unsigned)b, bhi = (unsigned)(b >> 32);
;                         f32x4 v; v[0] = __builtin_bit_cast(float, blo << 16); v[1] = __builtin_bit_cast(float, blo & 0xffff0000u); v[2] = __builtin_bit_cast(float, bhi << 16); v[3] = __builtin_bit_cast(float, bhi & 0xffff0000u);
;                         v = v + acc[ai][bj][m][n];
;                         sq += (v[0] * v[0] + v[1] * v[1]) + (v[2] * v[2] + v[3] * v[3]);
;                         *(unsigned long long*)(xb + off + bj * HALF + n * 16) = (unsigned long long)cvt_pk_bf16(v[0], v[1]) | ((unsigned long long)cvt_pk_bf16(v[2], v[3]) << 32); }
;                 sq += __shfl_xor(sq, 16); sq += __shfl_xor(sq, 32);
;                 if (fq == 0) ssp[(size_t)row * 16 + 4 * u.pn + wc] = sq; }
.LBB0_1515:
	v_lshl_or_b32 v136, s12, 8, v174
	v_lshl_add_u32 v140, s13, 8, v172
	v_ashrrev_i32_e32 v137, 31, v136
	v_lshlrev_b64 v[176:177], 1, v[136:137]
	v_ashrrev_i32_e32 v141, 31, v140
	v_lshl_add_u64 v[138:139], s[42:43], 0, v[176:177]
	v_lshlrev_b64 v[178:179], 11, v[140:141]
	v_lshl_add_u64 v[142:143], v[138:139], 0, v[178:179]
	global_load_dwordx2 v[180:181], v[142:143], off
	global_load_dwordx2 v[182:183], v[142:143], off offset:32
	global_load_dwordx2 v[184:185], v[142:143], off offset:256
	global_load_dwordx2 v[188:189], v[142:143], off offset:288
	v_or_b32_e32 v160, 16, v140
	v_ashrrev_i32_e32 v161, 31, v160
	v_lshlrev_b64 v[142:143], 11, v[160:161]
	v_or_b32_e32 v146, 32, v140
	v_lshl_add_u64 v[142:143], v[138:139], 0, v[142:143]
	v_ashrrev_i32_e32 v147, 31, v146
	global_load_dwordx2 v[170:171], v[142:143], off
	global_load_dwordx2 v[168:169], v[142:143], off offset:32
	global_load_dwordx2 v[166:167], v[142:143], off offset:256
	global_load_dwordx2 v[164:165], v[142:143], off offset:288
	v_lshlrev_b64 v[142:143], 11, v[146:147]
	v_lshl_add_u64 v[142:143], v[138:139], 0, v[142:143]
	global_load_dwordx2 v[162:163], v[142:143], off
	global_load_dwordx2 v[158:159], v[142:143], off offset:32
	global_load_dwordx2 v[154:155], v[142:143], off offset:256
	global_load_dwordx2 v[150:151], v[142:143], off offset:288
	v_or_b32_e32 v142, 48, v140
	v_ashrrev_i32_e32 v143, 31, v142
	v_lshlrev_b64 v[144:145], 11, v[142:143]
	v_lshl_add_u64 v[144:145], v[138:139], 0, v[144:145]
	global_load_dwordx2 v[156:157], v[144:145], off
	global_load_dwordx2 v[152:153], v[144:145], off offset:32
	global_load_dwordx2 v[148:149], v[144:145], off offset:256
	s_nop 0
	global_load_dwordx2 v[144:145], v[144:145], off offset:288
	s_lshl_b32 s72, s12, 2
	s_ashr_i32 s73, s72, 31
	s_waitcnt vmcnt(0)
	v_lshlrev_b32_e32 v190, 16, v180
	v_and_b32_e32 v191, 0xffff0000, v180
	v_lshlrev_b32_e32 v180, 16, v181
	v_and_b32_e32 v181, 0xffff0000, v181
	v_pk_add_f32 v[128:129], v[128:129], v[180:181]
	v_pk_add_f32 v[126:127], v[126:127], v[190:191]
	v_mul_f32_e32 v181, v129, v129
	v_mul_f32_e32 v180, v127, v127
	v_fmac_f32_e32 v180, v126, v126
	v_fmac_f32_e32 v181, v128, v128
	v_cvt_pk_bf16_f32 v126, v126, v127
	v_cvt_pk_bf16_f32 v127, v128, v129
	v_lshl_add_u64 v[128:129], s[42:43], 0, v[178:179]
	v_lshl_add_u64 v[128:129], v[128:129], 0, v[176:177]
	global_store_dwordx2 v[128:129], v[126:127], off
	v_lshlrev_b32_e32 v126, 16, v182
	v_and_b32_e32 v127, 0xffff0000, v182
	v_pk_add_f32 v[122:123], v[122:123], v[126:127]
	v_lshlrev_b32_e32 v176, 16, v183
	v_and_b32_e32 v177, 0xffff0000, v183
	v_mul_f32_e32 v126, v123, v123
	v_pk_add_f32 v[124:125], v[124:125], v[176:177]
	v_fmac_f32_e32 v126, v122, v122
	v_cvt_pk_bf16_f32 v122, v122, v123
	v_cvt_pk_bf16_f32 v123, v124, v125
	v_mul_f32_e32 v127, v125, v125
	global_store_dwordx2 v[128:129], v[122:123], off offset:32
	v_lshlrev_b32_e32 v122, 16, v184
	v_and_b32_e32 v123, 0xffff0000, v184
	v_fmac_f32_e32 v127, v124, v124
	v_lshlrev_b32_e32 v124, 16, v185
	v_and_b32_e32 v125, 0xffff0000, v185
	v_pk_add_f32 v[118:119], v[118:119], v[122:123]
	v_pk_add_f32 v[120:121], v[120:121], v[124:125]
	v_mul_f32_e32 v122, v119, v119
	v_fmac_f32_e32 v122, v118, v118
	v_mul_f32_e32 v123, v121, v121
	v_cvt_pk_bf16_f32 v118, v118, v119
	v_cvt_pk_bf16_f32 v119, v120, v121
	v_fmac_f32_e32 v123, v120, v120
	global_store_dwordx2 v[128:129], v[118:119], off offset:256
	v_lshlrev_b32_e32 v118, 16, v188
	v_and_b32_e32 v119, 0xffff0000, v188
	v_lshlrev_b32_e32 v120, 16, v189
	v_and_b32_e32 v121, 0xffff0000, v189
	v_pk_add_f32 v[116:117], v[116:117], v[120:121]
	v_pk_add_f32 v[118:119], v[114:115], v[118:119]
	v_add_f32_e32 v180, v180, v181
	v_add_f32_e32 v126, v126, v127
	v_mul_f32_e32 v114, v119, v119
	v_mul_f32_e32 v115, v117, v117
	v_add_f32_e32 v126, v180, v126
	v_add_f32_e32 v122, v122, v123
	v_fmac_f32_e32 v114, v118, v118
	v_fmac_f32_e32 v115, v116, v116
	v_add_f32_e32 v122, v126, v122
	v_add_f32_e32 v114, v114, v115
	v_cvt_pk_bf16_f32 v118, v118, v119
	v_cvt_pk_bf16_f32 v119, v116, v117
	v_and_b32_e32 v116, 64, v229
	v_add_f32_e32 v115, v122, v114
	v_xor_b32_e32 v114, 16, v229
	v_add_u32_e32 v117, 64, v116
	v_cmp_lt_i32_e32 vcc, v114, v117
	global_store_dwordx2 v[128:129], v[118:119], off offset:288
	s_nop 0
	v_cndmask_b32_e32 v114, v229, v114, vcc
	v_lshlrev_b32_e32 v114, 2, v114
	v_mov_b32_e32 v116, v115
	s_nop 1
	v_permlane16_swap_b32_e32 v116, v115
	s_waitcnt lgkmcnt(0)
	v_add_f32_e32 v116, v115, v116
	v_xor_b32_e32 v115, 32, v229
	v_cmp_lt_i32_e32 vcc, v115, v117
	s_nop 1
	v_cndmask_b32_e32 v115, v229, v115, vcc
	v_lshlrev_b32_e32 v115, 2, v115
	ds_bpermute_b32 v117, v115, v116
	s_and_saveexec_b64 s[74:75], s[4:5]
	s_cbranch_execz .LBB0_1517
	v_readlane_b32 s12, v253, 38
	v_lshlrev_b64 v[118:119], 6, v[140:141]
	v_readlane_b32 s13, v253, 39
	s_lshl_b32 s64, s82, 2
	s_waitcnt lgkmcnt(0)
	v_add_f32_e32 v116, v116, v117
	v_lshl_add_u64 v[118:119], s[12:13], 0, v[118:119]
	v_lshl_add_u64 v[118:119], s[72:73], 2, v[118:119]
	v_lshl_add_u64 v[118:119], v[118:119], 0, s[64:65]
	global_store_dword v[118:119], v116, off
; __device__ __forceinline__ unsigned cvt_pk_bf16(float lo, float hi) { unsigned r; asm volatile("v_cvt_pk_bf16_f32 %0, %1, %2" : "=v"(r) : "v"(lo), "v"(hi)); return r; }
;     __device__ __forceinline__ void operator()(f32x4 (&acc)[2][2][4][2], const Unit& u, int wr, int wc, int fr, int fq) const {
;     ...
;             for (int m = 0; m < 4; ++m) { const int row = u.pm * BM + ai * HALF + wr * 64 + m * 16 + fr; const size_t off = (size_t)row * ldc + col0; float sq = 0.f;
; #pragma unroll
;                 for (int bj = 0; bj < 2; ++bj)
; #pragma unroll
;                     for (int n = 0; n < 2; ++n) { const unsigned long long b = old[m][bj][n];
;                         const unsigned blo = (unsigned)b, bhi = (unsigned)(b >> 32);
;                         f32x4 v; v[0] = __builtin_bit_cast(float, blo << 16); v[1] = __builtin_bit_cast(float, blo & 0xffff0000u); v[2] = __builtin_bit_cast(float, bhi << 16); v[3] = __builtin_bit_cast(float, bhi & 0xffff0000u);
;                         v = v + acc[ai][bj][m][n];
;                         sq += (v[0] * v[0] + v[1] * v[1]) + (v[2] * v[2] + v[3] * v[3]);
;                         *(unsigned long long*)(xb + off + bj * HALF + n * 16) = (unsigned long long)cvt_pk_bf16(v[0], v[1]) | ((unsigned long long)cvt_pk_bf16(v[2], v[3]) << 32); }
;                 sq += __shfl_xor(sq, 16); sq += __shfl_xor(sq, 32);
;                 if (fq == 0) ssp[(size_t)row * 16 + 4 * u.pn + wc] = sq; }
.LBB0_1517:
	s_or_b64 exec, exec, s[74:75]
	v_lshlrev_b32_e32 v118, 16, v170
	v_and_b32_e32 v119, 0xffff0000, v170
	v_lshlrev_b32_e32 v120, 16, v171
	v_and_b32_e32 v121, 0xffff0000, v171
	v_pk_add_f32 v[112:113], v[112:113], v[120:121]
	v_pk_add_f32 v[110:111], v[110:111], v[118:119]
	s_waitcnt lgkmcnt(0)
	v_lshlrev_b64 v[116:117], 10, v[160:161]
	v_mul_f32_e32 v118, v111, v111
	v_mul_f32_e32 v119, v113, v113
	v_fmac_f32_e32 v118, v110, v110
	v_fmac_f32_e32 v119, v112, v112
	v_cvt_pk_bf16_f32 v110, v110, v111
	v_cvt_pk_bf16_f32 v111, v112, v113
	v_lshl_add_u64 v[112:113], v[116:117], 1, s[42:43]
	v_lshl_add_u64 v[112:113], v[136:137], 1, v[112:113]
	global_store_dwordx2 v[112:113], v[110:111], off
	v_lshlrev_b32_e32 v110, 16, v168
	v_and_b32_e32 v111, 0xffff0000, v168
	v_lshlrev_b32_e32 v116, 16, v169
	v_and_b32_e32 v117, 0xffff0000, v169
	v_pk_add_f32 v[108:109], v[108:109], v[116:117]
	v_pk_add_f32 v[106:107], v[106:107], v[110:111]
	v_mul_f32_e32 v111, v109, v109
	v_mul_f32_e32 v110, v107, v107
	v_fmac_f32_e32 v110, v106, v106
	v_fmac_f32_e32 v111, v108, v108
	v_add_f32_e32 v118, v118, v119
	v_add_f32_e32 v110, v110, v111
	v_add_f32_e32 v118, v118, v110
	v_lshlrev_b32_e32 v110, 16, v166
	v_and_b32_e32 v111, 0xffff0000, v166
	v_lshlrev_b32_e32 v116, 16, v167
	v_and_b32_e32 v117, 0xffff0000, v167
	v_pk_add_f32 v[104:105], v[104:105], v[116:117]
	v_pk_add_f32 v[102:103], v[102:103], v[110:111]
	v_cvt_pk_bf16_f32 v106, v106, v107
	v_mul_f32_e32 v110, v105, v105
	v_mul_f32_e32 v107, v103, v103
	v_fmac_f32_e32 v107, v102, v102
	v_fmac_f32_e32 v110, v104, v104
	v_add_f32_e32 v107, v107, v110
	v_lshlrev_b32_e32 v110, 16, v164
	v_and_b32_e32 v111, 0xffff0000, v164
	v_lshlrev_b32_e32 v116, 16, v165
	v_and_b32_e32 v117, 0xffff0000, v165
	v_pk_add_f32 v[100:101], v[100:101], v[116:117]
	v_pk_add_f32 v[110:111], v[98:99], v[110:111]
	v_mul_f32_e32 v99, v101, v101
	v_mul_f32_e32 v98, v111, v111
	v_fmac_f32_e32 v98, v110, v110
	v_fmac_f32_e32 v99, v100, v100
	v_add_f32_e32 v107, v118, v107
	v_add_f32_e32 v98, v98, v99
	v_add_f32_e32 v98, v107, v98
	v_mov_b32_e32 v99, v98
	s_nop 1
	v_permlane16_swap_b32_e32 v99, v98
	v_cvt_pk_bf16_f32 v107, v108, v109
	global_store_dwordx2 v[112:113], v[106:107], off offset:32
	v_cvt_pk_bf16_f32 v102, v102, v103
	v_cvt_pk_bf16_f32 v103, v104, v105
	s_waitcnt lgkmcnt(0)
	v_add_f32_e32 v98, v98, v99
	ds_bpermute_b32 v99, v115, v98
	global_store_dwordx2 v[112:113], v[102:103], off offset:256
	v_cvt_pk_bf16_f32 v102, v110, v111
	v_cvt_pk_bf16_f32 v103, v100, v101
	global_store_dwordx2 v[112:113], v[102:103], off offset:288
	s_and_saveexec_b64 s[74:75], s[4:5]
	s_cbranch_execz .LBB0_1519
	v_readlane_b32 s12, v253, 38
	v_lshlrev_b64 v[100:101], 6, v[160:161]
	v_readlane_b32 s13, v253, 39
	s_lshl_b32 s64, s82, 2
	s_waitcnt lgkmcnt(0)
	v_add_f32_e32 v98, v98, v99
	v_lshl_add_u64 v[100:101], s[12:13], 0, v[100:101]
	v_lshl_add_u64 v[100:101], s[72:73], 2, v[100:101]
	v_lshl_add_u64 v[100:101], v[100:101], 0, s[64:65]
	global_store_dword v[100:101], v98, off
; __device__ __forceinline__ unsigned cvt_pk_bf16(float lo, float hi) { unsigned r; asm volatile("v_cvt_pk_bf16_f32 %0, %1, %2" : "=v"(r) : "v"(lo), "v"(hi)); return r; }
;     __device__ __forceinline__ void operator()(f32x4 (&acc)[2][2][4][2], const Unit& u, int wr, int wc, int fr, int fq) const {
;     ...
;             for (int m = 0; m < 4; ++m) { const int row = u.pm * BM + ai * HALF + wr * 64 + m * 16 + fr; const size_t off = (size_t)row * ldc + col0; float sq = 0.f;
; #pragma unroll
;                 for (int bj = 0; bj < 2; ++bj)
; #pragma unroll
;                     for (int n = 0; n < 2; ++n) { const unsigned long long b = old[m][bj][n];
;                         const unsigned blo = (unsigned)b, bhi = (unsigned)(b >> 32);
;                         f32x4 v; v[0] = __builtin_bit_cast(float, blo << 16); v[1] = __builtin_bit_cast(float, blo & 0xffff0000u); v[2] = __builtin_bit_cast(float, bhi << 16); v[3] = __builtin_bit_cast(float, bhi & 0xffff0000u);
;                         v = v + acc[ai][bj][m][n];
;                         sq += (v[0] * v[0] + v[1] * v[1]) + (v[2] * v[2] + v[3] * v[3]);
;                         *(unsigned long long*)(xb + off + bj * HALF + n * 16) = (unsigned long long)cvt_pk_bf16(v[0], v[1]) | ((unsigned long long)cvt_pk_bf16(v[2], v[3]) << 32); }
;                 sq += __shfl_xor(sq, 16); sq += __shfl_xor(sq, 32);
;                 if (fq == 0) ssp[(size_t)row * 16 + 4 * u.pn + wc] = sq; }
.LBB0_1519:
	s_or_b64 exec, exec, s[74:75]
	v_lshlrev_b32_e32 v100, 16, v162
	v_and_b32_e32 v101, 0xffff0000, v162
	v_lshlrev_b32_e32 v102, 16, v163
	v_and_b32_e32 v103, 0xffff0000, v163
	v_pk_add_f32 v[96:97], v[96:97], v[102:103]
	v_pk_add_f32 v[94:95], v[94:95], v[100:101]
	s_waitcnt lgkmcnt(0)
	v_lshlrev_b64 v[98:99], 10, v[146:147]
	v_mul_f32_e32 v100, v95, v95
	v_mul_f32_e32 v101, v97, v97
	v_fmac_f32_e32 v100, v94, v94
	v_fmac_f32_e32 v101, v96, v96
	v_cvt_pk_bf16_f32 v94, v94, v95
	v_cvt_pk_bf16_f32 v95, v96, v97
	v_lshl_add_u64 v[96:97], v[98:99], 1, s[42:43]
	v_lshl_add_u64 v[96:97], v[136:137], 1, v[96:97]
	global_store_dwordx2 v[96:97], v[94:95], off
	v_lshlrev_b32_e32 v94, 16, v158
	v_and_b32_e32 v95, 0xffff0000, v158
	v_lshlrev_b32_e32 v98, 16, v159
	v_and_b32_e32 v99, 0xffff0000, v159
	v_pk_add_f32 v[92:93], v[92:93], v[98:99]
	v_pk_add_f32 v[90:91], v[90:91], v[94:95]
	v_mul_f32_e32 v95, v93, v93
	v_mul_f32_e32 v94, v91, v91
	v_fmac_f32_e32 v94, v90, v90
	v_fmac_f32_e32 v95, v92, v92
	v_add_f32_e32 v100, v100, v101
	v_add_f32_e32 v94, v94, v95
	v_add_f32_e32 v100, v100, v94
	v_lshlrev_b32_e32 v94, 16, v154
	v_and_b32_e32 v95, 0xffff0000, v154
	v_lshlrev_b32_e32 v98, 16, v155
	v_and_b32_e32 v99, 0xffff0000, v155
	v_pk_add_f32 v[88:89], v[88:89], v[98:99]
	v_pk_add_f32 v[86:87], v[86:87], v[94:95]
	v_cvt_pk_bf16_f32 v90, v90, v91
	v_mul_f32_e32 v94, v89, v89
	v_mul_f32_e32 v91, v87, v87
	v_fmac_f32_e32 v91, v86, v86
	v_fmac_f32_e32 v94, v88, v88
	v_add_f32_e32 v91, v91, v94
	v_lshlrev_b32_e32 v94, 16, v150
	v_and_b32_e32 v95, 0xffff0000, v150
	v_lshlrev_b32_e32 v98, 16, v151
	v_and_b32_e32 v99, 0xffff0000, v151
	v_pk_add_f32 v[84:85], v[84:85], v[98:99]
	v_pk_add_f32 v[94:95], v[82:83], v[94:95]
	v_mul_f32_e32 v83, v85, v85
	v_mul_f32_e32 v82, v95, v95
	v_fmac_f32_e32 v82, v94, v94
	v_fmac_f32_e32 v83, v84, v84
	v_add_f32_e32 v91, v100, v91
	v_add_f32_e32 v82, v82, v83
	v_add_f32_e32 v82, v91, v82
	v_mov_b32_e32 v83, v82
	s_nop 1
	v_permlane16_swap_b32_e32 v83, v82
	v_cvt_pk_bf16_f32 v91, v92, v93
	global_store_dwordx2 v[96:97], v[90:91], off offset:32
	v_cvt_pk_bf16_f32 v86, v86, v87
	v_cvt_pk_bf16_f32 v87, v88, v89
	s_waitcnt lgkmcnt(0)
	v_add_f32_e32 v82, v82, v83
	ds_bpermute_b32 v83, v115, v82
	global_store_dwordx2 v[96:97], v[86:87], off offset:256
	v_cvt_pk_bf16_f32 v86, v94, v95
	v_cvt_pk_bf16_f32 v87, v84, v85
	global_store_dwordx2 v[96:97], v[86:87], off offset:288
	s_and_saveexec_b64 s[74:75], s[4:5]
	v_readlane_b32 s54, v255, 28
	v_readlane_b32 s55, v255, 29
	s_cbranch_execz .LBB0_1521
	v_readlane_b32 s12, v253, 38
	v_lshlrev_b64 v[84:85], 6, v[146:147]
	v_readlane_b32 s13, v253, 39
	s_lshl_b32 s64, s82, 2
	s_waitcnt lgkmcnt(0)
	v_add_f32_e32 v82, v82, v83
	v_lshl_add_u64 v[84:85], s[12:13], 0, v[84:85]
	v_lshl_add_u64 v[84:85], s[72:73], 2, v[84:85]
	v_lshl_add_u64 v[84:85], v[84:85], 0, s[64:65]
	global_store_dword v[84:85], v82, off
.LBB0_1521:
	s_or_b64 exec, exec, s[74:75]
	v_lshlrev_b32_e32 v84, 16, v156
	v_and_b32_e32 v85, 0xffff0000, v156
	v_lshlrev_b32_e32 v86, 16, v157
	v_and_b32_e32 v87, 0xffff0000, v157
	v_pk_add_f32 v[80:81], v[80:81], v[86:87]
	v_pk_add_f32 v[78:79], v[78:79], v[84:85]
	s_waitcnt lgkmcnt(0)
	v_lshlrev_b64 v[82:83], 10, v[142:143]
	v_mul_f32_e32 v84, v79, v79
	v_mul_f32_e32 v85, v81, v81
	v_fmac_f32_e32 v84, v78, v78
	v_fmac_f32_e32 v85, v80, v80
	v_cvt_pk_bf16_f32 v78, v78, v79
	v_cvt_pk_bf16_f32 v79, v80, v81
	v_lshl_add_u64 v[80:81], v[82:83], 1, s[42:43]
	v_lshl_add_u64 v[80:81], v[136:137], 1, v[80:81]
	global_store_dwordx2 v[80:81], v[78:79], off
	v_lshlrev_b32_e32 v78, 16, v152
	v_and_b32_e32 v79, 0xffff0000, v152
	v_lshlrev_b32_e32 v82, 16, v153
	v_and_b32_e32 v83, 0xffff0000, v153
	v_pk_add_f32 v[76:77], v[76:77], v[82:83]
	v_pk_add_f32 v[74:75], v[74:75], v[78:79]
	v_mul_f32_e32 v79, v77, v77
	v_mul_f32_e32 v78, v75, v75
	v_fmac_f32_e32 v78, v74, v74
	v_fmac_f32_e32 v79, v76, v76
	v_add_f32_e32 v84, v84, v85
	v_add_f32_e32 v78, v78, v79
	v_add_f32_e32 v84, v84, v78
	v_lshlrev_b32_e32 v78, 16, v148
	v_and_b32_e32 v79, 0xffff0000, v148
	v_lshlrev_b32_e32 v82, 16, v149
	v_and_b32_e32 v83, 0xffff0000, v149
	v_pk_add_f32 v[72:73], v[72:73], v[82:83]
	v_pk_add_f32 v[70:71], v[70:71], v[78:79]
	v_cvt_pk_bf16_f32 v74, v74, v75
	v_mul_f32_e32 v78, v73, v73
	v_mul_f32_e32 v75, v71, v71
	v_fmac_f32_e32 v75, v70, v70
	v_fmac_f32_e32 v78, v72, v72
	v_add_f32_e32 v75, v75, v78
	v_lshlrev_b32_e32 v78, 16, v144
	v_and_b32_e32 v79, 0xffff0000, v144
	v_lshlrev_b32_e32 v82, 16, v145
	v_and_b32_e32 v83, 0xffff0000, v145
	v_pk_add_f32 v[68:69], v[68:69], v[82:83]
	v_pk_add_f32 v[78:79], v[66:67], v[78:79]
	v_mul_f32_e32 v67, v69, v69
	v_mul_f32_e32 v66, v79, v79
	v_fmac_f32_e32 v66, v78, v78
	v_fmac_f32_e32 v67, v68, v68
	v_add_f32_e32 v75, v84, v75
	v_add_f32_e32 v66, v66, v67
	v_add_f32_e32 v66, v75, v66
	v_mov_b32_e32 v67, v66
	s_nop 1
	v_permlane16_swap_b32_e32 v67, v66
	v_cvt_pk_bf16_f32 v75, v76, v77
	global_store_dwordx2 v[80:81], v[74:75], off offset:32
	v_cvt_pk_bf16_f32 v70, v70, v71
	v_cvt_pk_bf16_f32 v71, v72, v73
	s_waitcnt lgkmcnt(0)
	v_add_f32_e32 v66, v66, v67
	ds_bpermute_b32 v67, v115, v66
	global_store_dwordx2 v[80:81], v[70:71], off offset:256
	v_cvt_pk_bf16_f32 v70, v78, v79
	v_cvt_pk_bf16_f32 v71, v68, v69
	global_store_dwordx2 v[80:81], v[70:71], off offset:288
	s_and_saveexec_b64 s[74:75], s[4:5]
	s_cbranch_execz .LBB0_1523
	v_readlane_b32 s12, v253, 38
	v_lshlrev_b64 v[68:69], 6, v[142:143]
	v_readlane_b32 s13, v253, 39
	s_lshl_b32 s64, s82, 2
	s_waitcnt lgkmcnt(0)
	v_add_f32_e32 v66, v66, v67
	v_lshl_add_u64 v[68:69], s[12:13], 0, v[68:69]
	v_lshl_add_u64 v[68:69], s[72:73], 2, v[68:69]
	v_lshl_add_u64 v[68:69], v[68:69], 0, s[64:65]
	global_store_dword v[68:69], v66, off

; __device__ __forceinline__ unsigned cvt_pk_bf16(float lo, float hi) { unsigned r; asm volatile("v_cvt_pk_bf16_f32 %0, %1, %2" : "=v"(r) : "v"(lo), "v"(hi)); return r; }
;     __device__ __forceinline__ void operator()(f32x4 (&acc)[2][2][4][2], const Unit& u, int wr, int wc, int fr, int fq) const {
;     ...
;             for (int m = 0; m < 4; ++m) { const int row = u.pm * BM + ai * HALF + wr * 64 + m * 16 + fr; const size_t off = (size_t)row * ldc + col0; float sq = 0.f;
; #pragma unroll
;                 for (int bj = 0; bj < 2; ++bj)
; #pragma unroll
;                     for (int n = 0; n < 2; ++n) { const unsigned long long b = old[m][bj][n];
;                         const unsigned blo = (unsigned)b, bhi = (unsigned)(b >> 32);
;                         f32x4 v; v[0] = __builtin_bit_cast(float, blo << 16); v[1] = __builtin_bit_cast(float, blo & 0xffff0000u); v[2] = __builtin_bit_cast(float, bhi << 16); v[3] = __builtin_bit_cast(float, bhi & 0xffff0000u);
;                         v = v + acc[ai][bj][m][n];
;                         sq += (v[0] * v[0] + v[1] * v[1]) + (v[2] * v[2] + v[3] * v[3]);
;                         *(unsigned long long*)(xb + off + bj * HALF + n * 16) = (unsigned long long)cvt_pk_bf16(v[0], v[1]) | ((unsigned long long)cvt_pk_bf16(v[2], v[3]) << 32); }
;                 sq += __shfl_xor(sq, 16); sq += __shfl_xor(sq, 32);
;                 if (fq == 0) ssp[(size_t)row * 16 + 4 * u.pn + wc] = sq; }
.LBB0_1525:
	s_or_b64 exec, exec, s[74:75]
	s_waitcnt vmcnt(15)
	v_lshlrev_b32_e32 v52, 16, v94
	v_and_b32_e32 v53, 0xffff0000, v94
	v_lshlrev_b32_e32 v54, 16, v95
	v_and_b32_e32 v55, 0xffff0000, v95
	v_pk_add_f32 v[48:49], v[48:49], v[54:55]
	v_pk_add_f32 v[46:47], v[46:47], v[52:53]
	s_waitcnt lgkmcnt(0)
	v_lshlrev_b64 v[50:51], 10, v[84:85]
	v_mul_f32_e32 v52, v47, v47
	v_mul_f32_e32 v53, v49, v49
	v_fmac_f32_e32 v52, v46, v46
	v_fmac_f32_e32 v53, v48, v48
	v_cvt_pk_bf16_f32 v46, v46, v47
	v_cvt_pk_bf16_f32 v47, v48, v49
	v_lshl_add_u64 v[48:49], v[50:51], 1, s[42:43]
	v_lshl_add_u64 v[48:49], v[136:137], 1, v[48:49]
	global_store_dwordx2 v[48:49], v[46:47], off
	s_waitcnt vmcnt(15)
	v_lshlrev_b32_e32 v46, 16, v92
	v_and_b32_e32 v47, 0xffff0000, v92
	v_lshlrev_b32_e32 v50, 16, v93
	v_and_b32_e32 v51, 0xffff0000, v93
	v_pk_add_f32 v[44:45], v[44:45], v[50:51]
	v_pk_add_f32 v[42:43], v[42:43], v[46:47]
	v_mul_f32_e32 v47, v45, v45
	v_mul_f32_e32 v46, v43, v43
	v_fmac_f32_e32 v46, v42, v42
	v_fmac_f32_e32 v47, v44, v44
	v_add_f32_e32 v52, v52, v53
	v_add_f32_e32 v46, v46, v47
	v_add_f32_e32 v52, v52, v46
	s_waitcnt vmcnt(14)
	v_lshlrev_b32_e32 v46, 16, v90
	v_and_b32_e32 v47, 0xffff0000, v90
	v_lshlrev_b32_e32 v50, 16, v91
	v_and_b32_e32 v51, 0xffff0000, v91
	v_pk_add_f32 v[40:41], v[40:41], v[50:51]
	v_pk_add_f32 v[38:39], v[38:39], v[46:47]
	v_cvt_pk_bf16_f32 v42, v42, v43
	v_mul_f32_e32 v46, v41, v41
	v_mul_f32_e32 v43, v39, v39
	v_fmac_f32_e32 v43, v38, v38
	v_fmac_f32_e32 v46, v40, v40
	v_add_f32_e32 v43, v43, v46
	s_waitcnt vmcnt(13)
	v_lshlrev_b32_e32 v46, 16, v88
	v_and_b32_e32 v47, 0xffff0000, v88
	v_lshlrev_b32_e32 v50, 16, v89
	v_and_b32_e32 v51, 0xffff0000, v89
	v_pk_add_f32 v[36:37], v[36:37], v[50:51]
	v_pk_add_f32 v[46:47], v[34:35], v[46:47]
	v_mul_f32_e32 v35, v37, v37
	v_mul_f32_e32 v34, v47, v47
	v_fmac_f32_e32 v34, v46, v46
	v_fmac_f32_e32 v35, v36, v36
	v_add_f32_e32 v43, v52, v43
	v_add_f32_e32 v34, v34, v35
	v_add_f32_e32 v34, v43, v34
	v_mov_b32_e32 v35, v34
	s_nop 1
	v_permlane16_swap_b32_e32 v35, v34
	v_cvt_pk_bf16_f32 v43, v44, v45
	global_store_dwordx2 v[48:49], v[42:43], off offset:32
	v_cvt_pk_bf16_f32 v38, v38, v39
	v_cvt_pk_bf16_f32 v39, v40, v41
	s_waitcnt lgkmcnt(0)
	v_add_f32_e32 v34, v34, v35
	ds_bpermute_b32 v35, v115, v34
	global_store_dwordx2 v[48:49], v[38:39], off offset:256
	v_cvt_pk_bf16_f32 v38, v46, v47
	v_cvt_pk_bf16_f32 v39, v36, v37
	global_store_dwordx2 v[48:49], v[38:39], off offset:288
	s_and_saveexec_b64 s[74:75], s[4:5]
	s_cbranch_execz .LBB0_1527
	v_readlane_b32 s12, v253, 38
	v_lshlrev_b64 v[36:37], 6, v[84:85]
	v_readlane_b32 s13, v253, 39
	s_lshl_b32 s64, s82, 2
	s_waitcnt lgkmcnt(0)
	v_add_f32_e32 v34, v34, v35
	v_lshl_add_u64 v[36:37], s[12:13], 0, v[36:37]
	v_lshl_add_u64 v[36:37], s[72:73], 2, v[36:37]
	v_lshl_add_u64 v[36:37], v[36:37], 0, s[64:65]
	global_store_dword v[36:37], v34, off
; __device__ __forceinline__ unsigned cvt_pk_bf16(float lo, float hi) { unsigned r; asm volatile("v_cvt_pk_bf16_f32 %0, %1, %2" : "=v"(r) : "v"(lo), "v"(hi)); return r; }
;     __device__ __forceinline__ void operator()(f32x4 (&acc)[2][2][4][2], const Unit& u, int wr, int wc, int fr, int fq) const {
;     ...
;             for (int m = 0; m < 4; ++m) { const int row = u.pm * BM + ai * HALF + wr * 64 + m * 16 + fr; const size_t off = (size_t)row * ldc + col0; float sq = 0.f;
; #pragma unroll
;                 for (int bj = 0; bj < 2; ++bj)
; #pragma unroll
;                     for (int n = 0; n < 2; ++n) { const unsigned long long b = old[m][bj][n];
;                         const unsigned blo = (unsigned)b, bhi = (unsigned)(b >> 32);
;                         f32x4 v; v[0] = __builtin_bit_cast(float, blo << 16); v[1] = __builtin_bit_cast(float, blo & 0xffff0000u); v[2] = __builtin_bit_cast(float, bhi << 16); v[3] = __builtin_bit_cast(float, bhi & 0xffff0000u);
;                         v = v + acc[ai][bj][m][n];
;                         sq += (v[0] * v[0] + v[1] * v[1]) + (v[2] * v[2] + v[3] * v[3]);
;                         *(unsigned long long*)(xb + off + bj * HALF + n * 16) = (unsigned long long)cvt_pk_bf16(v[0], v[1]) | ((unsigned long long)cvt_pk_bf16(v[2], v[3]) << 32); }
;                 sq += __shfl_xor(sq, 16); sq += __shfl_xor(sq, 32);
;                 if (fq == 0) ssp[(size_t)row * 16 + 4 * u.pn + wc] = sq; }
.LBB0_1527:
	s_or_b64 exec, exec, s[74:75]
	s_waitcnt vmcnt(15)
	v_lshlrev_b32_e32 v36, 16, v86
	v_and_b32_e32 v37, 0xffff0000, v86
	v_lshlrev_b32_e32 v38, 16, v87
	v_and_b32_e32 v39, 0xffff0000, v87
	v_pk_add_f32 v[32:33], v[32:33], v[38:39]
	v_pk_add_f32 v[30:31], v[30:31], v[36:37]
	s_waitcnt lgkmcnt(0)
	v_lshlrev_b64 v[34:35], 10, v[70:71]
	v_mul_f32_e32 v36, v31, v31
	v_mul_f32_e32 v37, v33, v33
	v_fmac_f32_e32 v36, v30, v30
	v_fmac_f32_e32 v37, v32, v32
	v_cvt_pk_bf16_f32 v30, v30, v31
	v_cvt_pk_bf16_f32 v31, v32, v33
	v_lshl_add_u64 v[32:33], v[34:35], 1, s[42:43]
	v_lshl_add_u64 v[32:33], v[136:137], 1, v[32:33]
	global_store_dwordx2 v[32:33], v[30:31], off
	s_waitcnt vmcnt(15)
	v_lshlrev_b32_e32 v30, 16, v82
	v_and_b32_e32 v31, 0xffff0000, v82
	v_lshlrev_b32_e32 v34, 16, v83
	v_and_b32_e32 v35, 0xffff0000, v83
	v_pk_add_f32 v[28:29], v[28:29], v[34:35]
	v_pk_add_f32 v[26:27], v[26:27], v[30:31]
	v_mul_f32_e32 v31, v29, v29
	v_mul_f32_e32 v30, v27, v27
	v_fmac_f32_e32 v30, v26, v26
	v_fmac_f32_e32 v31, v28, v28
	v_add_f32_e32 v36, v36, v37
	v_add_f32_e32 v30, v30, v31
	v_add_f32_e32 v36, v36, v30
	s_waitcnt vmcnt(14)
	v_lshlrev_b32_e32 v30, 16, v78
	v_and_b32_e32 v31, 0xffff0000, v78
	v_lshlrev_b32_e32 v34, 16, v79
	v_and_b32_e32 v35, 0xffff0000, v79
	v_pk_add_f32 v[24:25], v[24:25], v[34:35]
	v_pk_add_f32 v[22:23], v[22:23], v[30:31]
	v_cvt_pk_bf16_f32 v26, v26, v27
	v_mul_f32_e32 v30, v25, v25
	v_mul_f32_e32 v27, v23, v23
	v_fmac_f32_e32 v27, v22, v22
	v_fmac_f32_e32 v30, v24, v24
	v_add_f32_e32 v27, v27, v30
	s_waitcnt vmcnt(13)
	v_lshlrev_b32_e32 v30, 16, v74
	v_and_b32_e32 v31, 0xffff0000, v74
	v_lshlrev_b32_e32 v34, 16, v75
	v_and_b32_e32 v35, 0xffff0000, v75
	v_pk_add_f32 v[20:21], v[20:21], v[34:35]
	v_pk_add_f32 v[30:31], v[18:19], v[30:31]
	v_mul_f32_e32 v19, v21, v21
	v_mul_f32_e32 v18, v31, v31
	v_fmac_f32_e32 v18, v30, v30
	v_fmac_f32_e32 v19, v20, v20
	v_add_f32_e32 v27, v36, v27
	v_add_f32_e32 v18, v18, v19
	v_add_f32_e32 v18, v27, v18
	v_mov_b32_e32 v19, v18
	s_nop 1
	v_permlane16_swap_b32_e32 v19, v18
	v_cvt_pk_bf16_f32 v27, v28, v29
	global_store_dwordx2 v[32:33], v[26:27], off offset:32
	v_cvt_pk_bf16_f32 v22, v22, v23
	v_cvt_pk_bf16_f32 v23, v24, v25
	s_waitcnt lgkmcnt(0)
	v_add_f32_e32 v18, v18, v19
	ds_bpermute_b32 v19, v115, v18
	global_store_dwordx2 v[32:33], v[22:23], off offset:256
	v_cvt_pk_bf16_f32 v22, v30, v31
	v_cvt_pk_bf16_f32 v23, v20, v21
	global_store_dwordx2 v[32:33], v[22:23], off offset:288
	s_and_saveexec_b64 s[74:75], s[4:5]
	s_cbranch_execz .LBB0_1529
	v_readlane_b32 s12, v253, 38
	v_lshlrev_b64 v[20:21], 6, v[70:71]
	v_readlane_b32 s13, v253, 39
	s_lshl_b32 s64, s82, 2
	s_waitcnt lgkmcnt(0)
	v_add_f32_e32 v18, v18, v19
	v_lshl_add_u64 v[20:21], s[12:13], 0, v[20:21]
	v_lshl_add_u64 v[20:21], s[72:73], 2, v[20:21]
	v_lshl_add_u64 v[20:21], v[20:21], 0, s[64:65]
	global_store_dword v[20:21], v18, off
.LBB0_1529:
	s_or_b64 exec, exec, s[74:75]
	s_waitcnt vmcnt(15)
	v_lshlrev_b32_e32 v20, 16, v80
	v_and_b32_e32 v21, 0xffff0000, v80
	v_lshlrev_b32_e32 v22, 16, v81
	v_and_b32_e32 v23, 0xffff0000, v81
	v_pk_add_f32 v[16:17], v[16:17], v[22:23]
	v_pk_add_f32 v[14:15], v[14:15], v[20:21]
	s_waitcnt lgkmcnt(0)
	v_lshlrev_b64 v[18:19], 10, v[66:67]
	v_mul_f32_e32 v20, v15, v15
	v_mul_f32_e32 v21, v17, v17
	v_fmac_f32_e32 v20, v14, v14
	v_fmac_f32_e32 v21, v16, v16
	v_cvt_pk_bf16_f32 v14, v14, v15
	v_cvt_pk_bf16_f32 v15, v16, v17
	v_lshl_add_u64 v[16:17], v[18:19], 1, s[42:43]
	v_lshl_add_u64 v[16:17], v[136:137], 1, v[16:17]
	global_store_dwordx2 v[16:17], v[14:15], off
	s_waitcnt vmcnt(15)
	v_lshlrev_b32_e32 v14, 16, v76
	v_and_b32_e32 v15, 0xffff0000, v76
	v_lshlrev_b32_e32 v18, 16, v77
	v_and_b32_e32 v19, 0xffff0000, v77
	v_pk_add_f32 v[12:13], v[12:13], v[18:19]
	v_pk_add_f32 v[10:11], v[10:11], v[14:15]
	v_mul_f32_e32 v15, v13, v13
	v_mul_f32_e32 v14, v11, v11
	v_fmac_f32_e32 v14, v10, v10
	v_fmac_f32_e32 v15, v12, v12
	v_add_f32_e32 v20, v20, v21
	v_add_f32_e32 v14, v14, v15
	v_add_f32_e32 v20, v20, v14
	s_waitcnt vmcnt(14)
	v_lshlrev_b32_e32 v14, 16, v72
	v_and_b32_e32 v15, 0xffff0000, v72
	v_lshlrev_b32_e32 v18, 16, v73
	v_and_b32_e32 v19, 0xffff0000, v73
	v_pk_add_f32 v[8:9], v[8:9], v[18:19]
	v_pk_add_f32 v[6:7], v[6:7], v[14:15]
	v_cvt_pk_bf16_f32 v10, v10, v11
	v_mul_f32_e32 v14, v9, v9
	v_mul_f32_e32 v11, v7, v7
	v_fmac_f32_e32 v11, v6, v6
	v_fmac_f32_e32 v14, v8, v8
	v_add_f32_e32 v11, v11, v14
	s_waitcnt vmcnt(13)
	v_lshlrev_b32_e32 v14, 16, v68
	v_and_b32_e32 v15, 0xffff0000, v68
	v_lshlrev_b32_e32 v18, 16, v69
	v_and_b32_e32 v19, 0xffff0000, v69
	v_pk_add_f32 v[4:5], v[4:5], v[18:19]
	v_pk_add_f32 v[14:15], v[2:3], v[14:15]
	v_mul_f32_e32 v3, v5, v5
	v_mul_f32_e32 v2, v15, v15
	v_fmac_f32_e32 v2, v14, v14
	v_fmac_f32_e32 v3, v4, v4
	v_add_f32_e32 v11, v20, v11
	v_add_f32_e32 v2, v2, v3
	v_add_f32_e32 v2, v11, v2
	v_mov_b32_e32 v3, v2
	s_nop 1
	v_permlane16_swap_b32_e32 v3, v2
	v_cvt_pk_bf16_f32 v11, v12, v13
	global_store_dwordx2 v[16:17], v[10:11], off offset:32
	v_cvt_pk_bf16_f32 v6, v6, v7
	v_cvt_pk_bf16_f32 v7, v8, v9
	s_waitcnt lgkmcnt(0)
	v_add_f32_e32 v2, v2, v3
	ds_bpermute_b32 v3, v115, v2
	global_store_dwordx2 v[16:17], v[6:7], off offset:256
	v_cvt_pk_bf16_f32 v6, v14, v15
	v_cvt_pk_bf16_f32 v7, v4, v5
	global_store_dwordx2 v[16:17], v[6:7], off offset:288
	s_and_saveexec_b64 s[74:75], s[4:5]
	s_cbranch_execz .LBB0_1531
	v_readlane_b32 s12, v253, 38
	v_lshlrev_b64 v[4:5], 6, v[66:67]
	v_readlane_b32 s13, v253, 39
	s_lshl_b32 s64, s82, 2
	s_waitcnt lgkmcnt(0)
	v_add_f32_e32 v2, v2, v3
	v_lshl_add_u64 v[4:5], s[12:13], 0, v[4:5]
	v_lshl_add_u64 v[4:5], s[72:73], 2, v[4:5]
	v_lshl_add_u64 v[4:5], v[4:5], 0, s[64:65]
	global_store_dword v[4:5], v2, off
